# GEMM K=1024 loops restructured: second-half MFMAs of stage kt-1 run right after barrier kt from registers while stage kt fragments load (skewed pipeline, +16 VGPR fragment regs)
# speedup vs baseline: 1.0286x; 1.0101x over previous
.LBB0_203:
	s_and_b32 s4, s69, 7
	s_mulk_i32 s4, 0x60
	s_ashr_i32 s5, s69, 3
	s_add_i32 s4, s4, s5
	s_mul_hi_i32 s5, s4, 0x2aaaaaab
	s_lshr_b32 s6, s5, 31
	s_add_i32 s5, s5, s6
	s_mul_i32 s6, s5, 6
	v_mov_b32_e32 v131, v157
	s_sub_i32 s7, s4, s6
	s_lshl_b32 s31, s5, 8
	v_readfirstlane_b32 s4, v131
	s_ashr_i32 s5, s4, 1
	s_and_b32 s5, s5, 0xffffff80
	v_and_b32_e32 v133, 15, v131
	s_add_i32 s6, s31, s5
	v_or_b32_e32 v144, s6, v133
	v_ashrrev_i32_e32 v145, 31, v144
	v_lshl_add_u64 v[0:1], v[144:145], 2, s[38:39]
	s_waitcnt vmcnt(0)
	v_mov_b32_e32 v10, v157
	global_load_dword v146, v[0:1], off
	global_load_dword v142, v[0:1], off offset:64
	global_load_dword v140, v[0:1], off offset:128
	global_load_dword v138, v[0:1], off offset:192
	global_load_dword v136, v[0:1], off offset:256
	global_load_dword v134, v[0:1], off offset:320
	global_load_dword v132, v[0:1], off offset:384
	global_load_dword v130, v[0:1], off offset:448
	s_lshl_b32 s5, s7, 8
	v_readfirstlane_b32 s74, v10
	s_ashr_i32 s7, s74, 6
	s_lshl_b32 s72, s7, 2
	s_add_i32 s75, s5, 0xffffff00
	s_cmp_lt_i32 s7, 4
	s_cselect_b64 s[8:9], -1, 0
	s_and_b32 s78, s74, 0xffffffc0
	s_and_b64 s[10:11], s[8:9], exec
	s_cselect_b32 s10, s31, s75
	s_add_i32 s10, s10, s78
	s_and_b64 s[8:9], s[8:9], exec
	s_cselect_b32 s18, s53, s68
	s_cselect_b32 s19, s52, s14
	s_ashr_i32 s11, s10, 31
	s_lshl_b64 s[8:9], s[10:11], 11
	s_add_u32 s8, s19, s8
	s_addc_u32 s9, s18, s9
	s_or_b32 s18, s72, 1
	s_cmp_lt_i32 s18, 16
	s_cselect_b64 s[10:11], -1, 0
	s_lshl_b32 s70, s18, 4
	s_and_b64 s[18:19], s[10:11], exec
	s_cselect_b32 s79, s31, s75
	s_add_i32 s18, s79, s70
	s_and_b64 s[10:11], s[10:11], exec
	s_cselect_b32 s84, s53, s68
	s_cselect_b32 s85, s52, s14
	s_ashr_i32 s19, s18, 31
	s_lshl_b64 s[10:11], s[18:19], 11
	s_add_u32 s10, s85, s10
	s_addc_u32 s11, s84, s11
	s_or_b32 s70, s72, 2
	s_cmp_lt_i32 s70, 16
	s_cselect_b64 s[18:19], -1, 0
	s_lshl_b32 s73, s70, 4
	s_and_b64 s[70:71], s[18:19], exec
	s_cselect_b32 s86, s31, s75
	s_add_i32 s70, s86, s73
	s_and_b64 s[18:19], s[18:19], exec
	s_cselect_b32 s87, s53, s68
	s_cselect_b32 vcc_lo, s52, s14
	s_ashr_i32 s71, s70, 31
	s_lshl_b64 s[18:19], s[70:71], 11
	s_add_u32 s18, vcc_lo, s18
	s_addc_u32 s19, s87, s19
	s_or_b32 s72, s72, 3
	s_cmp_lt_i32 s72, 16
	s_cselect_b64 s[70:71], -1, 0
	s_lshl_b32 vcc_hi, s72, 4
	s_and_b64 s[72:73], s[70:71], exec
	s_cselect_b32 s31, s31, s75
	s_add_i32 s72, s31, vcc_hi
	s_and_b64 s[70:71], s[70:71], exec
	v_lshrrev_b32_e32 v11, 4, v10
	s_cselect_b32 s75, s53, s68
	s_cselect_b32 vcc_hi, s52, s14
	s_ashr_i32 s73, s72, 31
	v_sub_u32_e32 v1, 0, v11
	s_lshl_b64 s[70:71], s[72:73], 11
	v_lshlrev_b32_e32 v0, 9, v10
	v_xor_b32_e32 v1, v10, v1
	s_add_u32 s70, vcc_hi, s70
	v_and_b32_e32 v0, 0x7800, v0
	v_lshlrev_b32_e32 v1, 4, v1
	s_addc_u32 s71, s75, s71
	s_lshl_b32 s7, s7, 12
	v_and_or_b32 v112, v1, 48, v0
	s_mov_b32 m0, s7
	v_lshl_add_u64 v[0:1], s[8:9], 0, v[112:113]
	global_load_lds_dwordx4 v112, s[8:9]
	s_or_b32 m0, s7, 0x400
	v_lshl_add_u64 v[2:3], s[10:11], 0, v[112:113]
	global_load_lds_dwordx4 v112, s[10:11]
	s_or_b32 m0, s7, 0x800
	s_waitcnt vmcnt(0)
	v_lshl_add_u64 v[8:9], v[0:1], 0, 64
	global_load_lds_dwordx4 v112, s[18:19]
	s_or_b32 m0, s7, 0xc00
	v_lshl_add_u64 v[4:5], s[18:19], 0, v[112:113]
	global_load_lds_dwordx4 v112, s[70:71]
	s_add_i32 m0, s7, 0x8000
	v_lshl_add_u64 v[6:7], s[70:71], 0, v[112:113]
	global_load_lds_dwordx4 v[8:9], off
	v_lshl_add_u64 v[8:9], v[2:3], 0, 64
	s_add_i32 m0, s7, 0x8400
	v_lshl_add_u64 v[2:3], v[2:3], 0, s[90:91]
	global_load_lds_dwordx4 v[8:9], off
	v_lshl_add_u64 v[8:9], v[4:5], 0, 64
	s_add_i32 m0, s7, 0x8800
	s_lshr_b32 s8, s74, 1
	global_load_lds_dwordx4 v[8:9], off
	v_lshl_add_u64 v[8:9], v[6:7], 0, 64
	s_add_i32 m0, s7, 0x8c00
	v_and_b32_e32 v12, 15, v10
	global_load_lds_dwordx4 v[8:9], off
	s_add_i32 m0, s7, 0x10000
	v_lshl_add_u64 v[8:9], v[0:1], 0, s[90:91]
	global_load_lds_dwordx4 v[8:9], off
	s_add_i32 m0, s7, 0x10400
	s_and_b32 s8, s8, 0x3ffff80
	global_load_lds_dwordx4 v[2:3], off
	v_lshl_add_u64 v[2:3], v[4:5], 0, s[90:91]
	s_add_i32 m0, s7, 0x10800
	v_lshl_add_u64 v[154:155], v[0:1], 0, s[76:77]
	global_load_lds_dwordx4 v[2:3], off
	v_lshl_add_u64 v[2:3], v[6:7], 0, s[90:91]
	s_add_i32 m0, s7, 0x10c00
	v_mov_b32_e32 v0, 0
	global_load_lds_dwordx4 v[2:3], off
	v_lshrrev_b32_e32 v2, 2, v10
	v_sub_u32_e32 v2, 0, v2
	v_bitop3_b32 v2, v11, 3, v2 bitop3:0x48
	v_or_b32_e32 v3, s8, v12
	v_lshlrev_b32_e32 v2, 4, v2
	s_and_b32 s8, s74, 0xc0
	v_lshl_or_b32 v135, v3, 6, v2
	v_or_b32_e32 v3, s8, v12
	s_add_i32 s8, s31, s78
	s_ashr_i32 s9, s8, 31
	s_lshl_b64 s[8:9], s[8:9], 11
	s_add_u32 s8, vcc_hi, s8
	v_lshlrev_b32_e32 v3, 6, v3
	s_addc_u32 s9, s75, s9
	v_or3_b32 v137, v2, v3, s83
	v_lshl_add_u64 v[2:3], s[8:9], 0, v[112:113]
	s_add_i32 s8, s86, s78
	s_ashr_i32 s9, s8, 31
	s_lshl_b64 s[8:9], s[8:9], 11
	s_add_u32 s8, vcc_lo, s8
	s_addc_u32 s9, s87, s9
	v_lshl_add_u64 v[148:149], v[2:3], 0, s[92:93]
	v_lshl_add_u64 v[2:3], s[8:9], 0, v[112:113]
	s_add_i32 s8, s79, s78
	s_ashr_i32 s9, s8, 31
	s_lshl_b64 s[8:9], s[8:9], 11
	s_add_u32 s8, s85, s8
	s_addc_u32 s9, s84, s9
	v_lshl_add_u64 v[150:151], v[2:3], 0, s[94:95]
	v_lshl_add_u64 v[2:3], s[8:9], 0, v[112:113]
	v_lshl_add_u64 v[152:153], v[2:3], 0, s[96:97]
	s_mov_b32 s8, 0x18000
	v_mov_b32_e32 v1, v0
	v_mov_b32_e32 v2, v0
	v_mov_b32_e32 v3, v0
	v_mov_b32_e32 v4, v0
	v_mov_b32_e32 v5, v0
	v_mov_b32_e32 v6, v0
	v_mov_b32_e32 v7, v0
	v_mov_b32_e32 v8, v0
	v_mov_b32_e32 v9, v0
	v_mov_b32_e32 v10, v0
	v_mov_b32_e32 v11, v0
	v_mov_b32_e32 v12, v0
	v_mov_b32_e32 v13, v0
	v_mov_b32_e32 v14, v0
	v_mov_b32_e32 v15, v0
	v_mov_b32_e32 v16, v0
	v_mov_b32_e32 v17, v0
	v_mov_b32_e32 v18, v0
	v_mov_b32_e32 v19, v0
	v_mov_b32_e32 v20, v0
	v_mov_b32_e32 v21, v0
	v_mov_b32_e32 v22, v0
	v_mov_b32_e32 v23, v0
	v_mov_b32_e32 v24, v0
	v_mov_b32_e32 v25, v0
	v_mov_b32_e32 v26, v0
	v_mov_b32_e32 v27, v0
	v_mov_b32_e32 v28, v0
	v_mov_b32_e32 v29, v0
	v_mov_b32_e32 v30, v0
	v_mov_b32_e32 v31, v0
	v_mov_b32_e32 v32, v0
	v_mov_b32_e32 v33, v0
	v_mov_b32_e32 v34, v0
	v_mov_b32_e32 v35, v0
	v_mov_b32_e32 v36, v0
	v_mov_b32_e32 v37, v0
	v_mov_b32_e32 v38, v0
	v_mov_b32_e32 v39, v0
	v_mov_b32_e32 v40, v0
	v_mov_b32_e32 v41, v0
	v_mov_b32_e32 v42, v0
	v_mov_b32_e32 v43, v0
	v_mov_b32_e32 v44, v0
	v_mov_b32_e32 v45, v0
	v_mov_b32_e32 v46, v0
	v_mov_b32_e32 v47, v0
	v_mov_b32_e32 v48, v0
	v_mov_b32_e32 v49, v0
	v_mov_b32_e32 v50, v0
	v_mov_b32_e32 v51, v0
	v_mov_b32_e32 v52, v0
	v_mov_b32_e32 v53, v0
	v_mov_b32_e32 v54, v0
	v_mov_b32_e32 v55, v0
	v_mov_b32_e32 v56, v0
	v_mov_b32_e32 v57, v0
	v_mov_b32_e32 v58, v0
	v_mov_b32_e32 v59, v0
	v_mov_b32_e32 v60, v0
	v_mov_b32_e32 v61, v0
	v_mov_b32_e32 v62, v0
	v_mov_b32_e32 v63, v0
	v_mov_b32_e32 v64, v0
	v_mov_b32_e32 v65, v0
	v_mov_b32_e32 v66, v0
	v_mov_b32_e32 v67, v0
	v_mov_b32_e32 v68, v0
	v_mov_b32_e32 v69, v0
	v_mov_b32_e32 v70, v0
	v_mov_b32_e32 v71, v0
	v_mov_b32_e32 v72, v0
	v_mov_b32_e32 v73, v0
	v_mov_b32_e32 v74, v0
	v_mov_b32_e32 v75, v0
	v_mov_b32_e32 v76, v0
	v_mov_b32_e32 v77, v0
	v_mov_b32_e32 v78, v0
	v_mov_b32_e32 v79, v0
	v_mov_b32_e32 v80, v0
	v_mov_b32_e32 v81, v0
	v_mov_b32_e32 v82, v0
	v_mov_b32_e32 v83, v0
	v_mov_b32_e32 v84, v0
	v_mov_b32_e32 v85, v0
	v_mov_b32_e32 v86, v0
	v_mov_b32_e32 v87, v0
	v_mov_b32_e32 v88, v0
	v_mov_b32_e32 v89, v0
	v_mov_b32_e32 v90, v0
	v_mov_b32_e32 v91, v0
	v_mov_b32_e32 v92, v0
	v_mov_b32_e32 v93, v0
	v_mov_b32_e32 v94, v0
	v_mov_b32_e32 v95, v0
	v_mov_b32_e32 v96, v0
	v_mov_b32_e32 v97, v0
	v_mov_b32_e32 v98, v0
	v_mov_b32_e32 v99, v0
	v_mov_b32_e32 v100, v0
	v_mov_b32_e32 v101, v0
	v_mov_b32_e32 v102, v0
	v_mov_b32_e32 v103, v0
	v_mov_b32_e32 v104, v0
	v_mov_b32_e32 v105, v0
	v_mov_b32_e32 v106, v0
	v_mov_b32_e32 v107, v0
	v_mov_b32_e32 v108, v0
	v_mov_b32_e32 v109, v0
	v_mov_b32_e32 v110, v0
	v_mov_b32_e32 v111, v0
	v_mov_b32_e32 v114, v0
	v_mov_b32_e32 v115, v0
	v_mov_b32_e32 v116, v0
	v_mov_b32_e32 v117, v0
	v_mov_b32_e32 v118, v0
	v_mov_b32_e32 v119, v0
	v_mov_b32_e32 v120, v0
	v_mov_b32_e32 v121, v0
	v_mov_b32_e32 v122, v0
	v_mov_b32_e32 v123, v0
	v_mov_b32_e32 v124, v0
	v_mov_b32_e32 v125, v0
	v_mov_b32_e32 v126, v0
	v_mov_b32_e32 v127, v0
	v_mov_b32_e32 v128, v0
	v_mov_b32_e32 v129, v0
	s_add_i32 s9, s8, 0xfffe8000
	s_and_b32 s10, s8, 0x18000
	s_waitcnt vmcnt(8)
	s_barrier
	s_and_b32 s9, s9, 0x18000
	s_add_i32 s10, s7, s10
	v_add_u32_e32 v112, s9, v135
	v_or_b32_e32 v139, s9, v137
	s_add_i32 s18, s10, 0x400
	s_add_i32 s11, s10, 0x800
	s_add_i32 s9, s10, 0xc00
	s_add_i32 s8, s8, 0x8000
	s_cmp_eq_u32 s8, 0x100000
	ds_read_b128 v[186:189], v112
	ds_read_b128 v[158:161], v139
	ds_read_b128 v[162:165], v139 offset:1024
	ds_read_b128 v[166:169], v139 offset:2048
	ds_read_b128 v[182:185], v139 offset:3072
	ds_read_b128 v[190:193], v112 offset:1024
	ds_read_b128 v[194:197], v112 offset:2048
	ds_read_b128 v[198:201], v112 offset:3072
	ds_read_b128 v[232:235], v112 offset:4096
	ds_read_b128 v[236:239], v112 offset:5120
	ds_read_b128 v[240:243], v112 offset:6144
	ds_read_b128 v[244:247], v112 offset:7168
	s_mov_b32 m0, s10
	s_nop 0
	global_load_lds_dwordx4 v[154:155], off
	v_lshl_add_u64 v[154:155], v[154:155], 0, 64
	s_mov_b32 m0, s18
	s_nop 0
	global_load_lds_dwordx4 v[152:153], off
	v_lshl_add_u64 v[152:153], v[152:153], 0, 64
	s_mov_b32 m0, s11
	s_nop 0
	global_load_lds_dwordx4 v[150:151], off
	v_lshl_add_u64 v[150:151], v[150:151], 0, 64
	s_mov_b32 m0, s9
	s_nop 0
	global_load_lds_dwordx4 v[148:149], off
	v_lshl_add_u64 v[148:149], v[148:149], 0, 64
	s_waitcnt lgkmcnt(4)
	v_mfma_f32_16x16x32_bf16 v[126:129], v[158:161], v[186:189], v[126:129]
	v_mfma_f32_16x16x32_bf16 v[122:125], v[162:165], v[186:189], v[122:125]
	v_mfma_f32_16x16x32_bf16 v[118:121], v[166:169], v[186:189], v[118:121]
	v_mfma_f32_16x16x32_bf16 v[114:117], v[182:185], v[186:189], v[114:117]
	v_mfma_f32_16x16x32_bf16 v[108:111], v[158:161], v[190:193], v[108:111]
	v_mfma_f32_16x16x32_bf16 v[104:107], v[162:165], v[190:193], v[104:107]
	v_mfma_f32_16x16x32_bf16 v[100:103], v[166:169], v[190:193], v[100:103]
	v_mfma_f32_16x16x32_bf16 v[96:99], v[182:185], v[190:193], v[96:99]
	v_mfma_f32_16x16x32_bf16 v[92:95], v[158:161], v[194:197], v[92:95]
	v_mfma_f32_16x16x32_bf16 v[88:91], v[162:165], v[194:197], v[88:91]
	v_mfma_f32_16x16x32_bf16 v[84:87], v[166:169], v[194:197], v[84:87]
	v_mfma_f32_16x16x32_bf16 v[80:83], v[182:185], v[194:197], v[80:83]
	v_mfma_f32_16x16x32_bf16 v[76:79], v[158:161], v[198:201], v[76:79]
	v_mfma_f32_16x16x32_bf16 v[72:75], v[162:165], v[198:201], v[72:75]
	v_mfma_f32_16x16x32_bf16 v[68:71], v[166:169], v[198:201], v[68:71]
	v_mfma_f32_16x16x32_bf16 v[64:67], v[182:185], v[198:201], v[64:67]
.Lgsk0_loop:
	s_add_i32 s9, s8, 0xfffe8000
	s_and_b32 s10, s8, 0x18000
	s_waitcnt vmcnt(8) lgkmcnt(0)
	s_barrier
	s_and_b32 s9, s9, 0x18000
	s_add_i32 s10, s7, s10
	v_add_u32_e32 v112, s9, v135
	v_or_b32_e32 v139, s9, v137
	s_add_i32 s18, s10, 0x400
	s_add_i32 s11, s10, 0x800
	s_add_i32 s9, s10, 0xc00
	s_add_i32 s8, s8, 0x8000
	s_cmp_eq_u32 s8, 0x100000
	ds_read_b128 v[186:189], v112
	ds_read_b128 v[190:193], v112 offset:1024
	ds_read_b128 v[194:197], v112 offset:2048
	ds_read_b128 v[198:201], v112 offset:3072
	v_mfma_f32_16x16x32_bf16 v[60:63], v[158:161], v[232:235], v[60:63]
	v_mfma_f32_16x16x32_bf16 v[44:47], v[158:161], v[236:239], v[44:47]
	v_mfma_f32_16x16x32_bf16 v[28:31], v[158:161], v[240:243], v[28:31]
	s_mov_b32 m0, s10
	v_mfma_f32_16x16x32_bf16 v[12:15], v[158:161], v[244:247], v[12:15]
	global_load_lds_dwordx4 v[154:155], off
	v_lshl_add_u64 v[154:155], v[154:155], 0, 64
	v_mfma_f32_16x16x32_bf16 v[56:59], v[162:165], v[232:235], v[56:59]
	ds_read_b128 v[158:161], v139
	v_mfma_f32_16x16x32_bf16 v[40:43], v[162:165], v[236:239], v[40:43]
	v_mfma_f32_16x16x32_bf16 v[24:27], v[162:165], v[240:243], v[24:27]
	s_mov_b32 m0, s18
	v_mfma_f32_16x16x32_bf16 v[8:11], v[162:165], v[244:247], v[8:11]
	global_load_lds_dwordx4 v[152:153], off
	v_lshl_add_u64 v[152:153], v[152:153], 0, 64
	v_mfma_f32_16x16x32_bf16 v[52:55], v[166:169], v[232:235], v[52:55]
	ds_read_b128 v[162:165], v139 offset:1024
	v_mfma_f32_16x16x32_bf16 v[36:39], v[166:169], v[236:239], v[36:39]
	v_mfma_f32_16x16x32_bf16 v[20:23], v[166:169], v[240:243], v[20:23]
	s_mov_b32 m0, s11
	v_mfma_f32_16x16x32_bf16 v[4:7], v[166:169], v[244:247], v[4:7]
	global_load_lds_dwordx4 v[150:151], off
	v_lshl_add_u64 v[150:151], v[150:151], 0, 64
	v_mfma_f32_16x16x32_bf16 v[48:51], v[182:185], v[232:235], v[48:51]
	ds_read_b128 v[166:169], v139 offset:2048
	v_mfma_f32_16x16x32_bf16 v[32:35], v[182:185], v[236:239], v[32:35]
	v_mfma_f32_16x16x32_bf16 v[16:19], v[182:185], v[240:243], v[16:19]
	s_mov_b32 m0, s9
	v_mfma_f32_16x16x32_bf16 v[0:3], v[182:185], v[244:247], v[0:3]
	global_load_lds_dwordx4 v[148:149], off
	v_lshl_add_u64 v[148:149], v[148:149], 0, 64
	s_waitcnt lgkmcnt(2)
	v_mfma_f32_16x16x32_bf16 v[126:129], v[158:161], v[186:189], v[126:129]
	ds_read_b128 v[182:185], v139 offset:3072
	v_mfma_f32_16x16x32_bf16 v[108:111], v[158:161], v[190:193], v[108:111]
	ds_read_b128 v[232:235], v112 offset:4096
	ds_read_b128 v[236:239], v112 offset:5120
	v_mfma_f32_16x16x32_bf16 v[92:95], v[158:161], v[194:197], v[92:95]
	ds_read_b128 v[240:243], v112 offset:6144
	ds_read_b128 v[244:247], v112 offset:7168
	v_mfma_f32_16x16x32_bf16 v[76:79], v[158:161], v[198:201], v[76:79]
	s_waitcnt lgkmcnt(6)
	v_mfma_f32_16x16x32_bf16 v[122:125], v[162:165], v[186:189], v[122:125]
	v_mfma_f32_16x16x32_bf16 v[104:107], v[162:165], v[190:193], v[104:107]
	v_mfma_f32_16x16x32_bf16 v[88:91], v[162:165], v[194:197], v[88:91]
	v_mfma_f32_16x16x32_bf16 v[72:75], v[162:165], v[198:201], v[72:75]
	s_waitcnt lgkmcnt(5)
	v_mfma_f32_16x16x32_bf16 v[118:121], v[166:169], v[186:189], v[118:121]
	v_mfma_f32_16x16x32_bf16 v[100:103], v[166:169], v[190:193], v[100:103]
	v_mfma_f32_16x16x32_bf16 v[84:87], v[166:169], v[194:197], v[84:87]
	v_mfma_f32_16x16x32_bf16 v[68:71], v[166:169], v[198:201], v[68:71]
	s_waitcnt lgkmcnt(4)
	v_mfma_f32_16x16x32_bf16 v[114:117], v[182:185], v[186:189], v[114:117]
	v_mfma_f32_16x16x32_bf16 v[96:99], v[182:185], v[190:193], v[96:99]
	v_mfma_f32_16x16x32_bf16 v[80:83], v[182:185], v[194:197], v[80:83]
	v_mfma_f32_16x16x32_bf16 v[64:67], v[182:185], v[198:201], v[64:67]
	s_cbranch_scc0 .Lgsk0_loop
	s_waitcnt lgkmcnt(0)
	v_mfma_f32_16x16x32_bf16 v[60:63], v[158:161], v[232:235], v[60:63]
	v_mfma_f32_16x16x32_bf16 v[44:47], v[158:161], v[236:239], v[44:47]
	v_mfma_f32_16x16x32_bf16 v[28:31], v[158:161], v[240:243], v[28:31]
	v_mfma_f32_16x16x32_bf16 v[12:15], v[158:161], v[244:247], v[12:15]
	v_mfma_f32_16x16x32_bf16 v[56:59], v[162:165], v[232:235], v[56:59]
	v_mfma_f32_16x16x32_bf16 v[40:43], v[162:165], v[236:239], v[40:43]
	v_mfma_f32_16x16x32_bf16 v[24:27], v[162:165], v[240:243], v[24:27]
	v_mfma_f32_16x16x32_bf16 v[8:11], v[162:165], v[244:247], v[8:11]
	v_mfma_f32_16x16x32_bf16 v[52:55], v[166:169], v[232:235], v[52:55]
	v_mfma_f32_16x16x32_bf16 v[36:39], v[166:169], v[236:239], v[36:39]
	v_mfma_f32_16x16x32_bf16 v[20:23], v[166:169], v[240:243], v[20:23]
	v_mfma_f32_16x16x32_bf16 v[4:7], v[166:169], v[244:247], v[4:7]
	v_mfma_f32_16x16x32_bf16 v[48:51], v[182:185], v[232:235], v[48:51]
	v_mfma_f32_16x16x32_bf16 v[32:35], v[182:185], v[236:239], v[32:35]
	v_mfma_f32_16x16x32_bf16 v[16:19], v[182:185], v[240:243], v[16:19]
	v_mfma_f32_16x16x32_bf16 v[0:3], v[182:185], v[244:247], v[0:3]
	s_waitcnt vmcnt(8)
	s_barrier
	v_add_u32_e32 v112, 0x8000, v135
	v_or_b32_e32 v139, 0x8000, v137
	ds_read_b128 v[148:151], v139
	ds_read_b128 v[152:155], v139 offset:1024
	ds_read_b128 v[158:161], v139 offset:2048
	ds_read_b128 v[162:165], v139 offset:3072
	ds_read_b128 v[166:169], v112
	ds_read_b128 v[182:185], v112 offset:1024
	ds_read_b128 v[186:189], v112 offset:2048
	ds_read_b128 v[190:193], v112 offset:3072
	v_or_b32_e32 v139, 0x10000, v137
	s_waitcnt lgkmcnt(0)
	s_lshl_b32 s7, s4, 8
	v_mfma_f32_16x16x32_bf16 v[126:129], v[148:151], v[166:169], v[126:129]
	s_and_b32 s4, s4, 0xc0
	s_and_b32 s78, s7, 0xffffc000
	s_or_b32 s8, s5, s4
	v_mfma_f32_16x16x32_bf16 v[122:125], v[152:155], v[166:169], v[122:125]
	s_mov_b64 s[4:5], -1
	s_cmpk_gt_i32 s8, 0x17f
	v_mfma_f32_16x16x32_bf16 v[118:121], v[158:161], v[166:169], v[118:121]
	v_mfma_f32_16x16x32_bf16 v[114:117], v[162:165], v[166:169], v[114:117]
	v_mfma_f32_16x16x32_bf16 v[108:111], v[148:151], v[182:185], v[108:111]
	v_mfma_f32_16x16x32_bf16 v[104:107], v[152:155], v[182:185], v[104:107]
	v_mfma_f32_16x16x32_bf16 v[100:103], v[158:161], v[182:185], v[100:103]
	v_mfma_f32_16x16x32_bf16 v[96:99], v[162:165], v[182:185], v[96:99]
	v_mfma_f32_16x16x32_bf16 v[92:95], v[148:151], v[186:189], v[92:95]
	v_mfma_f32_16x16x32_bf16 v[88:91], v[152:155], v[186:189], v[88:91]
	v_mfma_f32_16x16x32_bf16 v[84:87], v[158:161], v[186:189], v[84:87]
	v_mfma_f32_16x16x32_bf16 v[80:83], v[162:165], v[186:189], v[80:83]
	v_mfma_f32_16x16x32_bf16 v[76:79], v[148:151], v[190:193], v[76:79]
	v_mfma_f32_16x16x32_bf16 v[72:75], v[152:155], v[190:193], v[72:75]
	v_mfma_f32_16x16x32_bf16 v[68:71], v[158:161], v[190:193], v[68:71]
	v_mfma_f32_16x16x32_bf16 v[64:67], v[162:165], v[190:193], v[64:67]
	ds_read_b128 v[166:169], v112 offset:4096
	ds_read_b128 v[182:185], v112 offset:5120
	ds_read_b128 v[186:189], v112 offset:6144
	ds_read_b128 v[190:193], v112 offset:7168
	s_waitcnt lgkmcnt(0)
	s_waitcnt vmcnt(4)
	s_barrier
	v_mfma_f32_16x16x32_bf16 v[60:63], v[148:151], v[166:169], v[60:63]
	v_add_u32_e32 v112, 0x10000, v135
	v_mfma_f32_16x16x32_bf16 v[56:59], v[152:155], v[166:169], v[56:59]
	v_mfma_f32_16x16x32_bf16 v[52:55], v[158:161], v[166:169], v[52:55]
	v_mfma_f32_16x16x32_bf16 v[48:51], v[162:165], v[166:169], v[48:51]
	v_mfma_f32_16x16x32_bf16 v[44:47], v[148:151], v[182:185], v[44:47]
	v_mfma_f32_16x16x32_bf16 v[40:43], v[152:155], v[182:185], v[40:43]
	v_mfma_f32_16x16x32_bf16 v[36:39], v[158:161], v[182:185], v[36:39]
	v_mfma_f32_16x16x32_bf16 v[32:35], v[162:165], v[182:185], v[32:35]
	v_mfma_f32_16x16x32_bf16 v[28:31], v[148:151], v[186:189], v[28:31]
	v_mfma_f32_16x16x32_bf16 v[24:27], v[152:155], v[186:189], v[24:27]
	v_mfma_f32_16x16x32_bf16 v[20:23], v[158:161], v[186:189], v[20:23]
	v_mfma_f32_16x16x32_bf16 v[16:19], v[162:165], v[186:189], v[16:19]
	v_mfma_f32_16x16x32_bf16 v[12:15], v[148:151], v[190:193], v[12:15]
	v_mfma_f32_16x16x32_bf16 v[8:11], v[152:155], v[190:193], v[8:11]
	v_mfma_f32_16x16x32_bf16 v[4:7], v[158:161], v[190:193], v[4:7]
	v_mfma_f32_16x16x32_bf16 v[0:3], v[162:165], v[190:193], v[0:3]
	ds_read_b128 v[148:151], v139
	ds_read_b128 v[152:155], v139 offset:1024
	ds_read_b128 v[158:161], v139 offset:2048
	ds_read_b128 v[162:165], v139 offset:3072
	ds_read_b128 v[166:169], v112
	ds_read_b128 v[182:185], v112 offset:1024
	ds_read_b128 v[186:189], v112 offset:2048
	ds_read_b128 v[190:193], v112 offset:3072
	s_nop 0
	s_waitcnt lgkmcnt(0)
	s_nop 0
	v_mfma_f32_16x16x32_bf16 v[126:129], v[148:151], v[166:169], v[126:129]
	v_mfma_f32_16x16x32_bf16 v[122:125], v[152:155], v[166:169], v[122:125]
	v_mfma_f32_16x16x32_bf16 v[118:121], v[158:161], v[166:169], v[118:121]
	v_mfma_f32_16x16x32_bf16 v[114:117], v[162:165], v[166:169], v[114:117]
	v_mfma_f32_16x16x32_bf16 v[108:111], v[148:151], v[182:185], v[108:111]
	v_mfma_f32_16x16x32_bf16 v[104:107], v[152:155], v[182:185], v[104:107]
	v_mfma_f32_16x16x32_bf16 v[100:103], v[158:161], v[182:185], v[100:103]
	v_mfma_f32_16x16x32_bf16 v[96:99], v[162:165], v[182:185], v[96:99]
	v_mfma_f32_16x16x32_bf16 v[92:95], v[148:151], v[186:189], v[92:95]
	v_mfma_f32_16x16x32_bf16 v[88:91], v[152:155], v[186:189], v[88:91]
	v_mfma_f32_16x16x32_bf16 v[84:87], v[158:161], v[186:189], v[84:87]
	v_mfma_f32_16x16x32_bf16 v[80:83], v[162:165], v[186:189], v[80:83]
	v_mfma_f32_16x16x32_bf16 v[76:79], v[148:151], v[190:193], v[76:79]
	v_mfma_f32_16x16x32_bf16 v[72:75], v[152:155], v[190:193], v[72:75]
	v_mfma_f32_16x16x32_bf16 v[68:71], v[158:161], v[190:193], v[68:71]
	v_mfma_f32_16x16x32_bf16 v[64:67], v[162:165], v[190:193], v[64:67]
	ds_read_b128 v[166:169], v112 offset:4096
	ds_read_b128 v[182:185], v112 offset:5120
	ds_read_b128 v[186:189], v112 offset:6144
	ds_read_b128 v[190:193], v112 offset:7168
	s_waitcnt lgkmcnt(0)
	s_waitcnt vmcnt(0)
	s_barrier
	v_mfma_f32_16x16x32_bf16 v[60:63], v[148:151], v[166:169], v[60:63]
	v_add_u32_e32 v112, 0x18000, v135
	v_or_b32_e32 v135, 0x18000, v137
	v_mfma_f32_16x16x32_bf16 v[56:59], v[152:155], v[166:169], v[56:59]
	v_bfe_u32 v137, v131, 4, 2
	v_mfma_f32_16x16x32_bf16 v[52:55], v[158:161], v[166:169], v[52:55]
	v_mfma_f32_16x16x32_bf16 v[48:51], v[162:165], v[166:169], v[48:51]
	v_mfma_f32_16x16x32_bf16 v[44:47], v[148:151], v[182:185], v[44:47]
	v_mfma_f32_16x16x32_bf16 v[40:43], v[152:155], v[182:185], v[40:43]
	v_mfma_f32_16x16x32_bf16 v[36:39], v[158:161], v[182:185], v[36:39]
	v_mfma_f32_16x16x32_bf16 v[32:35], v[162:165], v[182:185], v[32:35]
	v_mfma_f32_16x16x32_bf16 v[28:31], v[148:151], v[186:189], v[28:31]
	v_mfma_f32_16x16x32_bf16 v[24:27], v[152:155], v[186:189], v[24:27]
	v_mfma_f32_16x16x32_bf16 v[20:23], v[158:161], v[186:189], v[20:23]
	v_mfma_f32_16x16x32_bf16 v[16:19], v[162:165], v[186:189], v[16:19]
	v_mfma_f32_16x16x32_bf16 v[12:15], v[148:151], v[190:193], v[12:15]
	v_mfma_f32_16x16x32_bf16 v[8:11], v[152:155], v[190:193], v[8:11]
	v_mfma_f32_16x16x32_bf16 v[4:7], v[158:161], v[190:193], v[4:7]
	v_mfma_f32_16x16x32_bf16 v[0:3], v[162:165], v[190:193], v[0:3]
	ds_read_b128 v[164:167], v135
	ds_read_b128 v[168:171], v135 offset:1024
	ds_read_b128 v[182:185], v135 offset:2048
	ds_read_b128 v[186:189], v135 offset:3072
	ds_read_b128 v[148:151], v112
	ds_read_b128 v[152:155], v112 offset:1024
	ds_read_b128 v[158:161], v112 offset:2048
	ds_read_b128 v[190:193], v112 offset:3072
	v_or_b32_e32 v162, 16, v144
	s_waitcnt lgkmcnt(0)
	v_ashrrev_i32_e32 v163, 31, v162
	v_mfma_f32_16x16x32_bf16 v[126:129], v[164:167], v[148:151], v[126:129]
	v_and_b32_e32 v135, 63, v131
	v_mfma_f32_16x16x32_bf16 v[122:125], v[168:171], v[148:151], v[122:125]
	v_mfma_f32_16x16x32_bf16 v[118:121], v[182:185], v[148:151], v[118:121]
	v_mfma_f32_16x16x32_bf16 v[114:117], v[186:189], v[148:151], v[114:117]
	v_mfma_f32_16x16x32_bf16 v[108:111], v[164:167], v[152:155], v[108:111]
	v_mfma_f32_16x16x32_bf16 v[104:107], v[168:171], v[152:155], v[104:107]
	v_mfma_f32_16x16x32_bf16 v[100:103], v[182:185], v[152:155], v[100:103]
	v_mfma_f32_16x16x32_bf16 v[96:99], v[186:189], v[152:155], v[96:99]
	v_mfma_f32_16x16x32_bf16 v[92:95], v[164:167], v[158:161], v[92:95]
	v_mfma_f32_16x16x32_bf16 v[88:91], v[168:171], v[158:161], v[88:91]
	v_mfma_f32_16x16x32_bf16 v[84:87], v[182:185], v[158:161], v[84:87]
	v_mfma_f32_16x16x32_bf16 v[80:83], v[186:189], v[158:161], v[80:83]
	v_or_b32_e32 v160, 32, v144
	v_or_b32_e32 v158, 48, v144
	v_ashrrev_i32_e32 v161, 31, v160
	v_mfma_f32_16x16x32_bf16 v[76:79], v[164:167], v[190:193], v[76:79]
	v_ashrrev_i32_e32 v159, 31, v158
	v_mfma_f32_16x16x32_bf16 v[72:75], v[168:171], v[190:193], v[72:75]
	v_mfma_f32_16x16x32_bf16 v[68:71], v[182:185], v[190:193], v[68:71]
	v_mfma_f32_16x16x32_bf16 v[64:67], v[186:189], v[190:193], v[64:67]
	ds_read_b128 v[148:151], v112 offset:4096
	ds_read_b128 v[152:155], v112 offset:5120
	ds_read_b128 v[190:193], v112 offset:6144
	ds_read_b128 v[194:197], v112 offset:7168
	s_waitcnt lgkmcnt(0)
	s_barrier
	v_mfma_f32_16x16x32_bf16 v[60:63], v[164:167], v[148:151], v[60:63]
	v_mfma_f32_16x16x32_bf16 v[56:59], v[168:171], v[148:151], v[56:59]
	v_mfma_f32_16x16x32_bf16 v[52:55], v[182:185], v[148:151], v[52:55]
	v_mfma_f32_16x16x32_bf16 v[48:51], v[186:189], v[148:151], v[48:51]
	v_or_b32_e32 v150, 0x60, v144
	v_or_b32_e32 v148, 0x70, v144
	v_ashrrev_i32_e32 v151, 31, v150
	v_mfma_f32_16x16x32_bf16 v[44:47], v[164:167], v[152:155], v[44:47]
	v_ashrrev_i32_e32 v149, 31, v148
	v_mfma_f32_16x16x32_bf16 v[40:43], v[168:171], v[152:155], v[40:43]
	v_mfma_f32_16x16x32_bf16 v[36:39], v[182:185], v[152:155], v[36:39]
	v_mfma_f32_16x16x32_bf16 v[32:35], v[186:189], v[152:155], v[32:35]
	v_or_b32_e32 v154, 64, v144
	v_or_b32_e32 v152, 0x50, v144
	v_ashrrev_i32_e32 v155, 31, v154
	v_mfma_f32_16x16x32_bf16 v[28:31], v[164:167], v[190:193], v[28:31]
	v_ashrrev_i32_e32 v153, 31, v152
	v_mfma_f32_16x16x32_bf16 v[24:27], v[168:171], v[190:193], v[24:27]
	v_mfma_f32_16x16x32_bf16 v[20:23], v[182:185], v[190:193], v[20:23]
	v_mfma_f32_16x16x32_bf16 v[16:19], v[186:189], v[190:193], v[16:19]
	v_mfma_f32_16x16x32_bf16 v[12:15], v[164:167], v[194:197], v[12:15]
	v_mfma_f32_16x16x32_bf16 v[8:11], v[168:171], v[194:197], v[8:11]
	v_mfma_f32_16x16x32_bf16 v[4:7], v[182:185], v[194:197], v[4:7]
	v_mfma_f32_16x16x32_bf16 v[0:3], v[186:189], v[194:197], v[0:3]
	s_cbranch_scc0 .LBB0_213
	s_cmpk_gt_u32 s8, 0x57f
	s_cbranch_scc0 .LBB0_210
	s_cmpk_lg_i32 s8, 0x580
	s_cbranch_scc1 .LBB0_209
	v_lshlrev_b32_e32 v112, 7, v144
	v_and_b32_e32 v112, 0x7c780, v112
	v_lshl_add_u64 v[164:165], s[46:47], 0, v[112:113]
	v_lshlrev_b32_e32 v112, 5, v137
	v_lshl_add_u64 v[168:169], v[164:165], 0, v[112:113]
	global_load_dwordx4 v[164:167], v[168:169], off offset:16
	s_nop 0
	global_load_dwordx4 v[168:171], v[168:169], off
	v_pk_mul_f32 v[184:185], v[146:147], v[122:123] op_sel_hi:[0,1]
	v_pk_mul_f32 v[176:177], v[146:147], v[126:127] op_sel_hi:[0,1]
	v_pk_mul_f32 v[182:183], v[146:147], v[124:125] op_sel_hi:[0,1]
	v_pk_mul_f32 v[174:175], v[146:147], v[128:129] op_sel_hi:[0,1]
	v_lshlrev_b32_e32 v139, 7, v162
	s_waitcnt vmcnt(0)
	v_mov_b32_e32 v186, v168
	v_mov_b32_e32 v187, v170
	v_mov_b32_e32 v170, v169
	v_pk_mul_f32 v[168:169], v[184:185], v[170:171]
	v_pk_mul_f32 v[184:185], v[184:185], v[186:187]
	v_pk_fma_f32 v[168:169], v[176:177], v[186:187], v[168:169] neg_lo:[0,0,1] neg_hi:[0,0,1]
	v_pk_fma_f32 v[170:171], v[176:177], v[170:171], v[184:185]
	v_mov_b32_e32 v177, v166
	v_mov_b32_e32 v166, v165
	v_mov_b32_e32 v176, v164
	v_pk_mul_f32 v[164:165], v[182:183], v[166:167]
	v_cvt_pk_bf16_f32 v168, v168, v169
	v_pk_fma_f32 v[164:165], v[174:175], v[176:177], v[164:165] neg_lo:[0,0,1] neg_hi:[0,0,1]
	v_pk_mul_f32 v[176:177], v[182:183], v[176:177]
	v_cvt_pk_bf16_f32 v169, v164, v165
	v_lshlrev_b64 v[164:165], 6, v[144:145]
	v_pk_fma_f32 v[166:167], v[174:175], v[166:167], v[176:177]
	v_lshl_add_u64 v[174:175], s[36:37], 0, v[164:165]
	v_lshlrev_b32_e32 v164, 3, v137
	v_mov_b32_e32 v165, v113
	v_lshl_add_u64 v[174:175], v[174:175], 0, v[164:165]
	global_store_dwordx2 v[174:175], v[168:169], off
	v_cvt_pk_bf16_f32 v169, v166, v167
	v_and_b32_e32 v166, 0x7cf80, v139
	v_mov_b32_e32 v167, v113
	v_cvt_pk_bf16_f32 v168, v170, v171
	v_lshl_add_u64 v[166:167], s[46:47], 0, v[166:167]
	global_store_dwordx2 v[174:175], v[168:169], off offset:32
	v_lshl_add_u64 v[182:183], v[166:167], 0, v[112:113]
	global_load_dwordx4 v[166:169], v[182:183], off offset:16
	s_nop 0
	global_load_dwordx4 v[182:185], v[182:183], off
	v_pk_mul_f32 v[186:187], v[142:143], v[104:105] op_sel_hi:[0,1]
	v_pk_mul_f32 v[174:175], v[142:143], v[108:109] op_sel_hi:[0,1]
	v_pk_mul_f32 v[176:177], v[142:143], v[106:107] op_sel_hi:[0,1]
	v_pk_mul_f32 v[170:171], v[142:143], v[110:111] op_sel_hi:[0,1]
	v_lshlrev_b32_e32 v139, 7, v160
	s_waitcnt vmcnt(0)
	v_mov_b32_e32 v188, v182
	v_mov_b32_e32 v189, v184
	v_mov_b32_e32 v184, v183
	v_pk_mul_f32 v[182:183], v[186:187], v[184:185]
	v_pk_mul_f32 v[186:187], v[186:187], v[188:189]
	v_pk_fma_f32 v[182:183], v[174:175], v[188:189], v[182:183] neg_lo:[0,0,1] neg_hi:[0,0,1]
	v_pk_fma_f32 v[174:175], v[174:175], v[184:185], v[186:187]
	v_mov_b32_e32 v185, v168
	v_mov_b32_e32 v168, v167
	v_mov_b32_e32 v184, v166
	v_pk_mul_f32 v[166:167], v[176:177], v[168:169]
	v_pk_mul_f32 v[176:177], v[176:177], v[184:185]
	v_pk_fma_f32 v[166:167], v[170:171], v[184:185], v[166:167] neg_lo:[0,0,1] neg_hi:[0,0,1]
	v_pk_fma_f32 v[168:169], v[170:171], v[168:169], v[176:177]
	v_cvt_pk_bf16_f32 v171, v166, v167
	v_lshlrev_b64 v[166:167], 6, v[162:163]
	v_lshl_add_u64 v[166:167], s[36:37], 0, v[166:167]
	v_cvt_pk_bf16_f32 v170, v182, v183
	v_lshl_add_u64 v[166:167], v[166:167], 0, v[164:165]
	global_store_dwordx2 v[166:167], v[170:171], off
	v_cvt_pk_bf16_f32 v170, v174, v175
	v_cvt_pk_bf16_f32 v171, v168, v169
	global_store_dwordx2 v[166:167], v[170:171], off offset:32
	v_and_b32_e32 v166, 0x7d780, v139
	v_mov_b32_e32 v167, v113
	v_lshl_add_u64 v[166:167], s[46:47], 0, v[166:167]
	v_lshl_add_u64 v[182:183], v[166:167], 0, v[112:113]
	global_load_dwordx4 v[166:169], v[182:183], off offset:16
	s_nop 0
	global_load_dwordx4 v[182:185], v[182:183], off
	v_pk_mul_f32 v[186:187], v[140:141], v[88:89] op_sel_hi:[0,1]
	v_pk_mul_f32 v[174:175], v[140:141], v[92:93] op_sel_hi:[0,1]
	v_pk_mul_f32 v[176:177], v[140:141], v[90:91] op_sel_hi:[0,1]
	v_pk_mul_f32 v[170:171], v[140:141], v[94:95] op_sel_hi:[0,1]
	s_waitcnt vmcnt(0)
	v_mov_b32_e32 v188, v182
	v_mov_b32_e32 v189, v184
	v_mov_b32_e32 v184, v183
	v_pk_mul_f32 v[182:183], v[186:187], v[184:185]
	v_pk_mul_f32 v[186:187], v[186:187], v[188:189]
	v_pk_fma_f32 v[182:183], v[174:175], v[188:189], v[182:183] neg_lo:[0,0,1] neg_hi:[0,0,1]
	v_pk_fma_f32 v[174:175], v[174:175], v[184:185], v[186:187]
	v_mov_b32_e32 v185, v168
	v_mov_b32_e32 v168, v167
	v_mov_b32_e32 v184, v166
	v_pk_mul_f32 v[166:167], v[176:177], v[168:169]
	v_pk_mul_f32 v[176:177], v[176:177], v[184:185]
	v_pk_fma_f32 v[166:167], v[170:171], v[184:185], v[166:167] neg_lo:[0,0,1] neg_hi:[0,0,1]
	v_pk_fma_f32 v[168:169], v[170:171], v[168:169], v[176:177]
	v_cvt_pk_bf16_f32 v171, v166, v167
	v_lshlrev_b64 v[166:167], 6, v[160:161]
	v_lshl_add_u64 v[166:167], s[36:37], 0, v[166:167]
	v_cvt_pk_bf16_f32 v170, v182, v183
	v_lshl_add_u64 v[166:167], v[166:167], 0, v[164:165]
	global_store_dwordx2 v[166:167], v[170:171], off
	v_cvt_pk_bf16_f32 v170, v174, v175
	v_cvt_pk_bf16_f32 v171, v168, v169
	global_store_dwordx2 v[166:167], v[170:171], off offset:32
	v_pk_mul_f32 v[170:171], v[138:139], v[78:79] op_sel_hi:[0,1]
	v_pk_mul_f32 v[174:175], v[138:139], v[76:77] op_sel_hi:[0,1]
	v_pk_mul_f32 v[176:177], v[138:139], v[74:75] op_sel_hi:[0,1]
	v_pk_mul_f32 v[186:187], v[138:139], v[72:73] op_sel_hi:[0,1]
	v_lshlrev_b32_e32 v139, 7, v158
	v_and_b32_e32 v166, 0x7df80, v139
	v_mov_b32_e32 v167, v113
	v_lshl_add_u64 v[166:167], s[46:47], 0, v[166:167]
	v_lshl_add_u64 v[182:183], v[166:167], 0, v[112:113]
	global_load_dwordx4 v[166:169], v[182:183], off offset:16
	s_nop 0
	global_load_dwordx4 v[182:185], v[182:183], off
	v_lshlrev_b32_e32 v139, 7, v154
	s_waitcnt vmcnt(0)
	v_mov_b32_e32 v188, v182
	v_mov_b32_e32 v189, v184
	v_mov_b32_e32 v184, v183
	v_pk_mul_f32 v[182:183], v[186:187], v[184:185]
	v_pk_mul_f32 v[186:187], v[186:187], v[188:189]
	v_pk_fma_f32 v[182:183], v[174:175], v[188:189], v[182:183] neg_lo:[0,0,1] neg_hi:[0,0,1]
	v_pk_fma_f32 v[174:175], v[174:175], v[184:185], v[186:187]
	v_mov_b32_e32 v185, v168
	v_mov_b32_e32 v168, v167
	v_mov_b32_e32 v184, v166
	v_pk_mul_f32 v[166:167], v[176:177], v[168:169]
	v_pk_mul_f32 v[176:177], v[176:177], v[184:185]
	v_pk_fma_f32 v[166:167], v[170:171], v[184:185], v[166:167] neg_lo:[0,0,1] neg_hi:[0,0,1]
	v_pk_fma_f32 v[168:169], v[170:171], v[168:169], v[176:177]
	v_cvt_pk_bf16_f32 v171, v166, v167
	v_lshlrev_b64 v[166:167], 6, v[158:159]
	v_lshl_add_u64 v[166:167], s[36:37], 0, v[166:167]
	v_cvt_pk_bf16_f32 v170, v182, v183
	v_lshl_add_u64 v[166:167], v[166:167], 0, v[164:165]
	global_store_dwordx2 v[166:167], v[170:171], off
	v_cvt_pk_bf16_f32 v170, v174, v175
	v_cvt_pk_bf16_f32 v171, v168, v169
	global_store_dwordx2 v[166:167], v[170:171], off offset:32
	v_and_b32_e32 v166, 0x7e780, v139
	v_mov_b32_e32 v167, v113
	v_lshl_add_u64 v[166:167], s[46:47], 0, v[166:167]
	v_lshl_add_u64 v[182:183], v[166:167], 0, v[112:113]
	global_load_dwordx4 v[166:169], v[182:183], off offset:16
	s_nop 0
	global_load_dwordx4 v[182:185], v[182:183], off
	v_pk_mul_f32 v[186:187], v[136:137], v[56:57] op_sel_hi:[0,1]
	v_pk_mul_f32 v[174:175], v[136:137], v[60:61] op_sel_hi:[0,1]
	v_pk_mul_f32 v[176:177], v[136:137], v[58:59] op_sel_hi:[0,1]
	v_pk_mul_f32 v[170:171], v[136:137], v[62:63] op_sel_hi:[0,1]
	v_lshlrev_b32_e32 v139, 7, v152
	s_waitcnt vmcnt(0)
	v_mov_b32_e32 v188, v182
	v_mov_b32_e32 v189, v184
	v_mov_b32_e32 v184, v183
	v_pk_mul_f32 v[182:183], v[186:187], v[184:185]
	v_pk_mul_f32 v[186:187], v[186:187], v[188:189]
	v_pk_fma_f32 v[182:183], v[174:175], v[188:189], v[182:183] neg_lo:[0,0,1] neg_hi:[0,0,1]
	v_pk_fma_f32 v[174:175], v[174:175], v[184:185], v[186:187]
	v_mov_b32_e32 v185, v168
	v_mov_b32_e32 v168, v167
	v_mov_b32_e32 v184, v166
	v_pk_mul_f32 v[166:167], v[176:177], v[168:169]
	v_pk_mul_f32 v[176:177], v[176:177], v[184:185]
	v_pk_fma_f32 v[166:167], v[170:171], v[184:185], v[166:167] neg_lo:[0,0,1] neg_hi:[0,0,1]
	v_pk_fma_f32 v[168:169], v[170:171], v[168:169], v[176:177]
	v_cvt_pk_bf16_f32 v171, v166, v167
	v_lshlrev_b64 v[166:167], 6, v[154:155]
	v_lshl_add_u64 v[166:167], s[36:37], 0, v[166:167]
	v_cvt_pk_bf16_f32 v170, v182, v183
	v_lshl_add_u64 v[166:167], v[166:167], 0, v[164:165]
	global_store_dwordx2 v[166:167], v[170:171], off
	v_cvt_pk_bf16_f32 v170, v174, v175
	v_cvt_pk_bf16_f32 v171, v168, v169
	global_store_dwordx2 v[166:167], v[170:171], off offset:32
	v_and_b32_e32 v166, 0x7ef80, v139
	v_mov_b32_e32 v167, v113
	v_lshl_add_u64 v[166:167], s[46:47], 0, v[166:167]
	v_lshl_add_u64 v[182:183], v[166:167], 0, v[112:113]
	global_load_dwordx4 v[166:169], v[182:183], off offset:16
	s_nop 0
	global_load_dwordx4 v[182:185], v[182:183], off
	v_pk_mul_f32 v[186:187], v[134:135], v[40:41] op_sel_hi:[0,1]
	v_pk_mul_f32 v[174:175], v[134:135], v[44:45] op_sel_hi:[0,1]
	v_pk_mul_f32 v[176:177], v[134:135], v[42:43] op_sel_hi:[0,1]
	v_pk_mul_f32 v[170:171], v[134:135], v[46:47] op_sel_hi:[0,1]
	v_lshlrev_b32_e32 v139, 7, v150
	s_waitcnt vmcnt(0)
	v_mov_b32_e32 v188, v182
	v_mov_b32_e32 v189, v184
	v_mov_b32_e32 v184, v183
	v_pk_mul_f32 v[182:183], v[186:187], v[184:185]
	v_pk_mul_f32 v[186:187], v[186:187], v[188:189]
	v_pk_fma_f32 v[182:183], v[174:175], v[188:189], v[182:183] neg_lo:[0,0,1] neg_hi:[0,0,1]
	v_pk_fma_f32 v[174:175], v[174:175], v[184:185], v[186:187]
	v_mov_b32_e32 v185, v168
	v_mov_b32_e32 v168, v167
	v_mov_b32_e32 v184, v166
	v_pk_mul_f32 v[166:167], v[176:177], v[168:169]
	v_pk_mul_f32 v[176:177], v[176:177], v[184:185]
	v_pk_fma_f32 v[166:167], v[170:171], v[184:185], v[166:167] neg_lo:[0,0,1] neg_hi:[0,0,1]
	v_pk_fma_f32 v[168:169], v[170:171], v[168:169], v[176:177]
	v_cvt_pk_bf16_f32 v171, v166, v167
	v_lshlrev_b64 v[166:167], 6, v[152:153]
	v_lshl_add_u64 v[166:167], s[36:37], 0, v[166:167]
	v_cvt_pk_bf16_f32 v170, v182, v183
	v_lshl_add_u64 v[166:167], v[166:167], 0, v[164:165]
	global_store_dwordx2 v[166:167], v[170:171], off
	v_cvt_pk_bf16_f32 v170, v174, v175
	v_cvt_pk_bf16_f32 v171, v168, v169
	global_store_dwordx2 v[166:167], v[170:171], off offset:32
	v_and_b32_e32 v166, 0x7f780, v139
	v_mov_b32_e32 v167, v113
	v_lshl_add_u64 v[166:167], s[46:47], 0, v[166:167]
	v_lshl_add_u64 v[182:183], v[166:167], 0, v[112:113]
	global_load_dwordx4 v[166:169], v[182:183], off offset:16
	s_nop 0
	global_load_dwordx4 v[182:185], v[182:183], off
	v_pk_mul_f32 v[186:187], v[132:133], v[24:25] op_sel_hi:[0,1]
	v_pk_mul_f32 v[174:175], v[132:133], v[28:29] op_sel_hi:[0,1]
	v_pk_mul_f32 v[176:177], v[132:133], v[26:27] op_sel_hi:[0,1]
	v_pk_mul_f32 v[170:171], v[132:133], v[30:31] op_sel_hi:[0,1]
	v_lshlrev_b32_e32 v139, 7, v148
	s_waitcnt vmcnt(0)
	v_mov_b32_e32 v188, v182
	v_mov_b32_e32 v189, v184
	v_mov_b32_e32 v184, v183
	v_pk_mul_f32 v[182:183], v[186:187], v[184:185]
	v_pk_mul_f32 v[186:187], v[186:187], v[188:189]
	v_pk_fma_f32 v[182:183], v[174:175], v[188:189], v[182:183] neg_lo:[0,0,1] neg_hi:[0,0,1]
	v_pk_fma_f32 v[174:175], v[174:175], v[184:185], v[186:187]
	v_mov_b32_e32 v185, v168
	v_mov_b32_e32 v168, v167
	v_mov_b32_e32 v184, v166
	v_pk_mul_f32 v[166:167], v[176:177], v[168:169]
	v_pk_mul_f32 v[176:177], v[176:177], v[184:185]
	v_pk_fma_f32 v[166:167], v[170:171], v[184:185], v[166:167] neg_lo:[0,0,1] neg_hi:[0,0,1]
	v_pk_fma_f32 v[168:169], v[170:171], v[168:169], v[176:177]
	v_cvt_pk_bf16_f32 v171, v166, v167
	v_lshlrev_b64 v[166:167], 6, v[150:151]
	v_lshl_add_u64 v[166:167], s[36:37], 0, v[166:167]
	v_cvt_pk_bf16_f32 v170, v182, v183
	v_lshl_add_u64 v[166:167], v[166:167], 0, v[164:165]
	global_store_dwordx2 v[166:167], v[170:171], off
	v_cvt_pk_bf16_f32 v170, v174, v175
	v_cvt_pk_bf16_f32 v171, v168, v169
	global_store_dwordx2 v[166:167], v[170:171], off offset:32
	v_and_b32_e32 v166, 0x7ff80, v139
	v_mov_b32_e32 v167, v113
	v_lshl_add_u64 v[166:167], s[46:47], 0, v[166:167]
	v_lshl_add_u64 v[182:183], v[166:167], 0, v[112:113]
	global_load_dwordx4 v[166:169], v[182:183], off offset:16
	s_nop 0
	global_load_dwordx4 v[182:185], v[182:183], off
	v_pk_mul_f32 v[186:187], v[130:131], v[8:9] op_sel_hi:[0,1]
	v_pk_mul_f32 v[174:175], v[130:131], v[12:13] op_sel_hi:[0,1]
	v_pk_mul_f32 v[176:177], v[130:131], v[10:11] op_sel_hi:[0,1]
	v_pk_mul_f32 v[170:171], v[130:131], v[14:15] op_sel_hi:[0,1]
	s_waitcnt vmcnt(0)
	v_mov_b32_e32 v188, v182
	v_mov_b32_e32 v189, v184
	v_mov_b32_e32 v184, v183
	v_pk_mul_f32 v[182:183], v[186:187], v[184:185]
	v_pk_mul_f32 v[186:187], v[186:187], v[188:189]
	v_pk_fma_f32 v[182:183], v[174:175], v[188:189], v[182:183] neg_lo:[0,0,1] neg_hi:[0,0,1]
	v_pk_fma_f32 v[174:175], v[174:175], v[184:185], v[186:187]
	v_mov_b32_e32 v185, v168
	v_mov_b32_e32 v168, v167
	v_mov_b32_e32 v184, v166
	v_pk_mul_f32 v[166:167], v[176:177], v[168:169]
	v_pk_mul_f32 v[176:177], v[176:177], v[184:185]
	v_pk_fma_f32 v[166:167], v[170:171], v[184:185], v[166:167] neg_lo:[0,0,1] neg_hi:[0,0,1]
	v_pk_fma_f32 v[168:169], v[170:171], v[168:169], v[176:177]
	v_cvt_pk_bf16_f32 v171, v166, v167
	v_lshlrev_b64 v[166:167], 6, v[148:149]
	v_lshl_add_u64 v[166:167], s[36:37], 0, v[166:167]
	v_cvt_pk_bf16_f32 v170, v182, v183
	v_lshl_add_u64 v[164:165], v[166:167], 0, v[164:165]
	v_cvt_pk_bf16_f32 v166, v174, v175
	v_cvt_pk_bf16_f32 v167, v168, v169
	global_store_dwordx2 v[164:165], v[170:171], off
	global_store_dwordx2 v[164:165], v[166:167], off offset:32

.LBB0_541:
	s_lshl_b32 s4, s14, 6
	s_and_b32 s4, s4, 0x1c0
	s_ashr_i32 s5, s14, 3
	s_add_i32 s4, s4, s5
	s_lshr_b32 s5, s4, 30
	s_add_i32 s5, s4, s5
	s_and_b32 s6, s5, 0xfffffc
	v_mov_b32_e32 v138, v157
	v_mov_b32_e32 v10, v157
	s_sub_i32 s7, s4, s6
	s_lshl_b32 s4, s5, 6
	v_readfirstlane_b32 s31, v10
	s_lshl_b32 s5, s7, 8
	s_ashr_i32 s7, s31, 6
	s_and_b32 s4, s4, 0xffffff00
	s_lshl_b32 s70, s7, 2
	s_add_i32 s72, s5, 0xffffff00
	s_cmp_lt_i32 s7, 4
	s_cselect_b64 s[8:9], -1, 0
	s_and_b32 s73, s31, 0xffffffc0
	s_and_b64 s[10:11], s[8:9], exec
	s_cselect_b32 s10, s4, s72
	s_add_i32 s10, s10, s73
	s_and_b64 s[8:9], s[8:9], exec
	s_cselect_b32 s18, s55, s13
	s_cselect_b32 s19, s54, s12
	s_ashr_i32 s11, s10, 31
	s_lshl_b64 s[8:9], s[10:11], 11
	s_add_u32 s8, s19, s8
	s_addc_u32 s9, s18, s9
	s_or_b32 s18, s70, 1
	s_cmp_lt_i32 s18, 16
	s_cselect_b64 s[10:11], -1, 0
	s_lshl_b32 s68, s18, 4
	s_and_b64 s[18:19], s[10:11], exec
	s_cselect_b32 s74, s4, s72
	s_add_i32 s18, s74, s68
	s_and_b64 s[10:11], s[10:11], exec
	s_cselect_b32 s75, s55, s13
	s_cselect_b32 s78, s54, s12
	s_ashr_i32 s19, s18, 31
	s_lshl_b64 s[10:11], s[18:19], 11
	s_add_u32 s10, s78, s10
	s_addc_u32 s11, s75, s11
	s_or_b32 s68, s70, 2
	s_cmp_lt_i32 s68, 16
	s_cselect_b64 s[18:19], -1, 0
	s_lshl_b32 s71, s68, 4
	s_and_b64 s[68:69], s[18:19], exec
	s_cselect_b32 s79, s4, s72
	s_add_i32 s68, s79, s71
	s_and_b64 s[18:19], s[18:19], exec
	s_cselect_b32 s84, s55, s13
	s_cselect_b32 s85, s54, s12
	s_ashr_i32 s69, s68, 31
	s_lshl_b64 s[18:19], s[68:69], 11
	s_add_u32 s18, s85, s18
	s_addc_u32 s19, s84, s19
	s_or_b32 s70, s70, 3
	s_cmp_lt_i32 s70, 16
	s_cselect_b64 s[68:69], -1, 0
	s_lshl_b32 s86, s70, 4
	s_and_b64 s[70:71], s[68:69], exec
	s_cselect_b32 s72, s4, s72
	s_add_i32 s70, s72, s86
	s_and_b64 s[68:69], s[68:69], exec
	v_lshrrev_b32_e32 v11, 4, v10
	s_cselect_b32 s86, s55, s13
	s_cselect_b32 s87, s54, s12
	s_ashr_i32 s71, s70, 31
	v_sub_u32_e32 v1, 0, v11
	s_lshl_b64 s[68:69], s[70:71], 11
	v_lshlrev_b32_e32 v0, 9, v10
	v_xor_b32_e32 v1, v10, v1
	s_add_u32 s68, s87, s68
	v_and_b32_e32 v0, 0x7800, v0
	v_lshlrev_b32_e32 v1, 4, v1
	s_addc_u32 s69, s86, s69
	s_lshl_b32 s7, s7, 12
	v_and_or_b32 v112, v1, 48, v0
	s_mov_b32 m0, s7
	v_lshl_add_u64 v[0:1], s[8:9], 0, v[112:113]
	global_load_lds_dwordx4 v112, s[8:9]
	s_or_b32 m0, s7, 0x400
	v_lshl_add_u64 v[2:3], s[10:11], 0, v[112:113]
	global_load_lds_dwordx4 v112, s[10:11]
	s_or_b32 m0, s7, 0x800
	v_lshl_add_u64 v[8:9], v[0:1], 0, 64
	global_load_lds_dwordx4 v112, s[18:19]
	s_or_b32 m0, s7, 0xc00
	v_lshl_add_u64 v[4:5], s[18:19], 0, v[112:113]
	global_load_lds_dwordx4 v112, s[68:69]
	s_add_i32 m0, s7, 0x8000
	v_lshl_add_u64 v[6:7], s[68:69], 0, v[112:113]
	global_load_lds_dwordx4 v[8:9], off
	v_lshl_add_u64 v[8:9], v[2:3], 0, 64
	s_add_i32 m0, s7, 0x8400
	v_lshl_add_u64 v[2:3], v[2:3], 0, s[90:91]
	global_load_lds_dwordx4 v[8:9], off
	v_lshl_add_u64 v[8:9], v[4:5], 0, 64
	s_add_i32 m0, s7, 0x8800
	s_lshr_b32 s8, s31, 1
	global_load_lds_dwordx4 v[8:9], off
	v_lshl_add_u64 v[8:9], v[6:7], 0, 64
	s_add_i32 m0, s7, 0x8c00
	v_and_b32_e32 v12, 15, v10
	global_load_lds_dwordx4 v[8:9], off
	s_add_i32 m0, s7, 0x10000
	v_lshl_add_u64 v[8:9], v[0:1], 0, s[90:91]
	global_load_lds_dwordx4 v[8:9], off
	s_add_i32 m0, s7, 0x10400
	s_and_b32 s8, s8, 0x3ffff80
	global_load_lds_dwordx4 v[2:3], off
	v_lshl_add_u64 v[2:3], v[4:5], 0, s[90:91]
	s_add_i32 m0, s7, 0x10800
	v_lshl_add_u64 v[136:137], v[0:1], 0, s[76:77]
	global_load_lds_dwordx4 v[2:3], off
	v_lshl_add_u64 v[2:3], v[6:7], 0, s[90:91]
	s_add_i32 m0, s7, 0x10c00
	v_mov_b32_e32 v0, 0
	global_load_lds_dwordx4 v[2:3], off
	v_lshrrev_b32_e32 v2, 2, v10
	v_sub_u32_e32 v2, 0, v2
	v_bitop3_b32 v2, v11, 3, v2 bitop3:0x48
	v_or_b32_e32 v3, s8, v12
	v_lshlrev_b32_e32 v2, 4, v2
	s_and_b32 s8, s31, 0xc0
	v_lshl_or_b32 v139, v3, 6, v2
	v_or_b32_e32 v3, s8, v12
	s_add_i32 s8, s72, s73
	s_ashr_i32 s9, s8, 31
	s_lshl_b64 s[8:9], s[8:9], 11
	s_add_u32 s8, s87, s8
	v_lshlrev_b32_e32 v3, 6, v3
	s_addc_u32 s9, s86, s9
	v_or3_b32 v140, v2, v3, s83
	v_lshl_add_u64 v[2:3], s[8:9], 0, v[112:113]
	s_add_i32 s8, s79, s73
	s_ashr_i32 s9, s8, 31
	s_lshl_b64 s[8:9], s[8:9], 11
	s_add_u32 s8, s85, s8
	s_addc_u32 s9, s84, s9
	v_lshl_add_u64 v[130:131], v[2:3], 0, s[92:93]
	v_lshl_add_u64 v[2:3], s[8:9], 0, v[112:113]
	s_add_i32 s8, s74, s73
	s_ashr_i32 s9, s8, 31
	s_lshl_b64 s[8:9], s[8:9], 11
	s_add_u32 s8, s78, s8
	s_addc_u32 s9, s75, s9
	v_lshl_add_u64 v[132:133], v[2:3], 0, s[94:95]
	v_lshl_add_u64 v[2:3], s[8:9], 0, v[112:113]
	v_readfirstlane_b32 s6, v138
	v_lshl_add_u64 v[134:135], v[2:3], 0, s[96:97]
	s_mov_b32 s8, 0x18000
	v_mov_b32_e32 v1, v0
	v_mov_b32_e32 v2, v0
	v_mov_b32_e32 v3, v0
	v_mov_b32_e32 v4, v0
	v_mov_b32_e32 v5, v0
	v_mov_b32_e32 v6, v0
	v_mov_b32_e32 v7, v0
	v_mov_b32_e32 v8, v0
	v_mov_b32_e32 v9, v0
	v_mov_b32_e32 v10, v0
	v_mov_b32_e32 v11, v0
	v_mov_b32_e32 v12, v0
	v_mov_b32_e32 v13, v0
	v_mov_b32_e32 v14, v0
	v_mov_b32_e32 v15, v0
	v_mov_b32_e32 v16, v0
	v_mov_b32_e32 v17, v0
	v_mov_b32_e32 v18, v0
	v_mov_b32_e32 v19, v0
	v_mov_b32_e32 v20, v0
	v_mov_b32_e32 v21, v0
	v_mov_b32_e32 v22, v0
	v_mov_b32_e32 v23, v0
	v_mov_b32_e32 v24, v0
	v_mov_b32_e32 v25, v0
	v_mov_b32_e32 v26, v0
	v_mov_b32_e32 v27, v0
	v_mov_b32_e32 v28, v0
	v_mov_b32_e32 v29, v0
	v_mov_b32_e32 v30, v0
	v_mov_b32_e32 v31, v0
	v_mov_b32_e32 v32, v0
	v_mov_b32_e32 v33, v0
	v_mov_b32_e32 v34, v0
	v_mov_b32_e32 v35, v0
	v_mov_b32_e32 v36, v0
	v_mov_b32_e32 v37, v0
	v_mov_b32_e32 v38, v0
	v_mov_b32_e32 v39, v0
	v_mov_b32_e32 v40, v0
	v_mov_b32_e32 v41, v0
	v_mov_b32_e32 v42, v0
	v_mov_b32_e32 v43, v0
	v_mov_b32_e32 v44, v0
	v_mov_b32_e32 v45, v0
	v_mov_b32_e32 v46, v0
	v_mov_b32_e32 v47, v0
	v_mov_b32_e32 v48, v0
	v_mov_b32_e32 v49, v0
	v_mov_b32_e32 v50, v0
	v_mov_b32_e32 v51, v0
	v_mov_b32_e32 v52, v0
	v_mov_b32_e32 v53, v0
	v_mov_b32_e32 v54, v0
	v_mov_b32_e32 v55, v0
	v_mov_b32_e32 v56, v0
	v_mov_b32_e32 v57, v0
	v_mov_b32_e32 v58, v0
	v_mov_b32_e32 v59, v0
	v_mov_b32_e32 v60, v0
	v_mov_b32_e32 v61, v0
	v_mov_b32_e32 v62, v0
	v_mov_b32_e32 v63, v0
	v_mov_b32_e32 v64, v0
	v_mov_b32_e32 v65, v0
	v_mov_b32_e32 v66, v0
	v_mov_b32_e32 v67, v0
	v_mov_b32_e32 v68, v0
	v_mov_b32_e32 v69, v0
	v_mov_b32_e32 v70, v0
	v_mov_b32_e32 v71, v0
	v_mov_b32_e32 v72, v0
	v_mov_b32_e32 v73, v0
	v_mov_b32_e32 v74, v0
	v_mov_b32_e32 v75, v0
	v_mov_b32_e32 v76, v0
	v_mov_b32_e32 v77, v0
	v_mov_b32_e32 v78, v0
	v_mov_b32_e32 v79, v0
	v_mov_b32_e32 v80, v0
	v_mov_b32_e32 v81, v0
	v_mov_b32_e32 v82, v0
	v_mov_b32_e32 v83, v0
	v_mov_b32_e32 v84, v0
	v_mov_b32_e32 v85, v0
	v_mov_b32_e32 v86, v0
	v_mov_b32_e32 v87, v0
	v_mov_b32_e32 v88, v0
	v_mov_b32_e32 v89, v0
	v_mov_b32_e32 v90, v0
	v_mov_b32_e32 v91, v0
	v_mov_b32_e32 v92, v0
	v_mov_b32_e32 v93, v0
	v_mov_b32_e32 v94, v0
	v_mov_b32_e32 v95, v0
	v_mov_b32_e32 v96, v0
	v_mov_b32_e32 v97, v0
	v_mov_b32_e32 v98, v0
	v_mov_b32_e32 v99, v0
	v_mov_b32_e32 v100, v0
	v_mov_b32_e32 v101, v0
	v_mov_b32_e32 v102, v0
	v_mov_b32_e32 v103, v0
	v_mov_b32_e32 v104, v0
	v_mov_b32_e32 v105, v0
	v_mov_b32_e32 v106, v0
	v_mov_b32_e32 v107, v0
	v_mov_b32_e32 v108, v0
	v_mov_b32_e32 v109, v0
	v_mov_b32_e32 v110, v0
	v_mov_b32_e32 v111, v0
	v_mov_b32_e32 v114, v0
	v_mov_b32_e32 v115, v0
	v_mov_b32_e32 v116, v0
	v_mov_b32_e32 v117, v0
	v_mov_b32_e32 v118, v0
	v_mov_b32_e32 v119, v0
	v_mov_b32_e32 v120, v0
	v_mov_b32_e32 v121, v0
	v_mov_b32_e32 v122, v0
	v_mov_b32_e32 v123, v0
	v_mov_b32_e32 v124, v0
	v_mov_b32_e32 v125, v0
	v_mov_b32_e32 v126, v0
	v_mov_b32_e32 v127, v0
	v_mov_b32_e32 v128, v0
	v_mov_b32_e32 v129, v0
	s_add_i32 s9, s8, 0xfffe8000
	s_and_b32 s10, s8, 0x18000
	s_waitcnt vmcnt(8)
	s_barrier
	s_and_b32 s9, s9, 0x18000
	s_add_i32 s10, s7, s10
	v_add_u32_e32 v112, s9, v139
	v_or_b32_e32 v141, s9, v140
	s_add_i32 s18, s10, 0x400
	s_add_i32 s11, s10, 0x800
	s_add_i32 s9, s10, 0xc00
	s_add_i32 s8, s8, 0x8000
	s_cmp_eq_u32 s8, 0x100000
	ds_read_b128 v[162:165], v112
	ds_read_b128 v[142:145], v141
	ds_read_b128 v[146:149], v141 offset:1024
	ds_read_b128 v[150:153], v141 offset:2048
	ds_read_b128 v[158:161], v141 offset:3072
	ds_read_b128 v[166:169], v112 offset:1024
	ds_read_b128 v[174:177], v112 offset:2048
	ds_read_b128 v[182:185], v112 offset:3072
	ds_read_b128 v[232:235], v112 offset:4096
	ds_read_b128 v[236:239], v112 offset:5120
	ds_read_b128 v[240:243], v112 offset:6144
	ds_read_b128 v[244:247], v112 offset:7168
	s_mov_b32 m0, s10
	s_nop 0
	global_load_lds_dwordx4 v[136:137], off
	v_lshl_add_u64 v[136:137], v[136:137], 0, 64
	s_mov_b32 m0, s18
	s_nop 0
	global_load_lds_dwordx4 v[134:135], off
	v_lshl_add_u64 v[134:135], v[134:135], 0, 64
	s_mov_b32 m0, s11
	s_nop 0
	global_load_lds_dwordx4 v[132:133], off
	v_lshl_add_u64 v[132:133], v[132:133], 0, 64
	s_mov_b32 m0, s9
	s_nop 0
	global_load_lds_dwordx4 v[130:131], off
	v_lshl_add_u64 v[130:131], v[130:131], 0, 64
	s_waitcnt lgkmcnt(4)
	v_mfma_f32_16x16x32_bf16 v[126:129], v[142:145], v[162:165], v[126:129]
	v_mfma_f32_16x16x32_bf16 v[122:125], v[146:149], v[162:165], v[122:125]
	v_mfma_f32_16x16x32_bf16 v[118:121], v[150:153], v[162:165], v[118:121]
	v_mfma_f32_16x16x32_bf16 v[114:117], v[158:161], v[162:165], v[114:117]
	v_mfma_f32_16x16x32_bf16 v[108:111], v[142:145], v[166:169], v[108:111]
	v_mfma_f32_16x16x32_bf16 v[104:107], v[146:149], v[166:169], v[104:107]
	v_mfma_f32_16x16x32_bf16 v[100:103], v[150:153], v[166:169], v[100:103]
	v_mfma_f32_16x16x32_bf16 v[96:99], v[158:161], v[166:169], v[96:99]
	v_mfma_f32_16x16x32_bf16 v[92:95], v[142:145], v[174:177], v[92:95]
	v_mfma_f32_16x16x32_bf16 v[88:91], v[146:149], v[174:177], v[88:91]
	v_mfma_f32_16x16x32_bf16 v[84:87], v[150:153], v[174:177], v[84:87]
	v_mfma_f32_16x16x32_bf16 v[80:83], v[158:161], v[174:177], v[80:83]
	v_mfma_f32_16x16x32_bf16 v[76:79], v[142:145], v[182:185], v[76:79]
	v_mfma_f32_16x16x32_bf16 v[72:75], v[146:149], v[182:185], v[72:75]
	v_mfma_f32_16x16x32_bf16 v[68:71], v[150:153], v[182:185], v[68:71]
	v_mfma_f32_16x16x32_bf16 v[64:67], v[158:161], v[182:185], v[64:67]
.Lgsk1_loop:
	s_add_i32 s9, s8, 0xfffe8000
	s_and_b32 s10, s8, 0x18000
	s_waitcnt vmcnt(8) lgkmcnt(0)
	s_barrier
	s_and_b32 s9, s9, 0x18000
	s_add_i32 s10, s7, s10
	v_add_u32_e32 v112, s9, v139
	v_or_b32_e32 v141, s9, v140
	s_add_i32 s18, s10, 0x400
	s_add_i32 s11, s10, 0x800
	s_add_i32 s9, s10, 0xc00
	s_add_i32 s8, s8, 0x8000
	s_cmp_eq_u32 s8, 0x100000
	ds_read_b128 v[162:165], v112
	ds_read_b128 v[166:169], v112 offset:1024
	ds_read_b128 v[174:177], v112 offset:2048
	ds_read_b128 v[182:185], v112 offset:3072
	v_mfma_f32_16x16x32_bf16 v[60:63], v[142:145], v[232:235], v[60:63]
	v_mfma_f32_16x16x32_bf16 v[44:47], v[142:145], v[236:239], v[44:47]
	v_mfma_f32_16x16x32_bf16 v[28:31], v[142:145], v[240:243], v[28:31]
	s_mov_b32 m0, s10
	v_mfma_f32_16x16x32_bf16 v[12:15], v[142:145], v[244:247], v[12:15]
	global_load_lds_dwordx4 v[136:137], off
	v_lshl_add_u64 v[136:137], v[136:137], 0, 64
	v_mfma_f32_16x16x32_bf16 v[56:59], v[146:149], v[232:235], v[56:59]
	ds_read_b128 v[142:145], v141
	v_mfma_f32_16x16x32_bf16 v[40:43], v[146:149], v[236:239], v[40:43]
	v_mfma_f32_16x16x32_bf16 v[24:27], v[146:149], v[240:243], v[24:27]
	s_mov_b32 m0, s18
	v_mfma_f32_16x16x32_bf16 v[8:11], v[146:149], v[244:247], v[8:11]
	global_load_lds_dwordx4 v[134:135], off
	v_lshl_add_u64 v[134:135], v[134:135], 0, 64
	v_mfma_f32_16x16x32_bf16 v[52:55], v[150:153], v[232:235], v[52:55]
	ds_read_b128 v[146:149], v141 offset:1024
	v_mfma_f32_16x16x32_bf16 v[36:39], v[150:153], v[236:239], v[36:39]
	v_mfma_f32_16x16x32_bf16 v[20:23], v[150:153], v[240:243], v[20:23]
	s_mov_b32 m0, s11
	v_mfma_f32_16x16x32_bf16 v[4:7], v[150:153], v[244:247], v[4:7]
	global_load_lds_dwordx4 v[132:133], off
	v_lshl_add_u64 v[132:133], v[132:133], 0, 64
	v_mfma_f32_16x16x32_bf16 v[48:51], v[158:161], v[232:235], v[48:51]
	ds_read_b128 v[150:153], v141 offset:2048
	v_mfma_f32_16x16x32_bf16 v[32:35], v[158:161], v[236:239], v[32:35]
	v_mfma_f32_16x16x32_bf16 v[16:19], v[158:161], v[240:243], v[16:19]
	s_mov_b32 m0, s9
	v_mfma_f32_16x16x32_bf16 v[0:3], v[158:161], v[244:247], v[0:3]
	global_load_lds_dwordx4 v[130:131], off
	v_lshl_add_u64 v[130:131], v[130:131], 0, 64
	s_waitcnt lgkmcnt(2)
	v_mfma_f32_16x16x32_bf16 v[126:129], v[142:145], v[162:165], v[126:129]
	ds_read_b128 v[158:161], v141 offset:3072
	v_mfma_f32_16x16x32_bf16 v[108:111], v[142:145], v[166:169], v[108:111]
	ds_read_b128 v[232:235], v112 offset:4096
	ds_read_b128 v[236:239], v112 offset:5120
	v_mfma_f32_16x16x32_bf16 v[92:95], v[142:145], v[174:177], v[92:95]
	ds_read_b128 v[240:243], v112 offset:6144
	ds_read_b128 v[244:247], v112 offset:7168
	v_mfma_f32_16x16x32_bf16 v[76:79], v[142:145], v[182:185], v[76:79]
	s_waitcnt lgkmcnt(6)
	v_mfma_f32_16x16x32_bf16 v[122:125], v[146:149], v[162:165], v[122:125]
	v_mfma_f32_16x16x32_bf16 v[104:107], v[146:149], v[166:169], v[104:107]
	v_mfma_f32_16x16x32_bf16 v[88:91], v[146:149], v[174:177], v[88:91]
	v_mfma_f32_16x16x32_bf16 v[72:75], v[146:149], v[182:185], v[72:75]
	s_waitcnt lgkmcnt(5)
	v_mfma_f32_16x16x32_bf16 v[118:121], v[150:153], v[162:165], v[118:121]
	v_mfma_f32_16x16x32_bf16 v[100:103], v[150:153], v[166:169], v[100:103]
	v_mfma_f32_16x16x32_bf16 v[84:87], v[150:153], v[174:177], v[84:87]
	v_mfma_f32_16x16x32_bf16 v[68:71], v[150:153], v[182:185], v[68:71]
	s_waitcnt lgkmcnt(4)
	v_mfma_f32_16x16x32_bf16 v[114:117], v[158:161], v[162:165], v[114:117]
	v_mfma_f32_16x16x32_bf16 v[96:99], v[158:161], v[166:169], v[96:99]
	v_mfma_f32_16x16x32_bf16 v[80:83], v[158:161], v[174:177], v[80:83]
	v_mfma_f32_16x16x32_bf16 v[64:67], v[158:161], v[182:185], v[64:67]
	s_cbranch_scc0 .Lgsk1_loop
	s_waitcnt lgkmcnt(0)
	v_mfma_f32_16x16x32_bf16 v[60:63], v[142:145], v[232:235], v[60:63]
	v_mfma_f32_16x16x32_bf16 v[44:47], v[142:145], v[236:239], v[44:47]
	v_mfma_f32_16x16x32_bf16 v[28:31], v[142:145], v[240:243], v[28:31]
	v_mfma_f32_16x16x32_bf16 v[12:15], v[142:145], v[244:247], v[12:15]
	v_mfma_f32_16x16x32_bf16 v[56:59], v[146:149], v[232:235], v[56:59]
	v_mfma_f32_16x16x32_bf16 v[40:43], v[146:149], v[236:239], v[40:43]
	v_mfma_f32_16x16x32_bf16 v[24:27], v[146:149], v[240:243], v[24:27]
	v_mfma_f32_16x16x32_bf16 v[8:11], v[146:149], v[244:247], v[8:11]
	v_mfma_f32_16x16x32_bf16 v[52:55], v[150:153], v[232:235], v[52:55]
	v_mfma_f32_16x16x32_bf16 v[36:39], v[150:153], v[236:239], v[36:39]
	v_mfma_f32_16x16x32_bf16 v[20:23], v[150:153], v[240:243], v[20:23]
	v_mfma_f32_16x16x32_bf16 v[4:7], v[150:153], v[244:247], v[4:7]
	v_mfma_f32_16x16x32_bf16 v[48:51], v[158:161], v[232:235], v[48:51]
	v_mfma_f32_16x16x32_bf16 v[32:35], v[158:161], v[236:239], v[32:35]
	v_mfma_f32_16x16x32_bf16 v[16:19], v[158:161], v[240:243], v[16:19]
	v_mfma_f32_16x16x32_bf16 v[0:3], v[158:161], v[244:247], v[0:3]
	s_waitcnt vmcnt(8)
	s_barrier
	v_add_u32_e32 v112, 0x8000, v139
	v_or_b32_e32 v141, 0x8000, v140
	ds_read_b128 v[130:133], v141
	ds_read_b128 v[134:137], v141 offset:1024
	ds_read_b128 v[142:145], v141 offset:2048
	ds_read_b128 v[146:149], v141 offset:3072
	ds_read_b128 v[150:153], v112
	ds_read_b128 v[158:161], v112 offset:1024
	ds_read_b128 v[162:165], v112 offset:2048
	ds_read_b128 v[166:169], v112 offset:3072
	v_add_u32_e32 v141, 0x10000, v139
	s_waitcnt lgkmcnt(0)
	v_or_b32_e32 v154, 0x10000, v140
	v_mfma_f32_16x16x32_bf16 v[126:129], v[130:133], v[150:153], v[126:129]
	v_add_u32_e32 v139, 0x18000, v139
	s_lshl_b32 s8, s6, 8
	v_and_b32_e32 v170, 15, v138
	v_mfma_f32_16x16x32_bf16 v[122:125], v[134:137], v[150:153], v[122:125]
	s_and_b32 s18, s8, 0xffffc000
	s_ashr_i32 s7, s6, 1
	s_and_b32 s7, s7, 0xffffff80
	v_mfma_f32_16x16x32_bf16 v[118:121], v[142:145], v[150:153], v[118:121]
	s_and_b32 s6, s6, 0xc0
	s_add_i32 s8, s4, s7
	s_or_b32 s4, s5, s6
	v_mfma_f32_16x16x32_bf16 v[114:117], v[146:149], v[150:153], v[114:117]
	s_ashr_i32 s10, s4, 6
	s_ashr_i32 s11, s10, 31
	v_mfma_f32_16x16x32_bf16 v[108:111], v[130:133], v[158:161], v[108:111]
	v_mfma_f32_16x16x32_bf16 v[104:107], v[134:137], v[158:161], v[104:107]
	v_mfma_f32_16x16x32_bf16 v[100:103], v[142:145], v[158:161], v[100:103]
	v_mfma_f32_16x16x32_bf16 v[96:99], v[146:149], v[158:161], v[96:99]
	v_mfma_f32_16x16x32_bf16 v[92:95], v[130:133], v[162:165], v[92:95]
	v_mfma_f32_16x16x32_bf16 v[88:91], v[134:137], v[162:165], v[88:91]
	v_mfma_f32_16x16x32_bf16 v[84:87], v[142:145], v[162:165], v[84:87]
	v_mfma_f32_16x16x32_bf16 v[80:83], v[146:149], v[162:165], v[80:83]
	v_mfma_f32_16x16x32_bf16 v[76:79], v[130:133], v[166:169], v[76:79]
	v_mfma_f32_16x16x32_bf16 v[72:75], v[134:137], v[166:169], v[72:75]
	v_mfma_f32_16x16x32_bf16 v[68:71], v[142:145], v[166:169], v[68:71]
	v_mfma_f32_16x16x32_bf16 v[64:67], v[146:149], v[166:169], v[64:67]
	ds_read_b128 v[150:153], v112 offset:4096
	ds_read_b128 v[158:161], v112 offset:5120
	ds_read_b128 v[162:165], v112 offset:6144
	ds_read_b128 v[166:169], v112 offset:7168
	s_waitcnt lgkmcnt(0)
	s_waitcnt vmcnt(4)
	s_barrier
	v_mfma_f32_16x16x32_bf16 v[60:63], v[130:133], v[150:153], v[60:63]
	v_and_b32_e32 v112, 63, v138
	v_mfma_f32_16x16x32_bf16 v[56:59], v[134:137], v[150:153], v[56:59]
	v_mfma_f32_16x16x32_bf16 v[52:55], v[142:145], v[150:153], v[52:55]
	v_mfma_f32_16x16x32_bf16 v[48:51], v[146:149], v[150:153], v[48:51]
	v_mfma_f32_16x16x32_bf16 v[44:47], v[130:133], v[158:161], v[44:47]
	v_mfma_f32_16x16x32_bf16 v[40:43], v[134:137], v[158:161], v[40:43]
	v_mfma_f32_16x16x32_bf16 v[36:39], v[142:145], v[158:161], v[36:39]
	v_mfma_f32_16x16x32_bf16 v[32:35], v[146:149], v[158:161], v[32:35]
	v_mfma_f32_16x16x32_bf16 v[28:31], v[130:133], v[162:165], v[28:31]
	v_mfma_f32_16x16x32_bf16 v[24:27], v[134:137], v[162:165], v[24:27]
	v_mfma_f32_16x16x32_bf16 v[20:23], v[142:145], v[162:165], v[20:23]
	v_mfma_f32_16x16x32_bf16 v[16:19], v[146:149], v[162:165], v[16:19]
	v_mfma_f32_16x16x32_bf16 v[12:15], v[130:133], v[166:169], v[12:15]
	v_mfma_f32_16x16x32_bf16 v[8:11], v[134:137], v[166:169], v[8:11]
	v_mfma_f32_16x16x32_bf16 v[4:7], v[142:145], v[166:169], v[4:7]
	v_mfma_f32_16x16x32_bf16 v[0:3], v[146:149], v[166:169], v[0:3]
	ds_read_b128 v[130:133], v154
	ds_read_b128 v[134:137], v154 offset:1024
	ds_read_b128 v[142:145], v154 offset:2048
	ds_read_b128 v[146:149], v154 offset:3072
	ds_read_b128 v[150:153], v141
	ds_read_b128 v[158:161], v141 offset:1024
	ds_read_b128 v[162:165], v141 offset:2048
	ds_read_b128 v[166:169], v141 offset:3072
	s_nop 0
	s_waitcnt lgkmcnt(0)
	s_nop 0
	v_mfma_f32_16x16x32_bf16 v[126:129], v[130:133], v[150:153], v[126:129]
	v_mfma_f32_16x16x32_bf16 v[122:125], v[134:137], v[150:153], v[122:125]
	v_mfma_f32_16x16x32_bf16 v[118:121], v[142:145], v[150:153], v[118:121]
	v_mfma_f32_16x16x32_bf16 v[114:117], v[146:149], v[150:153], v[114:117]
	v_mfma_f32_16x16x32_bf16 v[108:111], v[130:133], v[158:161], v[108:111]
	v_mfma_f32_16x16x32_bf16 v[104:107], v[134:137], v[158:161], v[104:107]
	v_mfma_f32_16x16x32_bf16 v[100:103], v[142:145], v[158:161], v[100:103]
	v_mfma_f32_16x16x32_bf16 v[150:153], v[146:149], v[158:161], v[96:99]
	v_mfma_f32_16x16x32_bf16 v[92:95], v[130:133], v[162:165], v[92:95]
	v_mfma_f32_16x16x32_bf16 v[88:91], v[134:137], v[162:165], v[88:91]
	v_mfma_f32_16x16x32_bf16 v[84:87], v[142:145], v[162:165], v[84:87]
	v_mfma_f32_16x16x32_bf16 v[80:83], v[146:149], v[162:165], v[80:83]
	v_mfma_f32_16x16x32_bf16 v[76:79], v[130:133], v[166:169], v[76:79]
	v_mfma_f32_16x16x32_bf16 v[72:75], v[134:137], v[166:169], v[72:75]
	v_mfma_f32_16x16x32_bf16 v[68:71], v[142:145], v[166:169], v[68:71]
	v_mfma_f32_16x16x32_bf16 v[64:67], v[146:149], v[166:169], v[64:67]
	ds_read_b128 v[96:99], v141 offset:4096
	ds_read_b128 v[158:161], v141 offset:5120
	ds_read_b128 v[162:165], v141 offset:6144
	ds_read_b128 v[166:169], v141 offset:7168
	s_waitcnt lgkmcnt(0)
	s_waitcnt vmcnt(0)
	s_barrier
	v_mfma_f32_16x16x32_bf16 v[60:63], v[130:133], v[96:99], v[60:63]
	v_mfma_f32_16x16x32_bf16 v[56:59], v[134:137], v[96:99], v[56:59]
	v_mfma_f32_16x16x32_bf16 v[52:55], v[142:145], v[96:99], v[52:55]
	v_mfma_f32_16x16x32_bf16 v[48:51], v[146:149], v[96:99], v[48:51]
	v_mfma_f32_16x16x32_bf16 v[44:47], v[130:133], v[158:161], v[44:47]
	v_mfma_f32_16x16x32_bf16 v[40:43], v[134:137], v[158:161], v[40:43]
	v_mfma_f32_16x16x32_bf16 v[36:39], v[142:145], v[158:161], v[36:39]
	v_mfma_f32_16x16x32_bf16 v[32:35], v[146:149], v[158:161], v[32:35]
	v_mfma_f32_16x16x32_bf16 v[28:31], v[130:133], v[162:165], v[28:31]
	v_mfma_f32_16x16x32_bf16 v[24:27], v[134:137], v[162:165], v[24:27]
	v_mfma_f32_16x16x32_bf16 v[20:23], v[142:145], v[162:165], v[20:23]
	v_mfma_f32_16x16x32_bf16 v[16:19], v[146:149], v[162:165], v[16:19]
	v_mfma_f32_16x16x32_bf16 v[12:15], v[130:133], v[166:169], v[12:15]
	v_mfma_f32_16x16x32_bf16 v[8:11], v[134:137], v[166:169], v[8:11]
	v_mfma_f32_16x16x32_bf16 v[4:7], v[142:145], v[166:169], v[4:7]
	v_mfma_f32_16x16x32_bf16 v[0:3], v[146:149], v[166:169], v[0:3]
	v_or_b32_e32 v148, 0x18000, v140
	ds_read_b128 v[130:133], v148
	ds_read_b128 v[134:137], v148 offset:1024
	ds_read_b128 v[140:143], v148 offset:2048
	ds_read_b128 v[144:147], v148 offset:3072
	ds_read_b128 v[96:99], v139
	ds_read_b128 v[158:161], v139 offset:1024
	ds_read_b128 v[162:165], v139 offset:2048
	ds_read_b128 v[166:169], v139 offset:3072
	s_nop 0
	s_waitcnt lgkmcnt(0)
	s_nop 0
	v_mfma_f32_16x16x32_bf16 v[126:129], v[130:133], v[96:99], v[126:129]
	v_mfma_f32_16x16x32_bf16 v[174:177], v[134:137], v[96:99], v[122:125]
	v_mfma_f32_16x16x32_bf16 v[182:185], v[140:143], v[96:99], v[118:121]
	v_mfma_f32_16x16x32_bf16 v[114:117], v[144:147], v[96:99], v[114:117]
	v_mfma_f32_16x16x32_bf16 v[96:99], v[140:143], v[158:161], v[100:103]
	v_mfma_f32_16x16x32_bf16 v[100:103], v[144:147], v[158:161], v[150:153]
	ds_read_b128 v[118:121], v139 offset:4096
	ds_read_b128 v[122:125], v139 offset:5120
	ds_read_b128 v[148:151], v139 offset:6144
	ds_read_b128 v[152:155], v139 offset:7168
	s_waitcnt lgkmcnt(0)
	s_barrier
	v_mfma_f32_16x16x32_bf16 v[60:63], v[130:133], v[118:121], v[60:63]
	v_mfma_f32_16x16x32_bf16 v[56:59], v[134:137], v[118:121], v[56:59]
	v_mfma_f32_16x16x32_bf16 v[52:55], v[140:143], v[118:121], v[52:55]
	v_mfma_f32_16x16x32_bf16 v[48:51], v[144:147], v[118:121], v[48:51]
	v_bfe_u32 v119, v138, 5, 1
	v_lshrrev_b32_e32 v121, 1, v138
	v_lshlrev_b32_e32 v118, 7, v170
	v_mfma_f32_16x16x32_bf16 v[44:47], v[130:133], v[122:125], v[44:47]
	v_and_b32_e32 v121, 8, v121
	v_and_b32_e32 v120, 7, v138
	v_mfma_f32_16x16x32_bf16 v[40:43], v[134:137], v[122:125], v[40:43]
	v_mfma_f32_16x16x32_bf16 v[36:39], v[140:143], v[122:125], v[36:39]
	v_mfma_f32_16x16x32_bf16 v[32:35], v[144:147], v[122:125], v[32:35]
	v_mul_f32_e32 v125, v127, v127
	v_bitop3_b32 v124, v119, v138, 7 bitop3:0x78
	v_or3_b32 v123, s18, v118, v121
	v_fmac_f32_e32 v125, v126, v126
	v_lshlrev_b32_e32 v124, 4, v124
	v_fmac_f32_e32 v125, v128, v128
	v_cvt_pk_bf16_f32 v126, v126, v127
	v_cvt_pk_bf16_f32 v127, v128, v129
	v_or_b32_e32 v128, v123, v124
	s_waitcnt vmcnt(0)
	ds_write_b64 v128, v[126:127]
	v_mul_f32_e32 v126, v175, v175
	v_fmac_f32_e32 v126, v174, v174
	v_fmac_f32_e32 v126, v176, v176
	v_fmac_f32_e32 v125, v129, v129
	v_fmac_f32_e32 v126, v177, v177
	v_add_f32_e32 v125, v125, v126
	v_bitop3_b32 v126, v119, v120, 2 bitop3:0x36
	v_lshlrev_b32_e32 v126, 4, v126
	v_cvt_pk_bf16_f32 v128, v174, v175
	v_cvt_pk_bf16_f32 v129, v176, v177
	v_or_b32_e32 v127, v123, v126
	ds_write_b64 v127, v[128:129]
	v_mul_f32_e32 v127, v183, v183
	v_fmac_f32_e32 v127, v182, v182
	v_fmac_f32_e32 v127, v184, v184
	v_fmac_f32_e32 v127, v185, v185
	v_add_f32_e32 v127, v125, v127
	v_bitop3_b32 v125, v119, v120, 4 bitop3:0x36
	v_lshlrev_b32_e32 v125, 4, v125
	v_mfma_f32_16x16x32_bf16 v[108:111], v[130:133], v[158:161], v[108:111]
	v_cvt_pk_bf16_f32 v128, v182, v183
	v_cvt_pk_bf16_f32 v129, v184, v185
	v_and_b32_e32 v121, 64, v172
	v_mfma_f32_16x16x32_bf16 v[92:95], v[130:133], v[162:165], v[92:95]
	v_xor_b32_e32 v118, 16, v172
	v_add_u32_e32 v122, 64, v121
	v_cmp_lt_i32_e32 vcc, v118, v122
	v_mfma_f32_16x16x32_bf16 v[76:79], v[130:133], v[166:169], v[76:79]
	s_nop 0
	v_cndmask_b32_e32 v118, v172, v118, vcc
	v_lshlrev_b32_e32 v121, 2, v118
	v_mfma_f32_16x16x32_bf16 v[28:31], v[130:133], v[148:151], v[28:31]
	v_xor_b32_e32 v118, 32, v172
	v_cmp_lt_i32_e32 vcc, v118, v122
	v_mfma_f32_16x16x32_bf16 v[12:15], v[130:133], v[152:155], v[12:15]
	v_or_b32_e32 v130, v123, v125
	ds_write_b64 v130, v[128:129]
	v_mul_f32_e32 v128, v115, v115
	v_fmac_f32_e32 v128, v114, v114
	v_fmac_f32_e32 v128, v116, v116
	v_fmac_f32_e32 v128, v117, v117
	v_add_f32_e32 v127, v127, v128
	v_cvt_pk_bf16_f32 v128, v114, v115
	v_bitop3_b32 v114, v119, v120, 6 bitop3:0x36
	v_lshlrev_b32_e32 v114, 4, v114
	v_cvt_pk_bf16_f32 v129, v116, v117
	v_or_b32_e32 v115, v123, v114
	ds_write_b64 v115, v[128:129]
	ds_bpermute_b32 v115, v121, v127
	v_cndmask_b32_e32 v118, v172, v118, vcc
	v_lshlrev_b32_e32 v122, 2, v118
	v_mfma_f32_16x16x32_bf16 v[104:107], v[134:137], v[158:161], v[104:107]
	v_cmp_gt_u32_e32 vcc, 16, v112
	s_waitcnt lgkmcnt(0)
	v_add_f32_e32 v115, v127, v115
	ds_bpermute_b32 v116, v122, v115
	v_mfma_f32_16x16x32_bf16 v[88:91], v[134:137], v[162:165], v[88:91]
	v_or_b32_e32 v118, s8, v170
	v_mfma_f32_16x16x32_bf16 v[84:87], v[140:143], v[162:165], v[84:87]
	v_mfma_f32_16x16x32_bf16 v[80:83], v[144:147], v[162:165], v[80:83]
	v_mfma_f32_16x16x32_bf16 v[72:75], v[134:137], v[166:169], v[72:75]
	v_mfma_f32_16x16x32_bf16 v[68:71], v[140:143], v[166:169], v[68:71]
	v_mfma_f32_16x16x32_bf16 v[64:67], v[144:147], v[166:169], v[64:67]
	v_mfma_f32_16x16x32_bf16 v[24:27], v[134:137], v[148:151], v[24:27]
	v_mfma_f32_16x16x32_bf16 v[20:23], v[140:143], v[148:151], v[20:23]
	v_mfma_f32_16x16x32_bf16 v[16:19], v[144:147], v[148:151], v[16:19]
	v_mfma_f32_16x16x32_bf16 v[8:11], v[134:137], v[152:155], v[8:11]
	v_mfma_f32_16x16x32_bf16 v[4:7], v[140:143], v[152:155], v[4:7]
	v_mfma_f32_16x16x32_bf16 v[0:3], v[144:147], v[152:155], v[0:3]
	s_and_saveexec_b64 s[6:7], vcc
	s_cbranch_execz .LBB0_545
	v_ashrrev_i32_e32 v119, 31, v118
	s_waitcnt lgkmcnt(0)
	v_add_f32_e32 v115, v115, v116
	v_lshlrev_b64 v[116:117], 6, v[118:119]
	v_lshl_add_u64 v[116:117], s[44:45], 0, v[116:117]
	v_lshl_add_u64 v[116:117], s[10:11], 2, v[116:117]
	global_store_dword v[116:117], v115, off

.LBB0_804:
	s_and_b32 s4, s37, 7
	s_lshl_b32 s4, s4, s14
	s_ashr_i32 s5, s37, 3
	s_add_i32 s4, s4, s5
	s_abs_i32 s8, s4
	s_mul_hi_u32 s9, s8, s19
	s_mul_i32 s10, s9, s6
	s_sub_i32 s8, s8, s10
	s_ashr_i32 s5, s4, 31
	s_add_i32 s10, s9, 1
	s_sub_i32 s11, s8, s6
	s_cmp_ge_u32 s8, s6
	s_cselect_b32 s9, s10, s9
	s_cselect_b32 s8, s11, s8
	s_add_i32 s10, s9, 1
	s_cmp_ge_u32 s8, s6
	s_cselect_b32 s8, s10, s9
	s_xor_b32 s8, s8, s5
	s_sub_i32 s39, s8, s5
	s_mul_i32 s5, s39, s6
	v_mov_b32_e32 v158, v157
	s_sub_i32 s4, s4, s5
	s_lshl_b32 s41, s39, 8
	v_readfirstlane_b32 s5, v158
	s_ashr_i32 s8, s5, 1
	s_and_b32 s8, s8, 0xffffff80
	s_add_i32 s12, s8, s41
	s_and_b32 s8, s5, 0xc0
	s_lshl_b32 s5, s5, 8
	s_ashr_i32 s9, s4, 2
	s_lshl_b32 s42, s4, 8
	s_and_b32 s38, s5, 0xffffc000
	s_add_i32 s10, s9, 2
	s_and_b64 s[4:5], s[90:91], exec
	s_cselect_b32 s13, s9, s10
	s_and_b32 s4, s42, 0x300
	s_or_b32 s40, s8, s4
	v_and_b32_e32 v138, 63, v158
	v_and_b32_e32 v140, 15, v158
	v_bfe_u32 v139, v158, 4, 2
	s_cmp_eq_u32 s13, 1
	s_mov_b64 s[4:5], -1
	s_cbranch_scc1 .LBB0_872
	v_or_b32_e32 v0, s12, v140
	v_ashrrev_i32_e32 v1, 31, v0
	v_lshl_add_u64 v[0:1], v[0:1], 2, s[62:63]
	v_mov_b32_e32 v10, v157
	global_load_dword v159, v[0:1], off
	global_load_dword v147, v[0:1], off offset:64
	global_load_dword v146, v[0:1], off offset:128
	global_load_dword v145, v[0:1], off offset:192
	global_load_dword v144, v[0:1], off offset:256
	global_load_dword v143, v[0:1], off offset:320
	global_load_dword v142, v[0:1], off offset:384
	global_load_dword v141, v[0:1], off offset:448
	s_add_i32 s45, s42, 0xffffff00
	v_readfirstlane_b32 s43, v10
	s_ashr_i32 s44, s43, 6
	s_lshl_b32 s30, s44, 2
	s_cmp_lt_i32 s44, 4
	s_cselect_b64 s[4:5], -1, 0
	s_and_b32 s46, s43, 0xffffffc0
	s_and_b64 s[8:9], s[4:5], exec
	s_cselect_b32 s8, s41, s45
	s_add_i32 s8, s8, s46
	s_and_b64 s[4:5], s[4:5], exec
	s_cselect_b32 s10, s57, s18
	s_cselect_b32 s11, s56, s15
	s_ashr_i32 s9, s8, 31
	s_lshl_b64 s[4:5], s[8:9], 11
	s_add_u32 s8, s11, s4
	s_addc_u32 s9, s10, s5
	s_or_b32 s10, s30, 1
	s_cmp_lt_i32 s10, 16
	s_cselect_b64 s[4:5], -1, 0
	s_lshl_b32 s28, s10, 4
	s_and_b64 s[10:11], s[4:5], exec
	s_cselect_b32 s47, s41, s45
	s_add_i32 s10, s47, s28
	s_and_b64 s[4:5], s[4:5], exec
	s_cselect_b32 s48, s57, s18
	s_cselect_b32 s49, s56, s15
	s_ashr_i32 s11, s10, 31
	s_lshl_b64 s[4:5], s[10:11], 11
	s_add_u32 s10, s49, s4
	s_addc_u32 s11, s48, s5
	s_or_b32 s28, s30, 2
	s_cmp_lt_i32 s28, 16
	s_cselect_b64 s[4:5], -1, 0
	s_lshl_b32 s31, s28, 4
	s_and_b64 s[28:29], s[4:5], exec
	s_cselect_b32 s50, s41, s45
	s_add_i32 s28, s50, s31
	s_and_b64 s[4:5], s[4:5], exec
	s_cselect_b32 s51, s57, s18
	s_cselect_b32 s66, s56, s15
	s_ashr_i32 s29, s28, 31
	s_lshl_b64 s[4:5], s[28:29], 11
	s_add_u32 s28, s66, s4
	s_addc_u32 s29, s51, s5
	s_or_b32 s30, s30, 3
	s_cmp_lt_i32 s30, 16
	s_cselect_b64 s[4:5], -1, 0
	s_lshl_b32 s67, s30, 4
	s_and_b64 s[30:31], s[4:5], exec
	s_cselect_b32 s45, s41, s45
	s_add_i32 s30, s45, s67
	s_and_b64 s[4:5], s[4:5], exec
	v_lshrrev_b32_e32 v11, 4, v10
	s_cselect_b32 s67, s57, s18
	s_cselect_b32 s83, s56, s15
	s_ashr_i32 s31, s30, 31
	v_sub_u32_e32 v1, 0, v11
	s_lshl_b64 s[4:5], s[30:31], 11
	v_lshlrev_b32_e32 v0, 9, v10
	v_xor_b32_e32 v1, v10, v1
	s_add_u32 s30, s83, s4
	v_and_b32_e32 v0, 0x7800, v0
	v_lshlrev_b32_e32 v1, 4, v1
	s_addc_u32 s31, s67, s5
	s_lshl_b32 s4, s44, 12
	v_and_or_b32 v128, v1, 48, v0
	s_mov_b32 m0, s4
	v_lshl_add_u64 v[0:1], s[8:9], 0, v[128:129]
	global_load_lds_dwordx4 v128, s[8:9]
	s_or_b32 m0, s4, 0x400
	v_lshl_add_u64 v[2:3], s[10:11], 0, v[128:129]
	global_load_lds_dwordx4 v128, s[10:11]
	s_or_b32 m0, s4, 0x800
	v_lshl_add_u64 v[8:9], v[0:1], 0, 64
	global_load_lds_dwordx4 v128, s[28:29]
	s_or_b32 m0, s4, 0xc00
	v_lshl_add_u64 v[4:5], s[28:29], 0, v[128:129]
	global_load_lds_dwordx4 v128, s[30:31]
	s_add_i32 m0, s4, 0x8000
	v_lshl_add_u64 v[6:7], s[30:31], 0, v[128:129]
	global_load_lds_dwordx4 v[8:9], off
	v_lshl_add_u64 v[8:9], v[2:3], 0, 64
	s_add_i32 m0, s4, 0x8400
	v_lshl_add_u64 v[2:3], v[2:3], 0, s[88:89]
	global_load_lds_dwordx4 v[8:9], off
	v_lshl_add_u64 v[8:9], v[4:5], 0, 64
	s_add_i32 m0, s4, 0x8800
	s_lshr_b32 s5, s43, 1
	global_load_lds_dwordx4 v[8:9], off
	v_lshl_add_u64 v[8:9], v[6:7], 0, 64
	s_add_i32 m0, s4, 0x8c00
	s_add_i32 s8, s45, s46
	global_load_lds_dwordx4 v[8:9], off
	s_add_i32 m0, s4, 0x10000
	v_lshl_add_u64 v[8:9], v[0:1], 0, s[88:89]
	global_load_lds_dwordx4 v[8:9], off
	s_add_i32 m0, s4, 0x10400
	v_and_b32_e32 v12, 15, v10
	global_load_lds_dwordx4 v[2:3], off
	v_lshl_add_u64 v[2:3], v[4:5], 0, s[88:89]
	s_add_i32 m0, s4, 0x10800
	s_and_b32 s5, s5, 0x3ffff80
	global_load_lds_dwordx4 v[2:3], off
	v_lshl_add_u64 v[2:3], v[6:7], 0, s[88:89]
	s_add_i32 m0, s4, 0x10c00
	s_ashr_i32 s9, s8, 31
	global_load_lds_dwordx4 v[2:3], off
	v_lshrrev_b32_e32 v2, 2, v10
	v_sub_u32_e32 v2, 0, v2
	v_bitop3_b32 v2, v11, 3, v2 bitop3:0x48
	v_or_b32_e32 v3, s5, v12
	v_lshlrev_b32_e32 v2, 4, v2
	s_and_b32 s5, s43, 0xc0
	s_lshl_b64 s[8:9], s[8:9], 11
	v_lshl_or_b32 v160, v3, 6, v2
	v_or_b32_e32 v3, s5, v12
	s_add_u32 s8, s83, s8
	v_lshlrev_b32_e32 v3, 6, v3
	s_addc_u32 s9, s67, s9
	v_or3_b32 v161, v2, v3, s68
	v_lshl_add_u64 v[2:3], s[8:9], 0, v[128:129]
	s_add_i32 s8, s50, s46
	s_ashr_i32 s9, s8, 31
	s_lshl_b64 s[8:9], s[8:9], 11
	s_add_u32 s8, s66, s8
	s_addc_u32 s9, s51, s9
	v_lshl_add_u64 v[130:131], v[2:3], 0, s[92:93]
	v_lshl_add_u64 v[2:3], s[8:9], 0, v[128:129]
	s_add_i32 s8, s47, s46
	s_ashr_i32 s9, s8, 31
	s_lshl_b64 s[8:9], s[8:9], 11
	s_add_u32 s8, s49, s8
	s_addc_u32 s9, s48, s9
	v_lshl_add_u64 v[132:133], v[2:3], 0, s[94:95]
	v_lshl_add_u64 v[2:3], s[8:9], 0, v[128:129]
	v_lshl_add_u64 v[136:137], v[0:1], 0, s[78:79]
	v_mov_b32_e32 v0, 0
	v_lshl_add_u64 v[134:135], v[2:3], 0, s[96:97]
	s_mov_b32 s5, 0x18000
	v_mov_b32_e32 v1, v0
	v_mov_b32_e32 v2, v0
	v_mov_b32_e32 v3, v0
	v_mov_b32_e32 v4, v0
	v_mov_b32_e32 v5, v0
	v_mov_b32_e32 v6, v0
	v_mov_b32_e32 v7, v0
	v_mov_b32_e32 v8, v0
	v_mov_b32_e32 v9, v0
	v_mov_b32_e32 v10, v0
	v_mov_b32_e32 v11, v0
	v_mov_b32_e32 v12, v0
	v_mov_b32_e32 v13, v0
	v_mov_b32_e32 v14, v0
	v_mov_b32_e32 v15, v0
	s_waitcnt vmcnt(0)
	v_mov_b32_e32 v16, v0
	v_mov_b32_e32 v17, v0
	v_mov_b32_e32 v18, v0
	v_mov_b32_e32 v19, v0
	v_mov_b32_e32 v20, v0
	v_mov_b32_e32 v21, v0
	v_mov_b32_e32 v22, v0
	v_mov_b32_e32 v23, v0
	v_mov_b32_e32 v24, v0
	v_mov_b32_e32 v25, v0
	v_mov_b32_e32 v26, v0
	v_mov_b32_e32 v27, v0
	v_mov_b32_e32 v28, v0
	v_mov_b32_e32 v29, v0
	v_mov_b32_e32 v30, v0
	v_mov_b32_e32 v31, v0
	v_mov_b32_e32 v32, v0
	v_mov_b32_e32 v33, v0
	v_mov_b32_e32 v34, v0
	v_mov_b32_e32 v35, v0
	v_mov_b32_e32 v36, v0
	v_mov_b32_e32 v37, v0
	v_mov_b32_e32 v38, v0
	v_mov_b32_e32 v39, v0
	v_mov_b32_e32 v40, v0
	v_mov_b32_e32 v41, v0
	v_mov_b32_e32 v42, v0
	v_mov_b32_e32 v43, v0
	v_mov_b32_e32 v44, v0
	v_mov_b32_e32 v45, v0
	v_mov_b32_e32 v46, v0
	v_mov_b32_e32 v47, v0
	v_mov_b32_e32 v48, v0
	v_mov_b32_e32 v49, v0
	v_mov_b32_e32 v50, v0
	v_mov_b32_e32 v51, v0
	v_mov_b32_e32 v52, v0
	v_mov_b32_e32 v53, v0
	v_mov_b32_e32 v54, v0
	v_mov_b32_e32 v55, v0
	v_mov_b32_e32 v56, v0
	v_mov_b32_e32 v57, v0
	v_mov_b32_e32 v58, v0
	v_mov_b32_e32 v59, v0
	v_mov_b32_e32 v60, v0
	v_mov_b32_e32 v61, v0
	v_mov_b32_e32 v62, v0
	v_mov_b32_e32 v63, v0
	v_mov_b32_e32 v64, v0
	v_mov_b32_e32 v65, v0
	v_mov_b32_e32 v66, v0
	v_mov_b32_e32 v67, v0
	v_mov_b32_e32 v68, v0
	v_mov_b32_e32 v69, v0
	v_mov_b32_e32 v70, v0
	v_mov_b32_e32 v71, v0
	v_mov_b32_e32 v72, v0
	v_mov_b32_e32 v73, v0
	v_mov_b32_e32 v74, v0
	v_mov_b32_e32 v75, v0
	v_mov_b32_e32 v76, v0
	v_mov_b32_e32 v77, v0
	v_mov_b32_e32 v78, v0
	v_mov_b32_e32 v79, v0
	v_mov_b32_e32 v80, v0
	v_mov_b32_e32 v81, v0
	v_mov_b32_e32 v82, v0
	v_mov_b32_e32 v83, v0
	v_mov_b32_e32 v84, v0
	v_mov_b32_e32 v85, v0
	v_mov_b32_e32 v86, v0
	v_mov_b32_e32 v87, v0
	v_mov_b32_e32 v88, v0
	v_mov_b32_e32 v89, v0
	v_mov_b32_e32 v90, v0
	v_mov_b32_e32 v91, v0
	v_mov_b32_e32 v92, v0
	v_mov_b32_e32 v93, v0
	v_mov_b32_e32 v94, v0
	v_mov_b32_e32 v95, v0
	v_mov_b32_e32 v96, v0
	v_mov_b32_e32 v97, v0
	v_mov_b32_e32 v98, v0
	v_mov_b32_e32 v99, v0
	v_mov_b32_e32 v100, v0
	v_mov_b32_e32 v101, v0
	v_mov_b32_e32 v102, v0
	v_mov_b32_e32 v103, v0
	v_mov_b32_e32 v104, v0
	v_mov_b32_e32 v105, v0
	v_mov_b32_e32 v106, v0
	v_mov_b32_e32 v107, v0
	v_mov_b32_e32 v108, v0
	v_mov_b32_e32 v109, v0
	v_mov_b32_e32 v110, v0
	v_mov_b32_e32 v111, v0
	v_mov_b32_e32 v112, v0
	v_mov_b32_e32 v113, v0
	v_mov_b32_e32 v114, v0
	v_mov_b32_e32 v115, v0
	v_mov_b32_e32 v116, v0
	v_mov_b32_e32 v117, v0
	v_mov_b32_e32 v118, v0
	v_mov_b32_e32 v119, v0
	v_mov_b32_e32 v120, v0
	v_mov_b32_e32 v121, v0
	v_mov_b32_e32 v122, v0
	v_mov_b32_e32 v123, v0
	v_mov_b32_e32 v124, v0
	v_mov_b32_e32 v125, v0
	v_mov_b32_e32 v126, v0
	v_mov_b32_e32 v127, v0
	s_add_i32 s8, s5, 0xfffe8000
	s_and_b32 s9, s5, 0x18000
	s_waitcnt vmcnt(8)
	s_barrier
	s_and_b32 s8, s8, 0x18000
	s_add_i32 s9, s4, s9
	v_add_u32_e32 v128, s8, v160
	v_or_b32_e32 v170, s8, v161
	s_add_i32 s11, s9, 0x400
	s_add_i32 s10, s9, 0x800
	s_add_i32 s8, s9, 0xc00
	s_add_i32 s5, s5, 0x8000
	s_cmp_eq_u32 s5, 0x100000
	ds_read_b128 v[182:185], v128
	ds_read_b128 v[162:165], v170
	ds_read_b128 v[166:169], v170 offset:1024
	ds_read_b128 v[174:177], v170 offset:2048
	ds_read_b128 v[178:181], v170 offset:3072
	ds_read_b128 v[186:189], v128 offset:1024
	ds_read_b128 v[190:193], v128 offset:2048
	ds_read_b128 v[194:197], v128 offset:3072
	ds_read_b128 v[232:235], v128 offset:4096
	ds_read_b128 v[236:239], v128 offset:5120
	ds_read_b128 v[240:243], v128 offset:6144
	ds_read_b128 v[244:247], v128 offset:7168
	s_mov_b32 m0, s9
	s_nop 0
	global_load_lds_dwordx4 v[136:137], off
	v_lshl_add_u64 v[136:137], v[136:137], 0, 64
	s_mov_b32 m0, s11
	s_nop 0
	global_load_lds_dwordx4 v[134:135], off
	v_lshl_add_u64 v[134:135], v[134:135], 0, 64
	s_mov_b32 m0, s10
	s_nop 0
	global_load_lds_dwordx4 v[132:133], off
	v_lshl_add_u64 v[132:133], v[132:133], 0, 64
	s_mov_b32 m0, s8
	s_nop 0
	global_load_lds_dwordx4 v[130:131], off
	v_lshl_add_u64 v[130:131], v[130:131], 0, 64
	s_waitcnt lgkmcnt(4)
	v_mfma_f32_16x16x32_bf16 v[124:127], v[162:165], v[182:185], v[124:127]
	v_mfma_f32_16x16x32_bf16 v[120:123], v[166:169], v[182:185], v[120:123]
	v_mfma_f32_16x16x32_bf16 v[116:119], v[174:177], v[182:185], v[116:119]
	v_mfma_f32_16x16x32_bf16 v[112:115], v[178:181], v[182:185], v[112:115]
	v_mfma_f32_16x16x32_bf16 v[108:111], v[162:165], v[186:189], v[108:111]
	v_mfma_f32_16x16x32_bf16 v[104:107], v[166:169], v[186:189], v[104:107]
	v_mfma_f32_16x16x32_bf16 v[100:103], v[174:177], v[186:189], v[100:103]
	v_mfma_f32_16x16x32_bf16 v[96:99], v[178:181], v[186:189], v[96:99]
	v_mfma_f32_16x16x32_bf16 v[92:95], v[162:165], v[190:193], v[92:95]
	v_mfma_f32_16x16x32_bf16 v[88:91], v[166:169], v[190:193], v[88:91]
	v_mfma_f32_16x16x32_bf16 v[84:87], v[174:177], v[190:193], v[84:87]
	v_mfma_f32_16x16x32_bf16 v[80:83], v[178:181], v[190:193], v[80:83]
	v_mfma_f32_16x16x32_bf16 v[76:79], v[162:165], v[194:197], v[76:79]
	v_mfma_f32_16x16x32_bf16 v[72:75], v[166:169], v[194:197], v[72:75]
	v_mfma_f32_16x16x32_bf16 v[68:71], v[174:177], v[194:197], v[68:71]
	v_mfma_f32_16x16x32_bf16 v[64:67], v[178:181], v[194:197], v[64:67]
.Lgsk2_loop:
	s_add_i32 s8, s5, 0xfffe8000
	s_and_b32 s9, s5, 0x18000
	s_waitcnt vmcnt(8) lgkmcnt(0)
	s_barrier
	s_and_b32 s8, s8, 0x18000
	s_add_i32 s9, s4, s9
	v_add_u32_e32 v128, s8, v160
	v_or_b32_e32 v170, s8, v161
	s_add_i32 s11, s9, 0x400
	s_add_i32 s10, s9, 0x800
	s_add_i32 s8, s9, 0xc00
	s_add_i32 s5, s5, 0x8000
	s_cmp_eq_u32 s5, 0x100000
	ds_read_b128 v[182:185], v128
	ds_read_b128 v[186:189], v128 offset:1024
	ds_read_b128 v[190:193], v128 offset:2048
	ds_read_b128 v[194:197], v128 offset:3072
	v_mfma_f32_16x16x32_bf16 v[60:63], v[162:165], v[232:235], v[60:63]
	v_mfma_f32_16x16x32_bf16 v[44:47], v[162:165], v[236:239], v[44:47]
	v_mfma_f32_16x16x32_bf16 v[28:31], v[162:165], v[240:243], v[28:31]
	s_mov_b32 m0, s9
	v_mfma_f32_16x16x32_bf16 v[12:15], v[162:165], v[244:247], v[12:15]
	global_load_lds_dwordx4 v[136:137], off
	v_lshl_add_u64 v[136:137], v[136:137], 0, 64
	v_mfma_f32_16x16x32_bf16 v[56:59], v[166:169], v[232:235], v[56:59]
	ds_read_b128 v[162:165], v170
	v_mfma_f32_16x16x32_bf16 v[40:43], v[166:169], v[236:239], v[40:43]
	v_mfma_f32_16x16x32_bf16 v[24:27], v[166:169], v[240:243], v[24:27]
	s_mov_b32 m0, s11
	v_mfma_f32_16x16x32_bf16 v[8:11], v[166:169], v[244:247], v[8:11]
	global_load_lds_dwordx4 v[134:135], off
	v_lshl_add_u64 v[134:135], v[134:135], 0, 64
	v_mfma_f32_16x16x32_bf16 v[52:55], v[174:177], v[232:235], v[52:55]
	ds_read_b128 v[166:169], v170 offset:1024
	v_mfma_f32_16x16x32_bf16 v[36:39], v[174:177], v[236:239], v[36:39]
	v_mfma_f32_16x16x32_bf16 v[20:23], v[174:177], v[240:243], v[20:23]
	s_mov_b32 m0, s10
	v_mfma_f32_16x16x32_bf16 v[4:7], v[174:177], v[244:247], v[4:7]
	global_load_lds_dwordx4 v[132:133], off
	v_lshl_add_u64 v[132:133], v[132:133], 0, 64
	v_mfma_f32_16x16x32_bf16 v[48:51], v[178:181], v[232:235], v[48:51]
	ds_read_b128 v[174:177], v170 offset:2048
	v_mfma_f32_16x16x32_bf16 v[32:35], v[178:181], v[236:239], v[32:35]
	v_mfma_f32_16x16x32_bf16 v[16:19], v[178:181], v[240:243], v[16:19]
	s_mov_b32 m0, s8
	v_mfma_f32_16x16x32_bf16 v[0:3], v[178:181], v[244:247], v[0:3]
	global_load_lds_dwordx4 v[130:131], off
	v_lshl_add_u64 v[130:131], v[130:131], 0, 64
	s_waitcnt lgkmcnt(2)
	v_mfma_f32_16x16x32_bf16 v[124:127], v[162:165], v[182:185], v[124:127]
	ds_read_b128 v[178:181], v170 offset:3072
	v_mfma_f32_16x16x32_bf16 v[108:111], v[162:165], v[186:189], v[108:111]
	ds_read_b128 v[232:235], v128 offset:4096
	ds_read_b128 v[236:239], v128 offset:5120
	v_mfma_f32_16x16x32_bf16 v[92:95], v[162:165], v[190:193], v[92:95]
	ds_read_b128 v[240:243], v128 offset:6144
	ds_read_b128 v[244:247], v128 offset:7168
	v_mfma_f32_16x16x32_bf16 v[76:79], v[162:165], v[194:197], v[76:79]
	s_waitcnt lgkmcnt(6)
	v_mfma_f32_16x16x32_bf16 v[120:123], v[166:169], v[182:185], v[120:123]
	v_mfma_f32_16x16x32_bf16 v[104:107], v[166:169], v[186:189], v[104:107]
	v_mfma_f32_16x16x32_bf16 v[88:91], v[166:169], v[190:193], v[88:91]
	v_mfma_f32_16x16x32_bf16 v[72:75], v[166:169], v[194:197], v[72:75]
	s_waitcnt lgkmcnt(5)
	v_mfma_f32_16x16x32_bf16 v[116:119], v[174:177], v[182:185], v[116:119]
	v_mfma_f32_16x16x32_bf16 v[100:103], v[174:177], v[186:189], v[100:103]
	v_mfma_f32_16x16x32_bf16 v[84:87], v[174:177], v[190:193], v[84:87]
	v_mfma_f32_16x16x32_bf16 v[68:71], v[174:177], v[194:197], v[68:71]
	s_waitcnt lgkmcnt(4)
	v_mfma_f32_16x16x32_bf16 v[112:115], v[178:181], v[182:185], v[112:115]
	v_mfma_f32_16x16x32_bf16 v[96:99], v[178:181], v[186:189], v[96:99]
	v_mfma_f32_16x16x32_bf16 v[80:83], v[178:181], v[190:193], v[80:83]
	v_mfma_f32_16x16x32_bf16 v[64:67], v[178:181], v[194:197], v[64:67]
	s_cbranch_scc0 .Lgsk2_loop
	s_waitcnt lgkmcnt(0)
	v_mfma_f32_16x16x32_bf16 v[60:63], v[162:165], v[232:235], v[60:63]
	v_mfma_f32_16x16x32_bf16 v[44:47], v[162:165], v[236:239], v[44:47]
	v_mfma_f32_16x16x32_bf16 v[28:31], v[162:165], v[240:243], v[28:31]
	v_mfma_f32_16x16x32_bf16 v[12:15], v[162:165], v[244:247], v[12:15]
	v_mfma_f32_16x16x32_bf16 v[56:59], v[166:169], v[232:235], v[56:59]
	v_mfma_f32_16x16x32_bf16 v[40:43], v[166:169], v[236:239], v[40:43]
	v_mfma_f32_16x16x32_bf16 v[24:27], v[166:169], v[240:243], v[24:27]
	v_mfma_f32_16x16x32_bf16 v[8:11], v[166:169], v[244:247], v[8:11]
	v_mfma_f32_16x16x32_bf16 v[52:55], v[174:177], v[232:235], v[52:55]
	v_mfma_f32_16x16x32_bf16 v[36:39], v[174:177], v[236:239], v[36:39]
	v_mfma_f32_16x16x32_bf16 v[20:23], v[174:177], v[240:243], v[20:23]
	v_mfma_f32_16x16x32_bf16 v[4:7], v[174:177], v[244:247], v[4:7]
	v_mfma_f32_16x16x32_bf16 v[48:51], v[178:181], v[232:235], v[48:51]
	v_mfma_f32_16x16x32_bf16 v[32:35], v[178:181], v[236:239], v[32:35]
	v_mfma_f32_16x16x32_bf16 v[16:19], v[178:181], v[240:243], v[16:19]
	v_mfma_f32_16x16x32_bf16 v[0:3], v[178:181], v[244:247], v[0:3]
	s_waitcnt vmcnt(8)
	s_barrier
	v_add_u32_e32 v128, 0x8000, v160
	v_or_b32_e32 v170, 0x8000, v161
	ds_read_b128 v[130:133], v170
	ds_read_b128 v[134:137], v170 offset:1024
	ds_read_b128 v[162:165], v170 offset:2048
	ds_read_b128 v[166:169], v170 offset:3072
	ds_read_b128 v[174:177], v128
	ds_read_b128 v[178:181], v128 offset:1024
	ds_read_b128 v[182:185], v128 offset:2048
	ds_read_b128 v[186:189], v128 offset:3072
	v_or_b32_e32 v170, 0x10000, v161
	s_waitcnt lgkmcnt(0)
	v_or_b32_e32 v173, 0x18000, v161
	v_mfma_f32_16x16x32_bf16 v[124:127], v[130:133], v[174:177], v[124:127]
	s_cmp_eq_u32 s13, 2
	s_cselect_b64 s[8:9], -1, 0
	s_cmp_eq_u32 s13, 3
	v_mfma_f32_16x16x32_bf16 v[120:123], v[134:137], v[174:177], v[120:123]
	s_cselect_b64 s[4:5], -1, 0
	s_and_b64 vcc, exec, s[4:5]
	v_mfma_f32_16x16x32_bf16 v[116:119], v[162:165], v[174:177], v[116:119]
	v_mfma_f32_16x16x32_bf16 v[112:115], v[166:169], v[174:177], v[112:115]
	v_mfma_f32_16x16x32_bf16 v[108:111], v[130:133], v[178:181], v[108:111]
	v_mfma_f32_16x16x32_bf16 v[104:107], v[134:137], v[178:181], v[104:107]
	v_mfma_f32_16x16x32_bf16 v[100:103], v[162:165], v[178:181], v[100:103]
	v_mfma_f32_16x16x32_bf16 v[96:99], v[166:169], v[178:181], v[96:99]
	v_mfma_f32_16x16x32_bf16 v[92:95], v[130:133], v[182:185], v[92:95]
	v_mfma_f32_16x16x32_bf16 v[88:91], v[134:137], v[182:185], v[88:91]
	v_mfma_f32_16x16x32_bf16 v[84:87], v[162:165], v[182:185], v[84:87]
	v_mfma_f32_16x16x32_bf16 v[80:83], v[166:169], v[182:185], v[80:83]
	v_mfma_f32_16x16x32_bf16 v[76:79], v[130:133], v[186:189], v[76:79]
	v_mfma_f32_16x16x32_bf16 v[72:75], v[134:137], v[186:189], v[72:75]
	v_mfma_f32_16x16x32_bf16 v[68:71], v[162:165], v[186:189], v[68:71]
	v_mfma_f32_16x16x32_bf16 v[64:67], v[166:169], v[186:189], v[64:67]
	ds_read_b128 v[174:177], v128 offset:4096
	ds_read_b128 v[178:181], v128 offset:5120
	ds_read_b128 v[182:185], v128 offset:6144
	ds_read_b128 v[186:189], v128 offset:7168
	s_waitcnt lgkmcnt(0)
	s_waitcnt vmcnt(4)
	s_barrier
	v_mfma_f32_16x16x32_bf16 v[60:63], v[130:133], v[174:177], v[60:63]
	v_add_u32_e32 v128, 0x10000, v160
	v_mfma_f32_16x16x32_bf16 v[56:59], v[134:137], v[174:177], v[56:59]
	v_mfma_f32_16x16x32_bf16 v[52:55], v[162:165], v[174:177], v[52:55]
	v_mfma_f32_16x16x32_bf16 v[48:51], v[166:169], v[174:177], v[48:51]
	v_mfma_f32_16x16x32_bf16 v[44:47], v[130:133], v[178:181], v[44:47]
	v_mfma_f32_16x16x32_bf16 v[40:43], v[134:137], v[178:181], v[40:43]
	v_mfma_f32_16x16x32_bf16 v[36:39], v[162:165], v[178:181], v[36:39]
	v_mfma_f32_16x16x32_bf16 v[32:35], v[166:169], v[178:181], v[32:35]
	v_mfma_f32_16x16x32_bf16 v[28:31], v[130:133], v[182:185], v[28:31]
	v_mfma_f32_16x16x32_bf16 v[24:27], v[134:137], v[182:185], v[24:27]
	v_mfma_f32_16x16x32_bf16 v[20:23], v[162:165], v[182:185], v[20:23]
	v_mfma_f32_16x16x32_bf16 v[16:19], v[166:169], v[182:185], v[16:19]
	v_mfma_f32_16x16x32_bf16 v[12:15], v[130:133], v[186:189], v[12:15]
	v_mfma_f32_16x16x32_bf16 v[8:11], v[134:137], v[186:189], v[8:11]
	v_mfma_f32_16x16x32_bf16 v[4:7], v[162:165], v[186:189], v[4:7]
	v_mfma_f32_16x16x32_bf16 v[0:3], v[166:169], v[186:189], v[0:3]
	ds_read_b128 v[130:133], v170
	ds_read_b128 v[134:137], v170 offset:1024
	ds_read_b128 v[162:165], v170 offset:2048
	ds_read_b128 v[166:169], v170 offset:3072
	ds_read_b128 v[174:177], v128
	ds_read_b128 v[178:181], v128 offset:1024
	ds_read_b128 v[182:185], v128 offset:2048
	ds_read_b128 v[186:189], v128 offset:3072
	s_nop 0
	s_waitcnt lgkmcnt(0)
	s_nop 0
	v_mfma_f32_16x16x32_bf16 v[124:127], v[130:133], v[174:177], v[124:127]
	v_mfma_f32_16x16x32_bf16 v[120:123], v[134:137], v[174:177], v[120:123]
	v_mfma_f32_16x16x32_bf16 v[116:119], v[162:165], v[174:177], v[116:119]
	v_mfma_f32_16x16x32_bf16 v[112:115], v[166:169], v[174:177], v[112:115]
	v_mfma_f32_16x16x32_bf16 v[108:111], v[130:133], v[178:181], v[108:111]
	v_mfma_f32_16x16x32_bf16 v[104:107], v[134:137], v[178:181], v[104:107]
	v_mfma_f32_16x16x32_bf16 v[100:103], v[162:165], v[178:181], v[100:103]
	v_mfma_f32_16x16x32_bf16 v[96:99], v[166:169], v[178:181], v[96:99]
	v_mfma_f32_16x16x32_bf16 v[92:95], v[130:133], v[182:185], v[92:95]
	v_mfma_f32_16x16x32_bf16 v[88:91], v[134:137], v[182:185], v[88:91]
	v_mfma_f32_16x16x32_bf16 v[84:87], v[162:165], v[182:185], v[84:87]
	v_mfma_f32_16x16x32_bf16 v[80:83], v[166:169], v[182:185], v[80:83]
	v_mfma_f32_16x16x32_bf16 v[76:79], v[130:133], v[186:189], v[76:79]
	v_mfma_f32_16x16x32_bf16 v[72:75], v[134:137], v[186:189], v[72:75]
	v_mfma_f32_16x16x32_bf16 v[68:71], v[162:165], v[186:189], v[68:71]
	v_mfma_f32_16x16x32_bf16 v[64:67], v[166:169], v[186:189], v[64:67]
	ds_read_b128 v[174:177], v128 offset:4096
	ds_read_b128 v[178:181], v128 offset:5120
	ds_read_b128 v[182:185], v128 offset:6144
	ds_read_b128 v[186:189], v128 offset:7168
	s_waitcnt lgkmcnt(0)
	s_waitcnt vmcnt(0)
	s_barrier
	v_mfma_f32_16x16x32_bf16 v[60:63], v[130:133], v[174:177], v[60:63]
	v_add_u32_e32 v128, 0x18000, v160
	v_mfma_f32_16x16x32_bf16 v[56:59], v[134:137], v[174:177], v[56:59]
	v_mfma_f32_16x16x32_bf16 v[52:55], v[162:165], v[174:177], v[52:55]
	v_mfma_f32_16x16x32_bf16 v[48:51], v[166:169], v[174:177], v[48:51]
	v_mfma_f32_16x16x32_bf16 v[44:47], v[130:133], v[178:181], v[44:47]
	v_mfma_f32_16x16x32_bf16 v[40:43], v[134:137], v[178:181], v[40:43]
	v_mfma_f32_16x16x32_bf16 v[36:39], v[162:165], v[178:181], v[36:39]
	v_mfma_f32_16x16x32_bf16 v[32:35], v[166:169], v[178:181], v[32:35]
	v_mfma_f32_16x16x32_bf16 v[28:31], v[130:133], v[182:185], v[28:31]
	v_mfma_f32_16x16x32_bf16 v[24:27], v[134:137], v[182:185], v[24:27]
	v_mfma_f32_16x16x32_bf16 v[20:23], v[162:165], v[182:185], v[20:23]
	v_mfma_f32_16x16x32_bf16 v[16:19], v[166:169], v[182:185], v[16:19]
	v_mfma_f32_16x16x32_bf16 v[12:15], v[130:133], v[186:189], v[12:15]
	v_mfma_f32_16x16x32_bf16 v[8:11], v[134:137], v[186:189], v[8:11]
	v_mfma_f32_16x16x32_bf16 v[4:7], v[162:165], v[186:189], v[4:7]
	v_mfma_f32_16x16x32_bf16 v[0:3], v[166:169], v[186:189], v[0:3]
	ds_read_b128 v[130:133], v173
	ds_read_b128 v[134:137], v173 offset:1024
	ds_read_b128 v[160:163], v173 offset:2048
	ds_read_b128 v[164:167], v173 offset:3072
	ds_read_b128 v[168:171], v128
	ds_read_b128 v[174:177], v128 offset:1024
	ds_read_b128 v[178:181], v128 offset:2048
	ds_read_b128 v[182:185], v128 offset:3072
	s_nop 0
	s_waitcnt lgkmcnt(0)
	s_nop 0
	v_mfma_f32_16x16x32_bf16 v[186:189], v[130:133], v[168:171], v[124:127]
	v_mfma_f32_16x16x32_bf16 v[120:123], v[134:137], v[168:171], v[120:123]
	v_mfma_f32_16x16x32_bf16 v[116:119], v[160:163], v[168:171], v[116:119]
	v_mfma_f32_16x16x32_bf16 v[112:115], v[164:167], v[168:171], v[112:115]
	v_mfma_f32_16x16x32_bf16 v[108:111], v[130:133], v[174:177], v[108:111]
	v_mfma_f32_16x16x32_bf16 v[104:107], v[134:137], v[174:177], v[104:107]
	v_mfma_f32_16x16x32_bf16 v[100:103], v[160:163], v[174:177], v[100:103]
	v_mfma_f32_16x16x32_bf16 v[96:99], v[164:167], v[174:177], v[96:99]
	v_mfma_f32_16x16x32_bf16 v[92:95], v[130:133], v[178:181], v[92:95]
	v_mfma_f32_16x16x32_bf16 v[88:91], v[134:137], v[178:181], v[88:91]
	v_mfma_f32_16x16x32_bf16 v[84:87], v[160:163], v[178:181], v[84:87]
	v_mfma_f32_16x16x32_bf16 v[80:83], v[164:167], v[178:181], v[80:83]
	ds_read_b128 v[124:127], v128 offset:4096
	ds_read_b128 v[168:171], v128 offset:5120
	ds_read_b128 v[174:177], v128 offset:6144
	ds_read_b128 v[178:181], v128 offset:7168
	s_waitcnt lgkmcnt(0)
	s_barrier
	v_mfma_f32_16x16x32_bf16 v[76:79], v[130:133], v[182:185], v[76:79]
	v_mfma_f32_16x16x32_bf16 v[72:75], v[134:137], v[182:185], v[72:75]
	v_mfma_f32_16x16x32_bf16 v[68:71], v[160:163], v[182:185], v[68:71]
	v_mfma_f32_16x16x32_bf16 v[64:67], v[164:167], v[182:185], v[64:67]
	v_mfma_f32_16x16x32_bf16 v[60:63], v[130:133], v[124:127], v[60:63]
	v_mfma_f32_16x16x32_bf16 v[56:59], v[134:137], v[124:127], v[56:59]
	v_mfma_f32_16x16x32_bf16 v[52:55], v[160:163], v[124:127], v[52:55]
	v_mfma_f32_16x16x32_bf16 v[48:51], v[164:167], v[124:127], v[48:51]
	v_mfma_f32_16x16x32_bf16 v[44:47], v[130:133], v[168:171], v[44:47]
	v_mfma_f32_16x16x32_bf16 v[40:43], v[134:137], v[168:171], v[40:43]
	v_mfma_f32_16x16x32_bf16 v[36:39], v[160:163], v[168:171], v[36:39]
	v_mfma_f32_16x16x32_bf16 v[32:35], v[164:167], v[168:171], v[32:35]
	v_mfma_f32_16x16x32_bf16 v[28:31], v[130:133], v[174:177], v[28:31]
	v_mfma_f32_16x16x32_bf16 v[24:27], v[134:137], v[174:177], v[24:27]
	v_mfma_f32_16x16x32_bf16 v[20:23], v[160:163], v[174:177], v[20:23]
	v_mfma_f32_16x16x32_bf16 v[16:19], v[164:167], v[174:177], v[16:19]
	v_mfma_f32_16x16x32_bf16 v[12:15], v[130:133], v[178:181], v[12:15]
	v_cndmask_b32_e64 v132, 1.0, v156, s[8:9]
	v_mul_f32_e32 v124, v132, v159
	v_pk_mul_f32 v[126:127], v[124:125], v[188:189] op_sel_hi:[0,1]
	v_mfma_f32_16x16x32_bf16 v[8:11], v[134:137], v[178:181], v[8:11]
	v_mul_f32_e64 v130, v124, v186
	v_mul_f32_e64 v131, v124, v187
	v_mfma_f32_16x16x32_bf16 v[4:7], v[160:163], v[178:181], v[4:7]
	v_mfma_f32_16x16x32_bf16 v[0:3], v[164:167], v[178:181], v[0:3]
	s_cbranch_vccz .LBB0_809
	v_mul_f32_e32 v125, 0xbfb8aa3b, v130
	v_exp_f32_e32 v125, v125
	v_mul_f32_e32 v133, 0xbfb8aa3b, v126
	v_mul_f32_e32 v128, 0xbfb8aa3b, v131
	v_exp_f32_e32 v128, v128
	v_add_f32_e32 v125, 1.0, v125
	v_rcp_f32_e32 v134, v125
	v_exp_f32_e32 v125, v133
	v_mul_f32_e32 v133, 0xbfb8aa3b, v127
	v_exp_f32_e32 v133, v133
	v_add_f32_e32 v128, 1.0, v128
	v_add_f32_e32 v125, 1.0, v125
	v_rcp_f32_e32 v136, v125
	v_add_f32_e32 v125, 1.0, v133
	v_rcp_f32_e32 v137, v125
	v_rcp_f32_e32 v135, v128
	v_pk_mul_f32 v[126:127], v[126:127], v[136:137]
	v_pk_mul_f32 v[130:131], v[130:131], v[134:135]

.LBB0_872:
	s_and_b64 vcc, exec, s[4:5]
	s_cbranch_vccz .LBB0_803
	v_mov_b32_e32 v10, v157
	s_addk_i32 s42, 0xff00
	v_readfirstlane_b32 s13, v10
	s_ashr_i32 s43, s13, 6
	s_lshl_b32 s30, s43, 2
	s_cmp_lt_i32 s43, 4
	s_cselect_b64 s[4:5], -1, 0
	s_and_b32 s44, s13, 0xffffffc0
	s_and_b64 s[8:9], s[4:5], exec
	s_cselect_b32 s8, s41, s42
	s_add_i32 s8, s8, s44
	s_and_b64 s[4:5], s[4:5], exec
	s_cselect_b32 s10, s57, s18
	s_cselect_b32 s11, s56, s15
	s_ashr_i32 s9, s8, 31
	s_lshl_b64 s[4:5], s[8:9], 11
	s_add_u32 s8, s11, s4
	s_addc_u32 s9, s10, s5
	s_or_b32 s10, s30, 1
	s_cmp_lt_i32 s10, 16
	s_cselect_b64 s[4:5], -1, 0
	s_lshl_b32 s28, s10, 4
	s_and_b64 s[10:11], s[4:5], exec
	s_cselect_b32 s45, s41, s42
	s_add_i32 s10, s45, s28
	s_and_b64 s[4:5], s[4:5], exec
	s_cselect_b32 s46, s57, s18
	s_cselect_b32 s47, s56, s15
	s_ashr_i32 s11, s10, 31
	s_lshl_b64 s[4:5], s[10:11], 11
	s_add_u32 s10, s47, s4
	s_addc_u32 s11, s46, s5
	s_or_b32 s28, s30, 2
	s_cmp_lt_i32 s28, 16
	s_cselect_b64 s[4:5], -1, 0
	s_lshl_b32 s31, s28, 4
	s_and_b64 s[28:29], s[4:5], exec
	s_cselect_b32 s48, s41, s42
	s_add_i32 s28, s48, s31
	s_and_b64 s[4:5], s[4:5], exec
	s_cselect_b32 s49, s57, s18
	s_cselect_b32 s50, s56, s15
	s_ashr_i32 s29, s28, 31
	s_lshl_b64 s[4:5], s[28:29], 11
	s_add_u32 s28, s50, s4
	s_addc_u32 s29, s49, s5
	s_or_b32 s30, s30, 3
	s_cmp_lt_i32 s30, 16
	s_cselect_b64 s[4:5], -1, 0
	s_lshl_b32 s51, s30, 4
	s_and_b64 s[30:31], s[4:5], exec
	s_cselect_b32 s41, s41, s42
	s_add_i32 s30, s41, s51
	s_and_b64 s[4:5], s[4:5], exec
	v_lshrrev_b32_e32 v11, 4, v10
	s_cselect_b32 s42, s57, s18
	s_cselect_b32 s51, s56, s15
	s_ashr_i32 s31, s30, 31
	v_sub_u32_e32 v1, 0, v11
	s_lshl_b64 s[4:5], s[30:31], 11
	v_lshlrev_b32_e32 v0, 9, v10
	v_xor_b32_e32 v1, v10, v1
	s_add_u32 s30, s51, s4
	v_and_b32_e32 v0, 0x7800, v0
	v_lshlrev_b32_e32 v1, 4, v1
	s_addc_u32 s31, s42, s5
	s_lshl_b32 s4, s43, 12
	v_and_or_b32 v128, v1, 48, v0
	s_mov_b32 m0, s4
	v_lshl_add_u64 v[0:1], s[8:9], 0, v[128:129]
	global_load_lds_dwordx4 v128, s[8:9]
	s_or_b32 m0, s4, 0x400
	v_lshl_add_u64 v[2:3], s[10:11], 0, v[128:129]
	global_load_lds_dwordx4 v128, s[10:11]
	s_or_b32 m0, s4, 0x800
	v_lshl_add_u64 v[8:9], v[0:1], 0, 64
	global_load_lds_dwordx4 v128, s[28:29]
	s_or_b32 m0, s4, 0xc00
	v_lshl_add_u64 v[4:5], s[28:29], 0, v[128:129]
	global_load_lds_dwordx4 v128, s[30:31]
	s_add_i32 m0, s4, 0x8000
	v_lshl_add_u64 v[6:7], s[30:31], 0, v[128:129]
	global_load_lds_dwordx4 v[8:9], off
	v_lshl_add_u64 v[8:9], v[2:3], 0, 64
	s_add_i32 m0, s4, 0x8400
	v_lshl_add_u64 v[2:3], v[2:3], 0, s[88:89]
	global_load_lds_dwordx4 v[8:9], off
	v_lshl_add_u64 v[8:9], v[4:5], 0, 64
	s_add_i32 m0, s4, 0x8800
	s_lshr_b32 s5, s13, 1
	global_load_lds_dwordx4 v[8:9], off
	v_lshl_add_u64 v[8:9], v[6:7], 0, 64
	s_add_i32 m0, s4, 0x8c00
	s_add_i32 s8, s41, s44
	global_load_lds_dwordx4 v[8:9], off
	s_add_i32 m0, s4, 0x10000
	v_lshl_add_u64 v[8:9], v[0:1], 0, s[88:89]
	global_load_lds_dwordx4 v[8:9], off
	s_add_i32 m0, s4, 0x10400
	v_and_b32_e32 v12, 15, v10
	global_load_lds_dwordx4 v[2:3], off
	v_lshl_add_u64 v[2:3], v[4:5], 0, s[88:89]
	s_add_i32 m0, s4, 0x10800
	s_and_b32 s5, s5, 0x3ffff80
	global_load_lds_dwordx4 v[2:3], off
	v_lshl_add_u64 v[2:3], v[6:7], 0, s[88:89]
	s_add_i32 m0, s4, 0x10c00
	s_ashr_i32 s9, s8, 31
	global_load_lds_dwordx4 v[2:3], off
	v_lshrrev_b32_e32 v2, 2, v10
	v_sub_u32_e32 v2, 0, v2
	v_bitop3_b32 v2, v11, 3, v2 bitop3:0x48
	v_or_b32_e32 v3, s5, v12
	v_lshlrev_b32_e32 v2, 4, v2
	s_and_b32 s5, s13, 0xc0
	s_lshl_b64 s[8:9], s[8:9], 11
	v_lshl_or_b32 v141, v3, 6, v2
	v_or_b32_e32 v3, s5, v12
	s_add_u32 s8, s51, s8
	v_lshlrev_b32_e32 v3, 6, v3
	s_addc_u32 s9, s42, s9
	v_or3_b32 v142, v2, v3, s68
	v_lshl_add_u64 v[2:3], s[8:9], 0, v[128:129]
	s_add_i32 s8, s48, s44
	s_ashr_i32 s9, s8, 31
	s_lshl_b64 s[8:9], s[8:9], 11
	s_add_u32 s8, s50, s8
	s_addc_u32 s9, s49, s9
	v_lshl_add_u64 v[130:131], v[2:3], 0, s[92:93]
	v_lshl_add_u64 v[2:3], s[8:9], 0, v[128:129]
	s_add_i32 s8, s45, s44
	s_ashr_i32 s9, s8, 31
	s_lshl_b64 s[8:9], s[8:9], 11
	s_add_u32 s8, s47, s8
	s_addc_u32 s9, s46, s9
	v_lshl_add_u64 v[132:133], v[2:3], 0, s[94:95]
	v_lshl_add_u64 v[2:3], s[8:9], 0, v[128:129]
	v_lshl_add_u64 v[136:137], v[0:1], 0, s[78:79]
	v_mov_b32_e32 v0, 0
	v_lshl_add_u64 v[134:135], v[2:3], 0, s[96:97]
	s_mov_b32 s5, 0x18000
	v_mov_b32_e32 v1, v0
	v_mov_b32_e32 v2, v0
	v_mov_b32_e32 v3, v0
	v_mov_b32_e32 v4, v0
	v_mov_b32_e32 v5, v0
	v_mov_b32_e32 v6, v0
	v_mov_b32_e32 v7, v0
	v_mov_b32_e32 v8, v0
	v_mov_b32_e32 v9, v0
	v_mov_b32_e32 v10, v0
	v_mov_b32_e32 v11, v0
	v_mov_b32_e32 v12, v0
	v_mov_b32_e32 v13, v0
	v_mov_b32_e32 v14, v0
	v_mov_b32_e32 v15, v0
	s_waitcnt vmcnt(0)
	v_mov_b32_e32 v16, v0
	v_mov_b32_e32 v17, v0
	v_mov_b32_e32 v18, v0
	v_mov_b32_e32 v19, v0
	v_mov_b32_e32 v20, v0
	v_mov_b32_e32 v21, v0
	v_mov_b32_e32 v22, v0
	v_mov_b32_e32 v23, v0
	v_mov_b32_e32 v24, v0
	v_mov_b32_e32 v25, v0
	v_mov_b32_e32 v26, v0
	v_mov_b32_e32 v27, v0
	v_mov_b32_e32 v28, v0
	v_mov_b32_e32 v29, v0
	v_mov_b32_e32 v30, v0
	v_mov_b32_e32 v31, v0
	v_mov_b32_e32 v32, v0
	v_mov_b32_e32 v33, v0
	v_mov_b32_e32 v34, v0
	v_mov_b32_e32 v35, v0
	v_mov_b32_e32 v36, v0
	v_mov_b32_e32 v37, v0
	v_mov_b32_e32 v38, v0
	v_mov_b32_e32 v39, v0
	v_mov_b32_e32 v40, v0
	v_mov_b32_e32 v41, v0
	v_mov_b32_e32 v42, v0
	v_mov_b32_e32 v43, v0
	v_mov_b32_e32 v44, v0
	v_mov_b32_e32 v45, v0
	v_mov_b32_e32 v46, v0
	v_mov_b32_e32 v47, v0
	v_mov_b32_e32 v48, v0
	v_mov_b32_e32 v49, v0
	v_mov_b32_e32 v50, v0
	v_mov_b32_e32 v51, v0
	v_mov_b32_e32 v52, v0
	v_mov_b32_e32 v53, v0
	v_mov_b32_e32 v54, v0
	v_mov_b32_e32 v55, v0
	v_mov_b32_e32 v56, v0
	v_mov_b32_e32 v57, v0
	v_mov_b32_e32 v58, v0
	v_mov_b32_e32 v59, v0
	v_mov_b32_e32 v60, v0
	v_mov_b32_e32 v61, v0
	v_mov_b32_e32 v62, v0
	v_mov_b32_e32 v63, v0
	v_mov_b32_e32 v64, v0
	v_mov_b32_e32 v65, v0
	v_mov_b32_e32 v66, v0
	v_mov_b32_e32 v67, v0
	v_mov_b32_e32 v68, v0
	v_mov_b32_e32 v69, v0
	v_mov_b32_e32 v70, v0
	v_mov_b32_e32 v71, v0
	v_mov_b32_e32 v72, v0
	v_mov_b32_e32 v73, v0
	v_mov_b32_e32 v74, v0
	v_mov_b32_e32 v75, v0
	v_mov_b32_e32 v76, v0
	v_mov_b32_e32 v77, v0
	v_mov_b32_e32 v78, v0
	v_mov_b32_e32 v79, v0
	v_mov_b32_e32 v80, v0
	v_mov_b32_e32 v81, v0
	v_mov_b32_e32 v82, v0
	v_mov_b32_e32 v83, v0
	v_mov_b32_e32 v84, v0
	v_mov_b32_e32 v85, v0
	v_mov_b32_e32 v86, v0
	v_mov_b32_e32 v87, v0
	v_mov_b32_e32 v88, v0
	v_mov_b32_e32 v89, v0
	v_mov_b32_e32 v90, v0
	v_mov_b32_e32 v91, v0
	v_mov_b32_e32 v92, v0
	v_mov_b32_e32 v93, v0
	v_mov_b32_e32 v94, v0
	v_mov_b32_e32 v95, v0
	v_mov_b32_e32 v96, v0
	v_mov_b32_e32 v97, v0
	v_mov_b32_e32 v98, v0
	v_mov_b32_e32 v99, v0
	v_mov_b32_e32 v100, v0
	v_mov_b32_e32 v101, v0
	v_mov_b32_e32 v102, v0
	v_mov_b32_e32 v103, v0
	v_mov_b32_e32 v104, v0
	v_mov_b32_e32 v105, v0
	v_mov_b32_e32 v106, v0
	v_mov_b32_e32 v107, v0
	v_mov_b32_e32 v108, v0
	v_mov_b32_e32 v109, v0
	v_mov_b32_e32 v110, v0
	v_mov_b32_e32 v111, v0
	v_mov_b32_e32 v112, v0
	v_mov_b32_e32 v113, v0
	v_mov_b32_e32 v114, v0
	v_mov_b32_e32 v115, v0
	v_mov_b32_e32 v116, v0
	v_mov_b32_e32 v117, v0
	v_mov_b32_e32 v118, v0
	v_mov_b32_e32 v119, v0
	v_mov_b32_e32 v120, v0
	v_mov_b32_e32 v121, v0
	v_mov_b32_e32 v122, v0
	v_mov_b32_e32 v123, v0
	v_mov_b32_e32 v124, v0
	v_mov_b32_e32 v125, v0
	v_mov_b32_e32 v126, v0
	v_mov_b32_e32 v127, v0
	s_add_i32 s8, s5, 0xfffe8000
	s_and_b32 s9, s5, 0x18000
	s_waitcnt vmcnt(8)
	s_barrier
	s_and_b32 s8, s8, 0x18000
	s_add_i32 s9, s4, s9
	v_add_u32_e32 v128, s8, v141
	v_or_b32_e32 v143, s8, v142
	s_add_i32 s11, s9, 0x400
	s_add_i32 s10, s9, 0x800
	s_add_i32 s8, s9, 0xc00
	s_add_i32 s5, s5, 0x8000
	s_cmp_eq_u32 s5, 0x100000
	ds_read_b128 v[174:177], v128
	ds_read_b128 v[144:147], v143
	ds_read_b128 v[158:161], v143 offset:1024
	ds_read_b128 v[162:165], v143 offset:2048
	ds_read_b128 v[166:169], v143 offset:3072
	ds_read_b128 v[178:181], v128 offset:1024
	ds_read_b128 v[182:185], v128 offset:2048
	ds_read_b128 v[186:189], v128 offset:3072
	ds_read_b128 v[232:235], v128 offset:4096
	ds_read_b128 v[236:239], v128 offset:5120
	ds_read_b128 v[240:243], v128 offset:6144
	ds_read_b128 v[244:247], v128 offset:7168
	s_mov_b32 m0, s9
	s_nop 0
	global_load_lds_dwordx4 v[136:137], off
	v_lshl_add_u64 v[136:137], v[136:137], 0, 64
	s_mov_b32 m0, s11
	s_nop 0
	global_load_lds_dwordx4 v[134:135], off
	v_lshl_add_u64 v[134:135], v[134:135], 0, 64
	s_mov_b32 m0, s10
	s_nop 0
	global_load_lds_dwordx4 v[132:133], off
	v_lshl_add_u64 v[132:133], v[132:133], 0, 64
	s_mov_b32 m0, s8
	s_nop 0
	global_load_lds_dwordx4 v[130:131], off
	v_lshl_add_u64 v[130:131], v[130:131], 0, 64
	s_waitcnt lgkmcnt(4)
	v_mfma_f32_16x16x32_bf16 v[124:127], v[174:177], v[144:147], v[124:127]
	v_mfma_f32_16x16x32_bf16 v[120:123], v[174:177], v[158:161], v[120:123]
	v_mfma_f32_16x16x32_bf16 v[116:119], v[174:177], v[162:165], v[116:119]
	v_mfma_f32_16x16x32_bf16 v[112:115], v[174:177], v[166:169], v[112:115]
	v_mfma_f32_16x16x32_bf16 v[108:111], v[178:181], v[144:147], v[108:111]
	v_mfma_f32_16x16x32_bf16 v[104:107], v[178:181], v[158:161], v[104:107]
	v_mfma_f32_16x16x32_bf16 v[100:103], v[178:181], v[162:165], v[100:103]
	v_mfma_f32_16x16x32_bf16 v[96:99], v[178:181], v[166:169], v[96:99]
	v_mfma_f32_16x16x32_bf16 v[92:95], v[182:185], v[144:147], v[92:95]
	v_mfma_f32_16x16x32_bf16 v[88:91], v[182:185], v[158:161], v[88:91]
	v_mfma_f32_16x16x32_bf16 v[84:87], v[182:185], v[162:165], v[84:87]
	v_mfma_f32_16x16x32_bf16 v[80:83], v[182:185], v[166:169], v[80:83]
	v_mfma_f32_16x16x32_bf16 v[76:79], v[186:189], v[144:147], v[76:79]
	v_mfma_f32_16x16x32_bf16 v[72:75], v[186:189], v[158:161], v[72:75]
	v_mfma_f32_16x16x32_bf16 v[68:71], v[186:189], v[162:165], v[68:71]
	v_mfma_f32_16x16x32_bf16 v[64:67], v[186:189], v[166:169], v[64:67]
.Lgsk3_loop:
	s_add_i32 s8, s5, 0xfffe8000
	s_and_b32 s9, s5, 0x18000
	s_waitcnt vmcnt(8) lgkmcnt(0)
	s_barrier
	s_and_b32 s8, s8, 0x18000
	s_add_i32 s9, s4, s9
	v_add_u32_e32 v128, s8, v141
	v_or_b32_e32 v143, s8, v142
	s_add_i32 s11, s9, 0x400
	s_add_i32 s10, s9, 0x800
	s_add_i32 s8, s9, 0xc00
	s_add_i32 s5, s5, 0x8000
	s_cmp_eq_u32 s5, 0x100000
	ds_read_b128 v[174:177], v128
	ds_read_b128 v[178:181], v128 offset:1024
	ds_read_b128 v[182:185], v128 offset:2048
	ds_read_b128 v[186:189], v128 offset:3072
	v_mfma_f32_16x16x32_bf16 v[60:63], v[232:235], v[144:147], v[60:63]
	v_mfma_f32_16x16x32_bf16 v[44:47], v[236:239], v[144:147], v[44:47]
	v_mfma_f32_16x16x32_bf16 v[28:31], v[240:243], v[144:147], v[28:31]
	s_mov_b32 m0, s9
	v_mfma_f32_16x16x32_bf16 v[12:15], v[244:247], v[144:147], v[12:15]
	global_load_lds_dwordx4 v[136:137], off
	v_lshl_add_u64 v[136:137], v[136:137], 0, 64
	v_mfma_f32_16x16x32_bf16 v[56:59], v[232:235], v[158:161], v[56:59]
	ds_read_b128 v[144:147], v143
	v_mfma_f32_16x16x32_bf16 v[40:43], v[236:239], v[158:161], v[40:43]
	v_mfma_f32_16x16x32_bf16 v[24:27], v[240:243], v[158:161], v[24:27]
	s_mov_b32 m0, s11
	v_mfma_f32_16x16x32_bf16 v[8:11], v[244:247], v[158:161], v[8:11]
	global_load_lds_dwordx4 v[134:135], off
	v_lshl_add_u64 v[134:135], v[134:135], 0, 64
	v_mfma_f32_16x16x32_bf16 v[52:55], v[232:235], v[162:165], v[52:55]
	ds_read_b128 v[158:161], v143 offset:1024
	v_mfma_f32_16x16x32_bf16 v[36:39], v[236:239], v[162:165], v[36:39]
	v_mfma_f32_16x16x32_bf16 v[20:23], v[240:243], v[162:165], v[20:23]
	s_mov_b32 m0, s10
	v_mfma_f32_16x16x32_bf16 v[4:7], v[244:247], v[162:165], v[4:7]
	global_load_lds_dwordx4 v[132:133], off
	v_lshl_add_u64 v[132:133], v[132:133], 0, 64
	v_mfma_f32_16x16x32_bf16 v[48:51], v[232:235], v[166:169], v[48:51]
	ds_read_b128 v[162:165], v143 offset:2048
	v_mfma_f32_16x16x32_bf16 v[32:35], v[236:239], v[166:169], v[32:35]
	v_mfma_f32_16x16x32_bf16 v[16:19], v[240:243], v[166:169], v[16:19]
	s_mov_b32 m0, s8
	v_mfma_f32_16x16x32_bf16 v[0:3], v[244:247], v[166:169], v[0:3]
	global_load_lds_dwordx4 v[130:131], off
	v_lshl_add_u64 v[130:131], v[130:131], 0, 64
	s_waitcnt lgkmcnt(2)
	v_mfma_f32_16x16x32_bf16 v[124:127], v[174:177], v[144:147], v[124:127]
	ds_read_b128 v[166:169], v143 offset:3072
	v_mfma_f32_16x16x32_bf16 v[108:111], v[178:181], v[144:147], v[108:111]
	ds_read_b128 v[232:235], v128 offset:4096
	ds_read_b128 v[236:239], v128 offset:5120
	v_mfma_f32_16x16x32_bf16 v[92:95], v[182:185], v[144:147], v[92:95]
	ds_read_b128 v[240:243], v128 offset:6144
	ds_read_b128 v[244:247], v128 offset:7168
	v_mfma_f32_16x16x32_bf16 v[76:79], v[186:189], v[144:147], v[76:79]
	s_waitcnt lgkmcnt(6)
	v_mfma_f32_16x16x32_bf16 v[120:123], v[174:177], v[158:161], v[120:123]
	v_mfma_f32_16x16x32_bf16 v[104:107], v[178:181], v[158:161], v[104:107]
	v_mfma_f32_16x16x32_bf16 v[88:91], v[182:185], v[158:161], v[88:91]
	v_mfma_f32_16x16x32_bf16 v[72:75], v[186:189], v[158:161], v[72:75]
	s_waitcnt lgkmcnt(5)
	v_mfma_f32_16x16x32_bf16 v[116:119], v[174:177], v[162:165], v[116:119]
	v_mfma_f32_16x16x32_bf16 v[100:103], v[178:181], v[162:165], v[100:103]
	v_mfma_f32_16x16x32_bf16 v[84:87], v[182:185], v[162:165], v[84:87]
	v_mfma_f32_16x16x32_bf16 v[68:71], v[186:189], v[162:165], v[68:71]
	s_waitcnt lgkmcnt(4)
	v_mfma_f32_16x16x32_bf16 v[112:115], v[174:177], v[166:169], v[112:115]
	v_mfma_f32_16x16x32_bf16 v[96:99], v[178:181], v[166:169], v[96:99]
	v_mfma_f32_16x16x32_bf16 v[80:83], v[182:185], v[166:169], v[80:83]
	v_mfma_f32_16x16x32_bf16 v[64:67], v[186:189], v[166:169], v[64:67]
	s_cbranch_scc0 .Lgsk3_loop
	s_waitcnt lgkmcnt(0)
	v_mfma_f32_16x16x32_bf16 v[60:63], v[232:235], v[144:147], v[60:63]
	v_mfma_f32_16x16x32_bf16 v[44:47], v[236:239], v[144:147], v[44:47]
	v_mfma_f32_16x16x32_bf16 v[28:31], v[240:243], v[144:147], v[28:31]
	v_mfma_f32_16x16x32_bf16 v[12:15], v[244:247], v[144:147], v[12:15]
	v_mfma_f32_16x16x32_bf16 v[56:59], v[232:235], v[158:161], v[56:59]
	v_mfma_f32_16x16x32_bf16 v[40:43], v[236:239], v[158:161], v[40:43]
	v_mfma_f32_16x16x32_bf16 v[24:27], v[240:243], v[158:161], v[24:27]
	v_mfma_f32_16x16x32_bf16 v[8:11], v[244:247], v[158:161], v[8:11]
	v_mfma_f32_16x16x32_bf16 v[52:55], v[232:235], v[162:165], v[52:55]
	v_mfma_f32_16x16x32_bf16 v[36:39], v[236:239], v[162:165], v[36:39]
	v_mfma_f32_16x16x32_bf16 v[20:23], v[240:243], v[162:165], v[20:23]
	v_mfma_f32_16x16x32_bf16 v[4:7], v[244:247], v[162:165], v[4:7]
	v_mfma_f32_16x16x32_bf16 v[48:51], v[232:235], v[166:169], v[48:51]
	v_mfma_f32_16x16x32_bf16 v[32:35], v[236:239], v[166:169], v[32:35]
	v_mfma_f32_16x16x32_bf16 v[16:19], v[240:243], v[166:169], v[16:19]
	v_mfma_f32_16x16x32_bf16 v[0:3], v[244:247], v[166:169], v[0:3]
	s_waitcnt vmcnt(8)
	s_barrier
	v_add_u32_e32 v128, 0x8000, v141
	v_or_b32_e32 v143, 0x8000, v142
	ds_read_b128 v[130:133], v143
	ds_read_b128 v[134:137], v143 offset:1024
	ds_read_b128 v[144:147], v143 offset:2048
	ds_read_b128 v[158:161], v143 offset:3072
	ds_read_b128 v[162:165], v128
	ds_read_b128 v[166:169], v128 offset:1024
	ds_read_b128 v[174:177], v128 offset:2048
	ds_read_b128 v[178:181], v128 offset:3072
	v_or_b32_e32 v143, 0x10000, v142
	s_waitcnt lgkmcnt(0)
	s_ashr_i32 s13, s12, 31
	v_mfma_f32_16x16x32_bf16 v[124:127], v[162:165], v[130:133], v[124:127]
	s_lshl_b64 s[4:5], s[12:13], 2
	s_add_u32 s4, s62, s4
	s_addc_u32 s5, s63, s5
	v_mfma_f32_16x16x32_bf16 v[120:123], v[162:165], v[134:137], v[120:123]
	v_mfma_f32_16x16x32_bf16 v[116:119], v[162:165], v[144:147], v[116:119]
	v_mfma_f32_16x16x32_bf16 v[112:115], v[162:165], v[158:161], v[112:115]
	v_mfma_f32_16x16x32_bf16 v[108:111], v[166:169], v[130:133], v[108:111]
	v_mfma_f32_16x16x32_bf16 v[104:107], v[166:169], v[134:137], v[104:107]
	v_mfma_f32_16x16x32_bf16 v[100:103], v[166:169], v[144:147], v[100:103]
	v_mfma_f32_16x16x32_bf16 v[96:99], v[166:169], v[158:161], v[96:99]
	v_mfma_f32_16x16x32_bf16 v[92:95], v[174:177], v[130:133], v[92:95]
	v_mfma_f32_16x16x32_bf16 v[88:91], v[174:177], v[134:137], v[88:91]
	v_mfma_f32_16x16x32_bf16 v[84:87], v[174:177], v[144:147], v[84:87]
	v_mfma_f32_16x16x32_bf16 v[80:83], v[174:177], v[158:161], v[80:83]
	v_mfma_f32_16x16x32_bf16 v[76:79], v[178:181], v[130:133], v[76:79]
	v_mfma_f32_16x16x32_bf16 v[72:75], v[178:181], v[134:137], v[72:75]
	v_mfma_f32_16x16x32_bf16 v[68:71], v[178:181], v[144:147], v[68:71]
	v_mfma_f32_16x16x32_bf16 v[64:67], v[178:181], v[158:161], v[64:67]
	ds_read_b128 v[162:165], v128 offset:4096
	ds_read_b128 v[166:169], v128 offset:5120
	ds_read_b128 v[174:177], v128 offset:6144
	ds_read_b128 v[178:181], v128 offset:7168
	s_waitcnt lgkmcnt(0)
	s_waitcnt vmcnt(4)
	s_barrier
	v_mfma_f32_16x16x32_bf16 v[60:63], v[162:165], v[130:133], v[60:63]
	v_add_u32_e32 v128, 0x10000, v141
	v_mfma_f32_16x16x32_bf16 v[56:59], v[162:165], v[134:137], v[56:59]
	v_mfma_f32_16x16x32_bf16 v[52:55], v[162:165], v[144:147], v[52:55]
	v_mfma_f32_16x16x32_bf16 v[48:51], v[162:165], v[158:161], v[48:51]
	v_mfma_f32_16x16x32_bf16 v[44:47], v[166:169], v[130:133], v[44:47]
	v_mfma_f32_16x16x32_bf16 v[40:43], v[166:169], v[134:137], v[40:43]
	v_mfma_f32_16x16x32_bf16 v[36:39], v[166:169], v[144:147], v[36:39]
	v_mfma_f32_16x16x32_bf16 v[32:35], v[166:169], v[158:161], v[32:35]
	v_mfma_f32_16x16x32_bf16 v[28:31], v[174:177], v[130:133], v[28:31]
	v_mfma_f32_16x16x32_bf16 v[24:27], v[174:177], v[134:137], v[24:27]
	v_mfma_f32_16x16x32_bf16 v[20:23], v[174:177], v[144:147], v[20:23]
	v_mfma_f32_16x16x32_bf16 v[16:19], v[174:177], v[158:161], v[16:19]
	v_mfma_f32_16x16x32_bf16 v[12:15], v[178:181], v[130:133], v[12:15]
	v_mfma_f32_16x16x32_bf16 v[8:11], v[178:181], v[134:137], v[8:11]
	v_mfma_f32_16x16x32_bf16 v[4:7], v[178:181], v[144:147], v[4:7]
	v_mfma_f32_16x16x32_bf16 v[0:3], v[178:181], v[158:161], v[0:3]
	ds_read_b128 v[130:133], v143
	ds_read_b128 v[134:137], v143 offset:1024
	ds_read_b128 v[144:147], v143 offset:2048
	ds_read_b128 v[158:161], v143 offset:3072
	ds_read_b128 v[162:165], v128
	ds_read_b128 v[166:169], v128 offset:1024
	ds_read_b128 v[174:177], v128 offset:2048
	ds_read_b128 v[178:181], v128 offset:3072
	s_nop 0
	s_waitcnt lgkmcnt(0)
	s_nop 0
	v_mfma_f32_16x16x32_bf16 v[124:127], v[162:165], v[130:133], v[124:127]
	v_mfma_f32_16x16x32_bf16 v[120:123], v[162:165], v[134:137], v[120:123]
	v_mfma_f32_16x16x32_bf16 v[116:119], v[162:165], v[144:147], v[116:119]
	v_mfma_f32_16x16x32_bf16 v[112:115], v[162:165], v[158:161], v[112:115]
	v_mfma_f32_16x16x32_bf16 v[108:111], v[166:169], v[130:133], v[108:111]
	v_mfma_f32_16x16x32_bf16 v[104:107], v[166:169], v[134:137], v[104:107]
	v_mfma_f32_16x16x32_bf16 v[100:103], v[166:169], v[144:147], v[100:103]
	v_mfma_f32_16x16x32_bf16 v[96:99], v[166:169], v[158:161], v[96:99]
	v_mfma_f32_16x16x32_bf16 v[92:95], v[174:177], v[130:133], v[92:95]
	v_mfma_f32_16x16x32_bf16 v[88:91], v[174:177], v[134:137], v[88:91]
	v_mfma_f32_16x16x32_bf16 v[84:87], v[174:177], v[144:147], v[84:87]
	v_mfma_f32_16x16x32_bf16 v[80:83], v[174:177], v[158:161], v[80:83]
	v_mfma_f32_16x16x32_bf16 v[76:79], v[178:181], v[130:133], v[76:79]
	v_mfma_f32_16x16x32_bf16 v[72:75], v[178:181], v[134:137], v[72:75]
	v_mfma_f32_16x16x32_bf16 v[68:71], v[178:181], v[144:147], v[68:71]
	v_mfma_f32_16x16x32_bf16 v[64:67], v[178:181], v[158:161], v[64:67]
	ds_read_b128 v[162:165], v128 offset:4096
	ds_read_b128 v[166:169], v128 offset:5120
	ds_read_b128 v[174:177], v128 offset:6144
	ds_read_b128 v[178:181], v128 offset:7168
	s_waitcnt lgkmcnt(0)
	s_waitcnt vmcnt(0)
	s_barrier
	v_mfma_f32_16x16x32_bf16 v[60:63], v[162:165], v[130:133], v[60:63]
	v_add_u32_e32 v128, 0x18000, v141
	v_or_b32_e32 v141, 0x18000, v142
	v_mfma_f32_16x16x32_bf16 v[56:59], v[162:165], v[134:137], v[56:59]
	v_mfma_f32_16x16x32_bf16 v[52:55], v[162:165], v[144:147], v[52:55]
	v_mfma_f32_16x16x32_bf16 v[48:51], v[162:165], v[158:161], v[48:51]
	v_mfma_f32_16x16x32_bf16 v[44:47], v[166:169], v[130:133], v[44:47]
	v_mfma_f32_16x16x32_bf16 v[40:43], v[166:169], v[134:137], v[40:43]
	v_mfma_f32_16x16x32_bf16 v[36:39], v[166:169], v[144:147], v[36:39]
	v_mfma_f32_16x16x32_bf16 v[32:35], v[166:169], v[158:161], v[32:35]
	v_mfma_f32_16x16x32_bf16 v[28:31], v[174:177], v[130:133], v[28:31]
	v_mfma_f32_16x16x32_bf16 v[24:27], v[174:177], v[134:137], v[24:27]
	v_mfma_f32_16x16x32_bf16 v[20:23], v[174:177], v[144:147], v[20:23]
	v_mfma_f32_16x16x32_bf16 v[16:19], v[174:177], v[158:161], v[16:19]
	v_mfma_f32_16x16x32_bf16 v[12:15], v[178:181], v[130:133], v[12:15]
	v_mfma_f32_16x16x32_bf16 v[8:11], v[178:181], v[134:137], v[8:11]
	v_mfma_f32_16x16x32_bf16 v[4:7], v[178:181], v[144:147], v[4:7]
	v_mfma_f32_16x16x32_bf16 v[0:3], v[178:181], v[158:161], v[0:3]
	ds_read_b128 v[130:133], v141
	ds_read_b128 v[134:137], v141 offset:1024
	ds_read_b128 v[142:145], v141 offset:2048
	ds_read_b128 v[158:161], v141 offset:3072
	ds_read_b128 v[162:165], v128
	ds_read_b128 v[166:169], v128 offset:1024
	ds_read_b128 v[174:177], v128 offset:2048
	ds_read_b128 v[178:181], v128 offset:3072
	s_nop 0
	s_waitcnt lgkmcnt(0)
	s_nop 0
	v_mfma_f32_16x16x32_bf16 v[124:127], v[162:165], v[130:133], v[124:127]
	v_mfma_f32_16x16x32_bf16 v[120:123], v[162:165], v[134:137], v[120:123]
	v_mfma_f32_16x16x32_bf16 v[116:119], v[162:165], v[142:145], v[116:119]
	v_mfma_f32_16x16x32_bf16 v[162:165], v[162:165], v[158:161], v[112:115]
	v_mfma_f32_16x16x32_bf16 v[108:111], v[166:169], v[130:133], v[108:111]
	v_mfma_f32_16x16x32_bf16 v[104:107], v[166:169], v[134:137], v[104:107]
	v_mfma_f32_16x16x32_bf16 v[100:103], v[166:169], v[142:145], v[100:103]
	v_mfma_f32_16x16x32_bf16 v[96:99], v[166:169], v[158:161], v[96:99]
	v_mfma_f32_16x16x32_bf16 v[92:95], v[174:177], v[130:133], v[92:95]
	v_mfma_f32_16x16x32_bf16 v[88:91], v[174:177], v[134:137], v[88:91]
	v_mfma_f32_16x16x32_bf16 v[84:87], v[174:177], v[142:145], v[84:87]
	v_mfma_f32_16x16x32_bf16 v[80:83], v[174:177], v[158:161], v[80:83]
	v_mfma_f32_16x16x32_bf16 v[76:79], v[178:181], v[130:133], v[76:79]
	v_mfma_f32_16x16x32_bf16 v[72:75], v[178:181], v[134:137], v[72:75]
	v_mfma_f32_16x16x32_bf16 v[68:71], v[178:181], v[142:145], v[68:71]
	v_mfma_f32_16x16x32_bf16 v[64:67], v[178:181], v[158:161], v[64:67]
	ds_read_b128 v[112:115], v128 offset:4096
	ds_read_b128 v[166:169], v128 offset:5120
	ds_read_b128 v[174:177], v128 offset:6144
	ds_read_b128 v[178:181], v128 offset:7168
	s_waitcnt lgkmcnt(0)
	s_barrier
	v_mfma_f32_16x16x32_bf16 v[60:63], v[112:115], v[130:133], v[60:63]
	v_mfma_f32_16x16x32_bf16 v[56:59], v[112:115], v[134:137], v[56:59]
	v_mfma_f32_16x16x32_bf16 v[52:55], v[112:115], v[142:145], v[52:55]
	v_mfma_f32_16x16x32_bf16 v[48:51], v[112:115], v[158:161], v[48:51]
	v_lshlrev_b32_e32 v114, 3, v139
	v_lshlrev_b32_e32 v113, 8, v140
	v_and_b32_e32 v114, 8, v114
	v_add3_u32 v113, s38, v113, v114
	v_lshlrev_b32_e32 v114, 4, v139
	v_mfma_f32_16x16x32_bf16 v[44:47], v[166:169], v[130:133], v[44:47]
	v_lshrrev_b32_e32 v112, 5, v138
	v_xor_b32_e32 v115, v112, v140
	v_lshl_add_u32 v115, v115, 4, v113
	v_mfma_f32_16x16x32_bf16 v[28:31], v[174:177], v[130:133], v[28:31]
	v_mfma_f32_16x16x32_bf16 v[12:15], v[178:181], v[130:133], v[12:15]
	global_load_dwordx4 v[130:133], v114, s[4:5]
	s_waitcnt vmcnt(0)
	v_pk_mul_f32 v[126:127], v[126:127], v[132:133]
	v_pk_mul_f32 v[124:125], v[124:125], v[130:131]
	v_pk_mul_f32 v[122:123], v[122:123], v[132:133]
	v_pk_mul_f32 v[120:121], v[120:121], v[130:131]
	v_cvt_pk_bf16_f32 v124, v124, v125
	v_cvt_pk_bf16_f32 v125, v126, v127
	v_cvt_pk_bf16_f32 v120, v120, v121
	v_cvt_pk_bf16_f32 v121, v122, v123
	v_pk_mul_f32 v[118:119], v[118:119], v[132:133]
	v_pk_mul_f32 v[116:117], v[116:117], v[130:131]
	ds_write2st64_b64 v115, v[124:125], v[120:121] offset1:8
	v_cvt_pk_bf16_f32 v116, v116, v117
	v_cvt_pk_bf16_f32 v117, v118, v119
	v_pk_mul_f32 v[118:119], v[164:165], v[132:133]
	v_pk_mul_f32 v[120:121], v[162:163], v[130:131]
	v_mfma_f32_16x16x32_bf16 v[36:39], v[166:169], v[142:145], v[36:39]
	v_cvt_pk_bf16_f32 v120, v120, v121
	v_cvt_pk_bf16_f32 v121, v118, v119
	ds_write2st64_b64 v115, v[116:117], v[120:121] offset0:16 offset1:24
	global_load_dwordx4 v[116:119], v114, s[4:5] offset:64
	v_bitop3_b32 v115, v112, v140, 2 bitop3:0x36
	v_lshl_add_u32 v115, v115, 4, v113
	v_mfma_f32_16x16x32_bf16 v[32:35], v[166:169], v[158:161], v[32:35]
	s_waitcnt vmcnt(0)
	v_pk_mul_f32 v[102:103], v[102:103], v[118:119]
	v_pk_mul_f32 v[100:101], v[100:101], v[116:117]
	v_pk_mul_f32 v[98:99], v[98:99], v[118:119]
	v_pk_mul_f32 v[96:97], v[96:97], v[116:117]
	v_cvt_pk_bf16_f32 v100, v100, v101
	v_cvt_pk_bf16_f32 v101, v102, v103
	v_cvt_pk_bf16_f32 v96, v96, v97
	v_cvt_pk_bf16_f32 v97, v98, v99
	ds_write2st64_b64 v115, v[100:101], v[96:97] offset0:16 offset1:24
	global_load_dwordx4 v[96:99], v114, s[4:5] offset:128
	v_bitop3_b32 v100, v112, v140, 4 bitop3:0x36
	v_lshl_add_u32 v100, v100, 4, v113
	v_mfma_f32_16x16x32_bf16 v[20:23], v[174:177], v[142:145], v[20:23]
	v_mul_f32_e64 v110, v110, v118
	v_mul_f32_e64 v111, v111, v119
	v_pk_mul_f32 v[108:109], v[108:109], v[116:117]
	v_pk_mul_f32 v[106:107], v[106:107], v[118:119]
	v_mfma_f32_16x16x32_bf16 v[16:19], v[174:177], v[158:161], v[16:19]
	v_mul_f32_e64 v104, v104, v116
	v_mul_f32_e64 v105, v105, v117
	v_cvt_pk_bf16_f32 v108, v108, v109
	v_cvt_pk_bf16_f32 v109, v110, v111
	v_mfma_f32_16x16x32_bf16 v[0:3], v[178:181], v[158:161], v[0:3]
	v_cvt_pk_bf16_f32 v104, v104, v105
	v_cvt_pk_bf16_f32 v105, v106, v107
	ds_write2st64_b64 v115, v[108:109], v[104:105] offset1:8
	v_mfma_f32_16x16x32_bf16 v[8:11], v[178:181], v[134:137], v[8:11]
	s_waitcnt vmcnt(0)
	v_pk_mul_f32 v[86:87], v[86:87], v[98:99]
	v_pk_mul_f32 v[84:85], v[84:85], v[96:97]
	v_pk_mul_f32 v[82:83], v[82:83], v[98:99]
	v_pk_mul_f32 v[80:81], v[80:81], v[96:97]
	v_cvt_pk_bf16_f32 v84, v84, v85
	v_cvt_pk_bf16_f32 v85, v86, v87
	v_cvt_pk_bf16_f32 v80, v80, v81
	v_cvt_pk_bf16_f32 v81, v82, v83
	ds_write2st64_b64 v100, v[84:85], v[80:81] offset0:16 offset1:24
	global_load_dwordx4 v[80:83], v114, s[4:5] offset:192
	v_bitop3_b32 v84, v112, v140, 6 bitop3:0x36
	v_lshl_add_u32 v84, v84, 4, v113
	v_mfma_f32_16x16x32_bf16 v[40:43], v[166:169], v[134:137], v[40:43]
	v_mul_f32_e64 v94, v94, v98
	v_mul_f32_e64 v95, v95, v99
	v_pk_mul_f32 v[92:93], v[92:93], v[96:97]
	v_pk_mul_f32 v[90:91], v[90:91], v[98:99]
	v_mfma_f32_16x16x32_bf16 v[24:27], v[174:177], v[134:137], v[24:27]
	v_mul_f32_e64 v88, v88, v96
	v_mul_f32_e64 v89, v89, v97
	v_cvt_pk_bf16_f32 v92, v92, v93
	v_cvt_pk_bf16_f32 v93, v94, v95
	v_mfma_f32_16x16x32_bf16 v[4:7], v[178:181], v[142:145], v[4:7]
	v_cvt_pk_bf16_f32 v88, v88, v89
	v_cvt_pk_bf16_f32 v89, v90, v91
	ds_write2st64_b64 v100, v[92:93], v[88:89] offset1:8
	s_waitcnt vmcnt(0)
	v_pk_mul_f32 v[70:71], v[70:71], v[82:83]
	v_pk_mul_f32 v[68:69], v[68:69], v[80:81]
	v_pk_mul_f32 v[66:67], v[66:67], v[82:83]
	v_pk_mul_f32 v[64:65], v[64:65], v[80:81]
	v_cvt_pk_bf16_f32 v68, v68, v69
	v_cvt_pk_bf16_f32 v69, v70, v71
	v_cvt_pk_bf16_f32 v64, v64, v65
	v_cvt_pk_bf16_f32 v65, v66, v67
	ds_write2st64_b64 v84, v[68:69], v[64:65] offset0:16 offset1:24
	global_load_dwordx4 v[64:67], v114, s[4:5] offset:256
	v_bitop3_b32 v68, v112, v140, 8 bitop3:0x36
	v_lshl_add_u32 v68, v68, 4, v113
	v_pk_mul_f32 v[78:79], v[78:79], v[82:83]
	v_pk_mul_f32 v[76:77], v[76:77], v[80:81]
	v_pk_mul_f32 v[74:75], v[74:75], v[82:83]
	v_pk_mul_f32 v[72:73], v[72:73], v[80:81]
	v_cvt_pk_bf16_f32 v76, v76, v77
	v_cvt_pk_bf16_f32 v77, v78, v79
	v_cvt_pk_bf16_f32 v72, v72, v73
	v_cvt_pk_bf16_f32 v73, v74, v75
	ds_write2st64_b64 v84, v[76:77], v[72:73] offset1:8
	s_waitcnt vmcnt(0)
	v_pk_mul_f32 v[54:55], v[54:55], v[66:67]
	v_pk_mul_f32 v[52:53], v[52:53], v[64:65]
	v_pk_mul_f32 v[50:51], v[50:51], v[66:67]
	v_pk_mul_f32 v[48:49], v[48:49], v[64:65]
	v_cvt_pk_bf16_f32 v52, v52, v53
	v_cvt_pk_bf16_f32 v53, v54, v55
	v_cvt_pk_bf16_f32 v48, v48, v49
	v_cvt_pk_bf16_f32 v49, v50, v51
	ds_write2st64_b64 v68, v[52:53], v[48:49] offset0:16 offset1:24
	global_load_dwordx4 v[48:51], v114, s[4:5] offset:320
	v_bitop3_b32 v52, v112, v140, 10 bitop3:0x36
	v_lshl_add_u32 v52, v52, 4, v113
	v_pk_mul_f32 v[62:63], v[62:63], v[66:67]
	v_pk_mul_f32 v[60:61], v[60:61], v[64:65]
	v_pk_mul_f32 v[58:59], v[58:59], v[66:67]
	v_pk_mul_f32 v[56:57], v[56:57], v[64:65]
	v_cvt_pk_bf16_f32 v60, v60, v61
	v_cvt_pk_bf16_f32 v61, v62, v63
	v_cvt_pk_bf16_f32 v56, v56, v57
	v_cvt_pk_bf16_f32 v57, v58, v59
	ds_write2st64_b64 v68, v[60:61], v[56:57] offset1:8
	s_waitcnt vmcnt(0)
	v_pk_mul_f32 v[38:39], v[38:39], v[50:51]
	v_pk_mul_f32 v[36:37], v[36:37], v[48:49]
	v_pk_mul_f32 v[34:35], v[34:35], v[50:51]
	v_pk_mul_f32 v[32:33], v[32:33], v[48:49]
	v_cvt_pk_bf16_f32 v36, v36, v37
	v_cvt_pk_bf16_f32 v37, v38, v39
	v_cvt_pk_bf16_f32 v32, v32, v33
	v_cvt_pk_bf16_f32 v33, v34, v35
	ds_write2st64_b64 v52, v[36:37], v[32:33] offset0:16 offset1:24
	global_load_dwordx4 v[32:35], v114, s[4:5] offset:384
	v_bitop3_b32 v36, v112, v140, 12 bitop3:0x36
	v_lshl_add_u32 v36, v36, 4, v113
	v_pk_mul_f32 v[46:47], v[46:47], v[50:51]
	v_pk_mul_f32 v[44:45], v[44:45], v[48:49]
	v_pk_mul_f32 v[42:43], v[42:43], v[50:51]
	v_pk_mul_f32 v[40:41], v[40:41], v[48:49]
	v_cvt_pk_bf16_f32 v44, v44, v45
	v_cvt_pk_bf16_f32 v45, v46, v47
	v_cvt_pk_bf16_f32 v40, v40, v41
	v_cvt_pk_bf16_f32 v41, v42, v43
	ds_write2st64_b64 v52, v[44:45], v[40:41] offset1:8
	s_waitcnt vmcnt(0)
	v_pk_mul_f32 v[22:23], v[22:23], v[34:35]
	v_pk_mul_f32 v[20:21], v[20:21], v[32:33]
	v_pk_mul_f32 v[18:19], v[18:19], v[34:35]
	v_pk_mul_f32 v[16:17], v[16:17], v[32:33]
	v_cvt_pk_bf16_f32 v20, v20, v21
	v_cvt_pk_bf16_f32 v21, v22, v23
	v_cvt_pk_bf16_f32 v16, v16, v17
	v_cvt_pk_bf16_f32 v17, v18, v19
	ds_write2st64_b64 v36, v[20:21], v[16:17] offset0:16 offset1:24
	global_load_dwordx4 v[16:19], v114, s[4:5] offset:448
	s_lshr_b32 s4, s40, 6
	s_and_b32 s5, s39, -16
	s_or_b32 s4, s4, s5
	v_bitop3_b32 v20, v112, v140, 14 bitop3:0x36
	s_ashr_i32 s5, s4, 31
	v_pk_mul_f32 v[30:31], v[30:31], v[34:35]
	v_pk_mul_f32 v[28:29], v[28:29], v[32:33]
	v_pk_mul_f32 v[26:27], v[26:27], v[34:35]
	v_pk_mul_f32 v[24:25], v[24:25], v[32:33]
	v_lshl_add_u32 v20, v20, 4, v113
	s_lshl_b64 s[4:5], s[4:5], 19
	v_cvt_pk_bf16_f32 v28, v28, v29
	v_cvt_pk_bf16_f32 v29, v30, v31
	v_cvt_pk_bf16_f32 v24, v24, v25
	v_cvt_pk_bf16_f32 v25, v26, v27
	s_add_u32 s4, s26, s4
	ds_write2st64_b64 v36, v[28:29], v[24:25] offset1:8
	s_addc_u32 s5, s27, s5
	s_and_b32 s8, s12, 0xf80
	s_lshl_b32 s8, s8, 1
	s_add_u32 s4, s4, s8
	s_addc_u32 s5, s5, 0
	s_waitcnt vmcnt(0)
	v_pk_mul_f32 v[2:3], v[2:3], v[18:19]
	v_pk_mul_f32 v[0:1], v[0:1], v[16:17]
	v_pk_mul_f32 v[14:15], v[14:15], v[18:19]
	v_pk_mul_f32 v[12:13], v[12:13], v[16:17]
	v_pk_mul_f32 v[10:11], v[10:11], v[18:19]
	v_pk_mul_f32 v[8:9], v[8:9], v[16:17]
	v_cvt_pk_bf16_f32 v0, v0, v1
	v_cvt_pk_bf16_f32 v1, v2, v3
	v_xor_b32_e32 v3, v139, v138
	v_cvt_pk_bf16_f32 v12, v12, v13
	v_cvt_pk_bf16_f32 v13, v14, v15
	v_cvt_pk_bf16_f32 v8, v8, v9
	v_cvt_pk_bf16_f32 v9, v10, v11
	v_lshlrev_b32_e32 v3, 4, v3
	ds_write2st64_b64 v20, v[12:13], v[8:9] offset1:8
	v_pk_mul_f32 v[6:7], v[6:7], v[18:19]
	v_pk_mul_f32 v[4:5], v[4:5], v[16:17]
	v_lshlrev_b32_e32 v2, 8, v139
	v_and_b32_e32 v8, 0xf0, v3
	v_cvt_pk_bf16_f32 v4, v4, v5
	v_cvt_pk_bf16_f32 v5, v6, v7
	v_add3_u32 v2, s38, v2, v8
	ds_write2st64_b64 v20, v[4:5], v[0:1] offset0:16 offset1:24
	ds_read_b128 v[2:5], v2
	v_lshlrev_b32_e32 v0, 4, v138
	v_and_b32_e32 v128, 0xf0, v0
	v_lshl_add_u64 v[0:1], s[4:5], 0, v[128:129]
	v_lshlrev_b32_e32 v128, 13, v139
	v_lshl_add_u64 v[6:7], v[0:1], 0, v[128:129]
	s_waitcnt lgkmcnt(0)
	global_store_dwordx4 v[6:7], v[2:5], off
	v_or_b32_e32 v6, 4, v139
	v_lshlrev_b32_e32 v128, 13, v6
	v_bitop3_b32 v3, v139, v138, 4 bitop3:0x36
	v_lshlrev_b32_e32 v3, 4, v3
	v_lshlrev_b32_e32 v2, 8, v6
	v_and_b32_e32 v3, 0xf0, v3
	v_add3_u32 v2, s38, v2, v3
	ds_read_b128 v[2:5], v2
	v_lshl_add_u64 v[6:7], v[0:1], 0, v[128:129]
	s_waitcnt lgkmcnt(0)
	global_store_dwordx4 v[6:7], v[2:5], off
	s_nop 1
	v_bitop3_b32 v3, v139, v138, 8 bitop3:0x36
	v_or_b32_e32 v6, 8, v139
	v_lshlrev_b32_e32 v3, 4, v3
	v_lshlrev_b32_e32 v2, 8, v6
	v_and_b32_e32 v3, 0xf0, v3
	v_add3_u32 v2, s38, v2, v3
	ds_read_b128 v[2:5], v2
	v_lshlrev_b32_e32 v128, 13, v6
	v_lshl_add_u64 v[6:7], v[0:1], 0, v[128:129]
	s_waitcnt lgkmcnt(0)
	global_store_dwordx4 v[6:7], v[2:5], off
	s_nop 1
	v_bitop3_b32 v3, v139, v138, 12 bitop3:0x36
	v_or_b32_e32 v6, 12, v139
	v_lshlrev_b32_e32 v3, 4, v3
	v_lshlrev_b32_e32 v2, 8, v6
	v_and_b32_e32 v3, 0xf0, v3
	v_add3_u32 v2, s38, v2, v3
	ds_read_b128 v[2:5], v2
	v_lshlrev_b32_e32 v128, 13, v6
	v_lshl_add_u64 v[6:7], v[0:1], 0, v[128:129]
	s_waitcnt lgkmcnt(0)
	global_store_dwordx4 v[6:7], v[2:5], off
	v_or_b32_e32 v6, 16, v139
	s_nop 0
	v_lshlrev_b32_e32 v2, 8, v6
	v_add3_u32 v2, s38, v2, v8
	ds_read_b128 v[2:5], v2
	v_lshlrev_b32_e32 v128, 13, v6
	v_lshl_add_u64 v[6:7], v[0:1], 0, v[128:129]
	s_waitcnt lgkmcnt(0)
	global_store_dwordx4 v[6:7], v[2:5], off
	s_nop 1
	v_bitop3_b32 v3, v139, v138, 20 bitop3:0x36
	v_or_b32_e32 v6, 20, v139
	v_lshlrev_b32_e32 v3, 4, v3
	v_lshlrev_b32_e32 v2, 8, v6
	v_and_b32_e32 v3, 0xf0, v3
	v_add3_u32 v2, s38, v2, v3
	ds_read_b128 v[2:5], v2
	v_lshlrev_b32_e32 v128, 13, v6
	v_lshl_add_u64 v[6:7], v[0:1], 0, v[128:129]
	s_waitcnt lgkmcnt(0)
	global_store_dwordx4 v[6:7], v[2:5], off
	s_nop 1
	v_bitop3_b32 v3, v139, v138, 24 bitop3:0x36
	v_or_b32_e32 v6, 24, v139
	v_lshlrev_b32_e32 v3, 4, v3
	v_lshlrev_b32_e32 v2, 8, v6
	v_and_b32_e32 v3, 0xf0, v3
	v_add3_u32 v2, s38, v2, v3
	ds_read_b128 v[2:5], v2
	v_lshlrev_b32_e32 v128, 13, v6
	v_lshl_add_u64 v[6:7], v[0:1], 0, v[128:129]
	s_waitcnt lgkmcnt(0)
	global_store_dwordx4 v[6:7], v[2:5], off
	s_nop 1
	v_bitop3_b32 v3, v139, v138, 28 bitop3:0x36
	v_or_b32_e32 v6, 28, v139
	v_lshlrev_b32_e32 v3, 4, v3
	v_lshlrev_b32_e32 v2, 8, v6
	v_and_b32_e32 v3, 0xf0, v3
	v_add3_u32 v2, s38, v2, v3
	ds_read_b128 v[2:5], v2
	v_lshlrev_b32_e32 v128, 13, v6
	v_lshl_add_u64 v[6:7], v[0:1], 0, v[128:129]
	s_waitcnt lgkmcnt(0)
	global_store_dwordx4 v[6:7], v[2:5], off
	v_or_b32_e32 v6, 32, v139
	s_nop 0
	v_lshlrev_b32_e32 v2, 8, v6
	v_add3_u32 v2, s38, v2, v8
	ds_read_b128 v[2:5], v2
	v_lshlrev_b32_e32 v128, 13, v6
	v_lshl_add_u64 v[6:7], v[0:1], 0, v[128:129]
	s_waitcnt lgkmcnt(0)
	global_store_dwordx4 v[6:7], v[2:5], off
	s_nop 1
	v_bitop3_b32 v3, v139, v138, 36 bitop3:0x36
	v_or_b32_e32 v6, 36, v139
	v_lshlrev_b32_e32 v3, 4, v3
	v_lshlrev_b32_e32 v2, 8, v6
	v_and_b32_e32 v3, 0xf0, v3
	v_add3_u32 v2, s38, v2, v3
	ds_read_b128 v[2:5], v2
	v_lshlrev_b32_e32 v128, 13, v6
	v_lshl_add_u64 v[6:7], v[0:1], 0, v[128:129]
	s_waitcnt lgkmcnt(0)
	global_store_dwordx4 v[6:7], v[2:5], off
	s_nop 1
	v_bitop3_b32 v3, v139, v138, 40 bitop3:0x36
	v_or_b32_e32 v6, 40, v139
	v_lshlrev_b32_e32 v3, 4, v3
	v_lshlrev_b32_e32 v2, 8, v6
	v_and_b32_e32 v3, 0xf0, v3
	v_add3_u32 v2, s38, v2, v3
	ds_read_b128 v[2:5], v2
	v_lshlrev_b32_e32 v128, 13, v6
	v_lshl_add_u64 v[6:7], v[0:1], 0, v[128:129]
	s_waitcnt lgkmcnt(0)
	global_store_dwordx4 v[6:7], v[2:5], off
	s_nop 1
	v_bitop3_b32 v3, v139, v138, 44 bitop3:0x36
	v_or_b32_e32 v6, 44, v139
	v_lshlrev_b32_e32 v3, 4, v3
	v_lshlrev_b32_e32 v2, 8, v6
	v_and_b32_e32 v3, 0xf0, v3
	v_add3_u32 v2, s38, v2, v3
	ds_read_b128 v[2:5], v2
	v_lshlrev_b32_e32 v128, 13, v6
	v_lshl_add_u64 v[6:7], v[0:1], 0, v[128:129]
	s_waitcnt lgkmcnt(0)
	global_store_dwordx4 v[6:7], v[2:5], off
	v_or_b32_e32 v6, 48, v139
	s_nop 0
	v_lshlrev_b32_e32 v2, 8, v6
	v_add3_u32 v2, s38, v2, v8
	ds_read_b128 v[2:5], v2
	v_lshlrev_b32_e32 v128, 13, v6
	v_lshl_add_u64 v[6:7], v[0:1], 0, v[128:129]
	s_waitcnt lgkmcnt(0)
	global_store_dwordx4 v[6:7], v[2:5], off
	s_nop 1
	v_bitop3_b32 v3, v139, v138, 52 bitop3:0x36
	v_or_b32_e32 v6, 52, v139
	v_lshlrev_b32_e32 v3, 4, v3
	v_lshlrev_b32_e32 v2, 8, v6
	v_and_b32_e32 v3, 0xf0, v3
	v_add3_u32 v2, s38, v2, v3
	ds_read_b128 v[2:5], v2
	v_lshlrev_b32_e32 v128, 13, v6
	v_lshl_add_u64 v[6:7], v[0:1], 0, v[128:129]
	s_waitcnt lgkmcnt(0)
	global_store_dwordx4 v[6:7], v[2:5], off
	s_nop 1
	v_bitop3_b32 v3, v139, v138, 56 bitop3:0x36
	v_or_b32_e32 v6, 56, v139
	v_lshlrev_b32_e32 v3, 4, v3
	v_lshlrev_b32_e32 v2, 8, v6
	v_and_b32_e32 v3, 0xf0, v3
	v_add3_u32 v2, s38, v2, v3
	ds_read_b128 v[2:5], v2
	v_lshlrev_b32_e32 v128, 13, v6
	v_lshl_add_u64 v[6:7], v[0:1], 0, v[128:129]
	s_waitcnt lgkmcnt(0)
	global_store_dwordx4 v[6:7], v[2:5], off
	s_nop 1
	v_bitop3_b32 v4, v139, v138, 60 bitop3:0x36
	v_or_b32_e32 v3, 60, v139
	v_lshlrev_b32_e32 v4, 4, v4
	v_lshlrev_b32_e32 v2, 8, v3
	v_and_b32_e32 v4, 0xf0, v4
	v_add3_u32 v2, s38, v2, v4
	v_lshlrev_b32_e32 v128, 12, v3
	s_branch .LBB0_803

.LBB0_1074:
	s_lshl_b32 s4, s14, 6
	s_and_b32 s4, s4, 0x1c0
	s_ashr_i32 s5, s14, 3
	s_add_i32 s4, s4, s5
	s_lshr_b32 s5, s4, 30
	s_add_i32 s5, s4, s5
	s_and_b32 s6, s5, 0xfffffc
	v_mov_b32_e32 v138, v157
	v_mov_b32_e32 v10, v157
	s_sub_i32 s7, s4, s6
	s_lshl_b32 s4, s5, 6
	v_readfirstlane_b32 s15, v10
	s_lshl_b32 s5, s7, 8
	s_ashr_i32 s7, s15, 6
	s_and_b32 s4, s4, 0xffffff00
	s_lshl_b32 s30, s7, 2
	s_add_i32 s37, s5, 0xffffff00
	s_cmp_lt_i32 s7, 4
	s_cselect_b64 s[8:9], -1, 0
	s_and_b32 s38, s15, 0xffffffc0
	s_and_b64 s[10:11], s[8:9], exec
	s_cselect_b32 s10, s4, s37
	s_add_i32 s10, s10, s38
	s_and_b64 s[8:9], s[8:9], exec
	s_cselect_b32 s18, s59, s13
	s_cselect_b32 s19, s58, s12
	s_ashr_i32 s11, s10, 31
	s_lshl_b64 s[8:9], s[10:11], 11
	s_add_u32 s8, s19, s8
	s_addc_u32 s9, s18, s9
	s_or_b32 s18, s30, 1
	s_cmp_lt_i32 s18, 16
	s_cselect_b64 s[10:11], -1, 0
	s_lshl_b32 s28, s18, 4
	s_and_b64 s[18:19], s[10:11], exec
	s_cselect_b32 s39, s4, s37
	s_add_i32 s18, s39, s28
	s_and_b64 s[10:11], s[10:11], exec
	s_cselect_b32 s40, s59, s13
	s_cselect_b32 s41, s58, s12
	s_ashr_i32 s19, s18, 31
	s_lshl_b64 s[10:11], s[18:19], 11
	s_add_u32 s10, s41, s10
	s_addc_u32 s11, s40, s11
	s_or_b32 s28, s30, 2
	s_cmp_lt_i32 s28, 16
	s_cselect_b64 s[18:19], -1, 0
	s_lshl_b32 s31, s28, 4
	s_and_b64 s[28:29], s[18:19], exec
	s_cselect_b32 s42, s4, s37
	s_add_i32 s28, s42, s31
	s_and_b64 s[18:19], s[18:19], exec
	s_cselect_b32 s43, s59, s13
	s_cselect_b32 s44, s58, s12
	s_ashr_i32 s29, s28, 31
	s_lshl_b64 s[18:19], s[28:29], 11
	s_add_u32 s18, s44, s18
	s_addc_u32 s19, s43, s19
	s_or_b32 s30, s30, 3
	s_cmp_lt_i32 s30, 16
	s_cselect_b64 s[28:29], -1, 0
	s_lshl_b32 s45, s30, 4
	s_and_b64 s[30:31], s[28:29], exec
	s_cselect_b32 s37, s4, s37
	s_add_i32 s30, s37, s45
	s_and_b64 s[28:29], s[28:29], exec
	v_lshrrev_b32_e32 v11, 4, v10
	s_cselect_b32 s45, s59, s13
	s_cselect_b32 s46, s58, s12
	s_ashr_i32 s31, s30, 31
	v_sub_u32_e32 v1, 0, v11
	s_lshl_b64 s[28:29], s[30:31], 11
	v_lshlrev_b32_e32 v0, 9, v10
	v_xor_b32_e32 v1, v10, v1
	s_add_u32 s28, s46, s28
	v_and_b32_e32 v0, 0x7800, v0
	v_lshlrev_b32_e32 v1, 4, v1
	s_addc_u32 s29, s45, s29
	s_lshl_b32 s7, s7, 12
	v_and_or_b32 v128, v1, 48, v0
	s_mov_b32 m0, s7
	v_lshl_add_u64 v[0:1], s[8:9], 0, v[128:129]
	global_load_lds_dwordx4 v128, s[8:9]
	s_or_b32 m0, s7, 0x400
	v_lshl_add_u64 v[2:3], s[10:11], 0, v[128:129]
	global_load_lds_dwordx4 v128, s[10:11]
	s_or_b32 m0, s7, 0x800
	v_lshl_add_u64 v[8:9], v[0:1], 0, 64
	global_load_lds_dwordx4 v128, s[18:19]
	s_or_b32 m0, s7, 0xc00
	v_lshl_add_u64 v[4:5], s[18:19], 0, v[128:129]
	global_load_lds_dwordx4 v128, s[28:29]
	s_add_i32 m0, s7, 0x8000
	v_lshl_add_u64 v[6:7], s[28:29], 0, v[128:129]
	global_load_lds_dwordx4 v[8:9], off
	v_lshl_add_u64 v[8:9], v[2:3], 0, 64
	s_add_i32 m0, s7, 0x8400
	v_lshl_add_u64 v[2:3], v[2:3], 0, s[88:89]
	global_load_lds_dwordx4 v[8:9], off
	v_lshl_add_u64 v[8:9], v[4:5], 0, 64
	s_add_i32 m0, s7, 0x8800
	s_lshr_b32 s8, s15, 1
	global_load_lds_dwordx4 v[8:9], off
	v_lshl_add_u64 v[8:9], v[6:7], 0, 64
	s_add_i32 m0, s7, 0x8c00
	v_and_b32_e32 v12, 15, v10
	global_load_lds_dwordx4 v[8:9], off
	s_add_i32 m0, s7, 0x10000
	v_lshl_add_u64 v[8:9], v[0:1], 0, s[88:89]
	global_load_lds_dwordx4 v[8:9], off
	s_add_i32 m0, s7, 0x10400
	s_and_b32 s8, s8, 0x3ffff80
	global_load_lds_dwordx4 v[2:3], off
	v_lshl_add_u64 v[2:3], v[4:5], 0, s[88:89]
	s_add_i32 m0, s7, 0x10800
	v_lshl_add_u64 v[136:137], v[0:1], 0, s[78:79]
	global_load_lds_dwordx4 v[2:3], off
	v_lshl_add_u64 v[2:3], v[6:7], 0, s[88:89]
	s_add_i32 m0, s7, 0x10c00
	v_mov_b32_e32 v0, 0
	global_load_lds_dwordx4 v[2:3], off
	v_lshrrev_b32_e32 v2, 2, v10
	v_sub_u32_e32 v2, 0, v2
	v_bitop3_b32 v2, v11, 3, v2 bitop3:0x48
	v_or_b32_e32 v3, s8, v12
	v_lshlrev_b32_e32 v2, 4, v2
	s_and_b32 s8, s15, 0xc0
	v_lshl_or_b32 v139, v3, 6, v2
	v_or_b32_e32 v3, s8, v12
	s_add_i32 s8, s37, s38
	s_ashr_i32 s9, s8, 31
	s_lshl_b64 s[8:9], s[8:9], 11
	s_add_u32 s8, s46, s8
	v_lshlrev_b32_e32 v3, 6, v3
	s_addc_u32 s9, s45, s9
	v_or3_b32 v140, v2, v3, s68
	v_lshl_add_u64 v[2:3], s[8:9], 0, v[128:129]
	s_add_i32 s8, s42, s38
	s_ashr_i32 s9, s8, 31
	s_lshl_b64 s[8:9], s[8:9], 11
	s_add_u32 s8, s44, s8
	s_addc_u32 s9, s43, s9
	v_lshl_add_u64 v[130:131], v[2:3], 0, s[92:93]
	v_lshl_add_u64 v[2:3], s[8:9], 0, v[128:129]
	s_add_i32 s8, s39, s38
	s_ashr_i32 s9, s8, 31
	s_lshl_b64 s[8:9], s[8:9], 11
	s_add_u32 s8, s41, s8
	s_addc_u32 s9, s40, s9
	v_lshl_add_u64 v[132:133], v[2:3], 0, s[94:95]
	v_lshl_add_u64 v[2:3], s[8:9], 0, v[128:129]
	v_readfirstlane_b32 s6, v138
	v_lshl_add_u64 v[134:135], v[2:3], 0, s[96:97]
	s_mov_b32 s8, 0x18000
	v_mov_b32_e32 v1, v0
	v_mov_b32_e32 v2, v0
	v_mov_b32_e32 v3, v0
	v_mov_b32_e32 v4, v0
	v_mov_b32_e32 v5, v0
	v_mov_b32_e32 v6, v0
	v_mov_b32_e32 v7, v0
	v_mov_b32_e32 v8, v0
	v_mov_b32_e32 v9, v0
	v_mov_b32_e32 v10, v0
	v_mov_b32_e32 v11, v0
	v_mov_b32_e32 v12, v0
	v_mov_b32_e32 v13, v0
	v_mov_b32_e32 v14, v0
	v_mov_b32_e32 v15, v0
	v_mov_b32_e32 v16, v0
	v_mov_b32_e32 v17, v0
	v_mov_b32_e32 v18, v0
	v_mov_b32_e32 v19, v0
	v_mov_b32_e32 v20, v0
	v_mov_b32_e32 v21, v0
	v_mov_b32_e32 v22, v0
	v_mov_b32_e32 v23, v0
	v_mov_b32_e32 v24, v0
	v_mov_b32_e32 v25, v0
	v_mov_b32_e32 v26, v0
	v_mov_b32_e32 v27, v0
	v_mov_b32_e32 v28, v0
	v_mov_b32_e32 v29, v0
	v_mov_b32_e32 v30, v0
	v_mov_b32_e32 v31, v0
	v_mov_b32_e32 v32, v0
	v_mov_b32_e32 v33, v0
	v_mov_b32_e32 v34, v0
	v_mov_b32_e32 v35, v0
	v_mov_b32_e32 v36, v0
	v_mov_b32_e32 v37, v0
	v_mov_b32_e32 v38, v0
	v_mov_b32_e32 v39, v0
	v_mov_b32_e32 v40, v0
	v_mov_b32_e32 v41, v0
	v_mov_b32_e32 v42, v0
	v_mov_b32_e32 v43, v0
	v_mov_b32_e32 v44, v0
	v_mov_b32_e32 v45, v0
	v_mov_b32_e32 v46, v0
	v_mov_b32_e32 v47, v0
	v_mov_b32_e32 v48, v0
	v_mov_b32_e32 v49, v0
	v_mov_b32_e32 v50, v0
	v_mov_b32_e32 v51, v0
	v_mov_b32_e32 v52, v0
	v_mov_b32_e32 v53, v0
	v_mov_b32_e32 v54, v0
	v_mov_b32_e32 v55, v0
	v_mov_b32_e32 v56, v0
	v_mov_b32_e32 v57, v0
	v_mov_b32_e32 v58, v0
	v_mov_b32_e32 v59, v0
	v_mov_b32_e32 v60, v0
	v_mov_b32_e32 v61, v0
	v_mov_b32_e32 v62, v0
	v_mov_b32_e32 v63, v0
	v_mov_b32_e32 v64, v0
	v_mov_b32_e32 v65, v0
	v_mov_b32_e32 v66, v0
	v_mov_b32_e32 v67, v0
	v_mov_b32_e32 v68, v0
	v_mov_b32_e32 v69, v0
	v_mov_b32_e32 v70, v0
	v_mov_b32_e32 v71, v0
	v_mov_b32_e32 v72, v0
	v_mov_b32_e32 v73, v0
	v_mov_b32_e32 v74, v0
	v_mov_b32_e32 v75, v0
	v_mov_b32_e32 v76, v0
	v_mov_b32_e32 v77, v0
	v_mov_b32_e32 v78, v0
	v_mov_b32_e32 v79, v0
	v_mov_b32_e32 v80, v0
	v_mov_b32_e32 v81, v0
	v_mov_b32_e32 v82, v0
	v_mov_b32_e32 v83, v0
	v_mov_b32_e32 v84, v0
	v_mov_b32_e32 v85, v0
	v_mov_b32_e32 v86, v0
	v_mov_b32_e32 v87, v0
	v_mov_b32_e32 v88, v0
	v_mov_b32_e32 v89, v0
	v_mov_b32_e32 v90, v0
	v_mov_b32_e32 v91, v0
	v_mov_b32_e32 v92, v0
	v_mov_b32_e32 v93, v0
	v_mov_b32_e32 v94, v0
	v_mov_b32_e32 v95, v0
	v_mov_b32_e32 v96, v0
	v_mov_b32_e32 v97, v0
	v_mov_b32_e32 v98, v0
	v_mov_b32_e32 v99, v0
	v_mov_b32_e32 v100, v0
	v_mov_b32_e32 v101, v0
	v_mov_b32_e32 v102, v0
	v_mov_b32_e32 v103, v0
	v_mov_b32_e32 v104, v0
	v_mov_b32_e32 v105, v0
	v_mov_b32_e32 v106, v0
	v_mov_b32_e32 v107, v0
	v_mov_b32_e32 v108, v0
	v_mov_b32_e32 v109, v0
	v_mov_b32_e32 v110, v0
	v_mov_b32_e32 v111, v0
	v_mov_b32_e32 v112, v0
	v_mov_b32_e32 v113, v0
	v_mov_b32_e32 v114, v0
	v_mov_b32_e32 v115, v0
	v_mov_b32_e32 v116, v0
	v_mov_b32_e32 v117, v0
	v_mov_b32_e32 v118, v0
	v_mov_b32_e32 v119, v0
	v_mov_b32_e32 v120, v0
	v_mov_b32_e32 v121, v0
	v_mov_b32_e32 v122, v0
	v_mov_b32_e32 v123, v0
	v_mov_b32_e32 v124, v0
	v_mov_b32_e32 v125, v0
	v_mov_b32_e32 v126, v0
	v_mov_b32_e32 v127, v0
	s_add_i32 s9, s8, 0xfffe8000
	s_and_b32 s10, s8, 0x18000
	s_waitcnt vmcnt(8)
	s_barrier
	s_and_b32 s9, s9, 0x18000
	s_add_i32 s10, s7, s10
	v_add_u32_e32 v128, s9, v139
	v_or_b32_e32 v141, s9, v140
	s_add_i32 s15, s10, 0x400
	s_add_i32 s11, s10, 0x800
	s_add_i32 s9, s10, 0xc00
	s_add_i32 s8, s8, 0x8000
	s_cmp_eq_u32 s8, 0x100000
	ds_read_b128 v[174:177], v128
	ds_read_b128 v[142:145], v141
	ds_read_b128 v[158:161], v141 offset:1024
	ds_read_b128 v[162:165], v141 offset:2048
	ds_read_b128 v[166:169], v141 offset:3072
	ds_read_b128 v[178:181], v128 offset:1024
	ds_read_b128 v[182:185], v128 offset:2048
	ds_read_b128 v[186:189], v128 offset:3072
	ds_read_b128 v[232:235], v128 offset:4096
	ds_read_b128 v[236:239], v128 offset:5120
	ds_read_b128 v[240:243], v128 offset:6144
	ds_read_b128 v[244:247], v128 offset:7168
	s_mov_b32 m0, s10
	s_nop 0
	global_load_lds_dwordx4 v[136:137], off
	v_lshl_add_u64 v[136:137], v[136:137], 0, 64
	s_mov_b32 m0, s15
	s_nop 0
	global_load_lds_dwordx4 v[134:135], off
	v_lshl_add_u64 v[134:135], v[134:135], 0, 64
	s_mov_b32 m0, s11
	s_nop 0
	global_load_lds_dwordx4 v[132:133], off
	v_lshl_add_u64 v[132:133], v[132:133], 0, 64
	s_mov_b32 m0, s9
	s_nop 0
	global_load_lds_dwordx4 v[130:131], off
	v_lshl_add_u64 v[130:131], v[130:131], 0, 64
	s_waitcnt lgkmcnt(4)
	v_mfma_f32_16x16x32_bf16 v[124:127], v[142:145], v[174:177], v[124:127]
	v_mfma_f32_16x16x32_bf16 v[120:123], v[158:161], v[174:177], v[120:123]
	v_mfma_f32_16x16x32_bf16 v[116:119], v[162:165], v[174:177], v[116:119]
	v_mfma_f32_16x16x32_bf16 v[112:115], v[166:169], v[174:177], v[112:115]
	v_mfma_f32_16x16x32_bf16 v[108:111], v[142:145], v[178:181], v[108:111]
	v_mfma_f32_16x16x32_bf16 v[104:107], v[158:161], v[178:181], v[104:107]
	v_mfma_f32_16x16x32_bf16 v[100:103], v[162:165], v[178:181], v[100:103]
	v_mfma_f32_16x16x32_bf16 v[96:99], v[166:169], v[178:181], v[96:99]
	v_mfma_f32_16x16x32_bf16 v[92:95], v[142:145], v[182:185], v[92:95]
	v_mfma_f32_16x16x32_bf16 v[88:91], v[158:161], v[182:185], v[88:91]
	v_mfma_f32_16x16x32_bf16 v[84:87], v[162:165], v[182:185], v[84:87]
	v_mfma_f32_16x16x32_bf16 v[80:83], v[166:169], v[182:185], v[80:83]
	v_mfma_f32_16x16x32_bf16 v[76:79], v[142:145], v[186:189], v[76:79]
	v_mfma_f32_16x16x32_bf16 v[72:75], v[158:161], v[186:189], v[72:75]
	v_mfma_f32_16x16x32_bf16 v[68:71], v[162:165], v[186:189], v[68:71]
	v_mfma_f32_16x16x32_bf16 v[64:67], v[166:169], v[186:189], v[64:67]
.Lgsk4_loop:
	s_add_i32 s9, s8, 0xfffe8000
	s_and_b32 s10, s8, 0x18000
	s_waitcnt vmcnt(8) lgkmcnt(0)
	s_barrier
	s_and_b32 s9, s9, 0x18000
	s_add_i32 s10, s7, s10
	v_add_u32_e32 v128, s9, v139
	v_or_b32_e32 v141, s9, v140
	s_add_i32 s15, s10, 0x400
	s_add_i32 s11, s10, 0x800
	s_add_i32 s9, s10, 0xc00
	s_add_i32 s8, s8, 0x8000
	s_cmp_eq_u32 s8, 0x100000
	ds_read_b128 v[174:177], v128
	ds_read_b128 v[178:181], v128 offset:1024
	ds_read_b128 v[182:185], v128 offset:2048
	ds_read_b128 v[186:189], v128 offset:3072
	v_mfma_f32_16x16x32_bf16 v[60:63], v[142:145], v[232:235], v[60:63]
	v_mfma_f32_16x16x32_bf16 v[44:47], v[142:145], v[236:239], v[44:47]
	v_mfma_f32_16x16x32_bf16 v[28:31], v[142:145], v[240:243], v[28:31]
	s_mov_b32 m0, s10
	v_mfma_f32_16x16x32_bf16 v[12:15], v[142:145], v[244:247], v[12:15]
	global_load_lds_dwordx4 v[136:137], off
	v_lshl_add_u64 v[136:137], v[136:137], 0, 64
	v_mfma_f32_16x16x32_bf16 v[56:59], v[158:161], v[232:235], v[56:59]
	ds_read_b128 v[142:145], v141
	v_mfma_f32_16x16x32_bf16 v[40:43], v[158:161], v[236:239], v[40:43]
	v_mfma_f32_16x16x32_bf16 v[24:27], v[158:161], v[240:243], v[24:27]
	s_mov_b32 m0, s15
	v_mfma_f32_16x16x32_bf16 v[8:11], v[158:161], v[244:247], v[8:11]
	global_load_lds_dwordx4 v[134:135], off
	v_lshl_add_u64 v[134:135], v[134:135], 0, 64
	v_mfma_f32_16x16x32_bf16 v[52:55], v[162:165], v[232:235], v[52:55]
	ds_read_b128 v[158:161], v141 offset:1024
	v_mfma_f32_16x16x32_bf16 v[36:39], v[162:165], v[236:239], v[36:39]
	v_mfma_f32_16x16x32_bf16 v[20:23], v[162:165], v[240:243], v[20:23]
	s_mov_b32 m0, s11
	v_mfma_f32_16x16x32_bf16 v[4:7], v[162:165], v[244:247], v[4:7]
	global_load_lds_dwordx4 v[132:133], off
	v_lshl_add_u64 v[132:133], v[132:133], 0, 64
	v_mfma_f32_16x16x32_bf16 v[48:51], v[166:169], v[232:235], v[48:51]
	ds_read_b128 v[162:165], v141 offset:2048
	v_mfma_f32_16x16x32_bf16 v[32:35], v[166:169], v[236:239], v[32:35]
	v_mfma_f32_16x16x32_bf16 v[16:19], v[166:169], v[240:243], v[16:19]
	s_mov_b32 m0, s9
	v_mfma_f32_16x16x32_bf16 v[0:3], v[166:169], v[244:247], v[0:3]
	global_load_lds_dwordx4 v[130:131], off
	v_lshl_add_u64 v[130:131], v[130:131], 0, 64
	s_waitcnt lgkmcnt(2)
	v_mfma_f32_16x16x32_bf16 v[124:127], v[142:145], v[174:177], v[124:127]
	ds_read_b128 v[166:169], v141 offset:3072
	v_mfma_f32_16x16x32_bf16 v[108:111], v[142:145], v[178:181], v[108:111]
	ds_read_b128 v[232:235], v128 offset:4096
	ds_read_b128 v[236:239], v128 offset:5120
	v_mfma_f32_16x16x32_bf16 v[92:95], v[142:145], v[182:185], v[92:95]
	ds_read_b128 v[240:243], v128 offset:6144
	ds_read_b128 v[244:247], v128 offset:7168
	v_mfma_f32_16x16x32_bf16 v[76:79], v[142:145], v[186:189], v[76:79]
	s_waitcnt lgkmcnt(6)
	v_mfma_f32_16x16x32_bf16 v[120:123], v[158:161], v[174:177], v[120:123]
	v_mfma_f32_16x16x32_bf16 v[104:107], v[158:161], v[178:181], v[104:107]
	v_mfma_f32_16x16x32_bf16 v[88:91], v[158:161], v[182:185], v[88:91]
	v_mfma_f32_16x16x32_bf16 v[72:75], v[158:161], v[186:189], v[72:75]
	s_waitcnt lgkmcnt(5)
	v_mfma_f32_16x16x32_bf16 v[116:119], v[162:165], v[174:177], v[116:119]
	v_mfma_f32_16x16x32_bf16 v[100:103], v[162:165], v[178:181], v[100:103]
	v_mfma_f32_16x16x32_bf16 v[84:87], v[162:165], v[182:185], v[84:87]
	v_mfma_f32_16x16x32_bf16 v[68:71], v[162:165], v[186:189], v[68:71]
	s_waitcnt lgkmcnt(4)
	v_mfma_f32_16x16x32_bf16 v[112:115], v[166:169], v[174:177], v[112:115]
	v_mfma_f32_16x16x32_bf16 v[96:99], v[166:169], v[178:181], v[96:99]
	v_mfma_f32_16x16x32_bf16 v[80:83], v[166:169], v[182:185], v[80:83]
	v_mfma_f32_16x16x32_bf16 v[64:67], v[166:169], v[186:189], v[64:67]
	s_cbranch_scc0 .Lgsk4_loop
	s_waitcnt lgkmcnt(0)
	v_mfma_f32_16x16x32_bf16 v[60:63], v[142:145], v[232:235], v[60:63]
	v_mfma_f32_16x16x32_bf16 v[44:47], v[142:145], v[236:239], v[44:47]
	v_mfma_f32_16x16x32_bf16 v[28:31], v[142:145], v[240:243], v[28:31]
	v_mfma_f32_16x16x32_bf16 v[12:15], v[142:145], v[244:247], v[12:15]
	v_mfma_f32_16x16x32_bf16 v[56:59], v[158:161], v[232:235], v[56:59]
	v_mfma_f32_16x16x32_bf16 v[40:43], v[158:161], v[236:239], v[40:43]
	v_mfma_f32_16x16x32_bf16 v[24:27], v[158:161], v[240:243], v[24:27]
	v_mfma_f32_16x16x32_bf16 v[8:11], v[158:161], v[244:247], v[8:11]
	v_mfma_f32_16x16x32_bf16 v[52:55], v[162:165], v[232:235], v[52:55]
	v_mfma_f32_16x16x32_bf16 v[36:39], v[162:165], v[236:239], v[36:39]
	v_mfma_f32_16x16x32_bf16 v[20:23], v[162:165], v[240:243], v[20:23]
	v_mfma_f32_16x16x32_bf16 v[4:7], v[162:165], v[244:247], v[4:7]
	v_mfma_f32_16x16x32_bf16 v[48:51], v[166:169], v[232:235], v[48:51]
	v_mfma_f32_16x16x32_bf16 v[32:35], v[166:169], v[236:239], v[32:35]
	v_mfma_f32_16x16x32_bf16 v[16:19], v[166:169], v[240:243], v[16:19]
	v_mfma_f32_16x16x32_bf16 v[0:3], v[166:169], v[244:247], v[0:3]
	s_waitcnt vmcnt(8)
	s_barrier
	v_add_u32_e32 v128, 0x8000, v139
	v_or_b32_e32 v141, 0x8000, v140
	ds_read_b128 v[130:133], v141
	ds_read_b128 v[134:137], v141 offset:1024
	ds_read_b128 v[142:145], v141 offset:2048
	ds_read_b128 v[158:161], v141 offset:3072
	ds_read_b128 v[162:165], v128
	ds_read_b128 v[166:169], v128 offset:1024
	ds_read_b128 v[174:177], v128 offset:2048
	ds_read_b128 v[178:181], v128 offset:3072
	s_lshl_b32 s8, s6, 8
	s_waitcnt lgkmcnt(0)
	s_and_b32 s15, s8, 0xffffc000
	v_mfma_f32_16x16x32_bf16 v[124:127], v[130:133], v[162:165], v[124:127]
	s_ashr_i32 s7, s6, 1
	s_and_b32 s7, s7, 0xffffff80
	s_and_b32 s6, s6, 0xc0
	v_mfma_f32_16x16x32_bf16 v[120:123], v[134:137], v[162:165], v[120:123]
	s_add_i32 s8, s4, s7
	s_or_b32 s4, s5, s6
	s_ashr_i32 s10, s4, 6
	v_mfma_f32_16x16x32_bf16 v[182:185], v[142:145], v[162:165], v[116:119]
	s_ashr_i32 s11, s10, 31
	v_mfma_f32_16x16x32_bf16 v[112:115], v[158:161], v[162:165], v[112:115]
	v_mfma_f32_16x16x32_bf16 v[108:111], v[130:133], v[166:169], v[108:111]
	v_mfma_f32_16x16x32_bf16 v[104:107], v[134:137], v[166:169], v[104:107]
	v_mfma_f32_16x16x32_bf16 v[100:103], v[142:145], v[166:169], v[100:103]
	v_mfma_f32_16x16x32_bf16 v[96:99], v[158:161], v[166:169], v[96:99]
	v_mfma_f32_16x16x32_bf16 v[92:95], v[130:133], v[174:177], v[92:95]
	v_mfma_f32_16x16x32_bf16 v[88:91], v[134:137], v[174:177], v[88:91]
	v_mfma_f32_16x16x32_bf16 v[84:87], v[142:145], v[174:177], v[84:87]
	v_mfma_f32_16x16x32_bf16 v[80:83], v[158:161], v[174:177], v[80:83]
	ds_read_b128 v[116:119], v128 offset:4096
	ds_read_b128 v[162:165], v128 offset:5120
	ds_read_b128 v[166:169], v128 offset:6144
	ds_read_b128 v[174:177], v128 offset:7168
	s_waitcnt lgkmcnt(0)
	s_waitcnt vmcnt(4)
	s_barrier
	v_mfma_f32_16x16x32_bf16 v[76:79], v[130:133], v[178:181], v[76:79]
	v_mfma_f32_16x16x32_bf16 v[72:75], v[134:137], v[178:181], v[72:75]
	v_mfma_f32_16x16x32_bf16 v[68:71], v[142:145], v[178:181], v[68:71]
	v_mfma_f32_16x16x32_bf16 v[64:67], v[158:161], v[178:181], v[64:67]
	v_mfma_f32_16x16x32_bf16 v[60:63], v[130:133], v[116:119], v[60:63]
	v_mfma_f32_16x16x32_bf16 v[56:59], v[134:137], v[116:119], v[56:59]
	v_mfma_f32_16x16x32_bf16 v[52:55], v[142:145], v[116:119], v[52:55]
	v_mfma_f32_16x16x32_bf16 v[48:51], v[158:161], v[116:119], v[48:51]
	v_add_u32_e32 v117, 0x10000, v139
	v_or_b32_e32 v119, 0x10000, v140
	v_and_b32_e32 v116, 15, v138
	v_mfma_f32_16x16x32_bf16 v[44:47], v[130:133], v[162:165], v[44:47]
	v_and_b32_e32 v118, 63, v138
	v_mfma_f32_16x16x32_bf16 v[40:43], v[134:137], v[162:165], v[40:43]
	v_mfma_f32_16x16x32_bf16 v[36:39], v[142:145], v[162:165], v[36:39]
	v_mfma_f32_16x16x32_bf16 v[32:35], v[158:161], v[162:165], v[32:35]
	v_mfma_f32_16x16x32_bf16 v[28:31], v[130:133], v[166:169], v[28:31]
	v_mfma_f32_16x16x32_bf16 v[24:27], v[134:137], v[166:169], v[24:27]
	v_mfma_f32_16x16x32_bf16 v[20:23], v[142:145], v[166:169], v[20:23]
	v_mfma_f32_16x16x32_bf16 v[16:19], v[158:161], v[166:169], v[16:19]
	v_mfma_f32_16x16x32_bf16 v[12:15], v[130:133], v[174:177], v[12:15]
	v_mfma_f32_16x16x32_bf16 v[8:11], v[134:137], v[174:177], v[8:11]
	v_mfma_f32_16x16x32_bf16 v[4:7], v[142:145], v[174:177], v[4:7]
	v_mfma_f32_16x16x32_bf16 v[0:3], v[158:161], v[174:177], v[0:3]
	ds_read_b128 v[130:133], v119
	ds_read_b128 v[134:137], v119 offset:1024
	ds_read_b128 v[142:145], v119 offset:2048
	ds_read_b128 v[158:161], v119 offset:3072
	ds_read_b128 v[162:165], v117
	ds_read_b128 v[166:169], v117 offset:1024
	ds_read_b128 v[174:177], v117 offset:2048
	ds_read_b128 v[178:181], v117 offset:3072
	v_or_b32_e32 v119, 0x18000, v140
	s_waitcnt lgkmcnt(0)
	s_nop 0
	v_mfma_f32_16x16x32_bf16 v[124:127], v[130:133], v[162:165], v[124:127]
	v_mfma_f32_16x16x32_bf16 v[120:123], v[134:137], v[162:165], v[120:123]
	v_mfma_f32_16x16x32_bf16 v[182:185], v[142:145], v[162:165], v[182:185]
	v_mfma_f32_16x16x32_bf16 v[112:115], v[158:161], v[162:165], v[112:115]
	v_mfma_f32_16x16x32_bf16 v[108:111], v[130:133], v[166:169], v[108:111]
	v_mfma_f32_16x16x32_bf16 v[104:107], v[134:137], v[166:169], v[104:107]
	v_mfma_f32_16x16x32_bf16 v[100:103], v[142:145], v[166:169], v[100:103]
	v_mfma_f32_16x16x32_bf16 v[162:165], v[158:161], v[166:169], v[96:99]
	v_mfma_f32_16x16x32_bf16 v[92:95], v[130:133], v[174:177], v[92:95]
	v_mfma_f32_16x16x32_bf16 v[88:91], v[134:137], v[174:177], v[88:91]
	v_mfma_f32_16x16x32_bf16 v[84:87], v[142:145], v[174:177], v[84:87]
	v_mfma_f32_16x16x32_bf16 v[80:83], v[158:161], v[174:177], v[80:83]
	v_mfma_f32_16x16x32_bf16 v[76:79], v[130:133], v[178:181], v[76:79]
	v_mfma_f32_16x16x32_bf16 v[72:75], v[134:137], v[178:181], v[72:75]
	v_mfma_f32_16x16x32_bf16 v[68:71], v[142:145], v[178:181], v[68:71]
	v_mfma_f32_16x16x32_bf16 v[64:67], v[158:161], v[178:181], v[64:67]
	ds_read_b128 v[96:99], v117 offset:4096
	ds_read_b128 v[166:169], v117 offset:5120
	ds_read_b128 v[174:177], v117 offset:6144
	ds_read_b128 v[178:181], v117 offset:7168
	s_waitcnt lgkmcnt(0)
	s_waitcnt vmcnt(0)
	s_barrier
	v_mfma_f32_16x16x32_bf16 v[60:63], v[130:133], v[96:99], v[60:63]
	v_add_u32_e32 v117, 0x18000, v139
	v_mfma_f32_16x16x32_bf16 v[56:59], v[134:137], v[96:99], v[56:59]
	v_mfma_f32_16x16x32_bf16 v[52:55], v[142:145], v[96:99], v[52:55]
	v_mfma_f32_16x16x32_bf16 v[48:51], v[158:161], v[96:99], v[48:51]
	v_mfma_f32_16x16x32_bf16 v[44:47], v[130:133], v[166:169], v[44:47]
	v_mfma_f32_16x16x32_bf16 v[40:43], v[134:137], v[166:169], v[40:43]
	v_mfma_f32_16x16x32_bf16 v[36:39], v[142:145], v[166:169], v[36:39]
	v_mfma_f32_16x16x32_bf16 v[32:35], v[158:161], v[166:169], v[32:35]
	v_mfma_f32_16x16x32_bf16 v[28:31], v[130:133], v[174:177], v[28:31]
	v_mfma_f32_16x16x32_bf16 v[24:27], v[134:137], v[174:177], v[24:27]
	v_mfma_f32_16x16x32_bf16 v[20:23], v[142:145], v[174:177], v[20:23]
	v_mfma_f32_16x16x32_bf16 v[16:19], v[158:161], v[174:177], v[16:19]
	v_mfma_f32_16x16x32_bf16 v[12:15], v[130:133], v[178:181], v[12:15]
	v_mfma_f32_16x16x32_bf16 v[8:11], v[134:137], v[178:181], v[8:11]
	v_mfma_f32_16x16x32_bf16 v[4:7], v[142:145], v[178:181], v[4:7]
	v_mfma_f32_16x16x32_bf16 v[0:3], v[158:161], v[178:181], v[0:3]
	ds_read_b128 v[130:133], v119
	ds_read_b128 v[134:137], v119 offset:1024
	ds_read_b128 v[140:143], v119 offset:2048
	ds_read_b128 v[144:147], v119 offset:3072
	ds_read_b128 v[96:99], v117
	ds_read_b128 v[158:161], v117 offset:1024
	ds_read_b128 v[166:169], v117 offset:2048
	ds_read_b128 v[174:177], v117 offset:3072
	v_and_b32_e32 v119, 7, v138
	s_waitcnt lgkmcnt(0)
	s_nop 0
	v_mfma_f32_16x16x32_bf16 v[124:127], v[130:133], v[96:99], v[124:127]
	v_mfma_f32_16x16x32_bf16 v[178:181], v[134:137], v[96:99], v[120:123]
	v_mfma_f32_16x16x32_bf16 v[182:185], v[140:143], v[96:99], v[182:185]
	s_nop 5
	v_mul_f32_e32 v128, v125, v125
	v_fmac_f32_e32 v128, v124, v124
	v_fmac_f32_e32 v128, v126, v126
	v_mfma_f32_16x16x32_bf16 v[112:115], v[144:147], v[96:99], v[112:115]
	v_cvt_pk_bf16_f32 v124, v124, v125
	v_cvt_pk_bf16_f32 v125, v126, v127
	v_fmac_f32_e32 v128, v127, v127
	v_mfma_f32_16x16x32_bf16 v[108:111], v[130:133], v[158:161], v[108:111]
	v_cvt_pk_bf16_f32 v127, v180, v181
	v_mfma_f32_16x16x32_bf16 v[104:107], v[134:137], v[158:161], v[104:107]
	v_mfma_f32_16x16x32_bf16 v[96:99], v[140:143], v[158:161], v[100:103]
	v_mfma_f32_16x16x32_bf16 v[100:103], v[144:147], v[158:161], v[162:165]
	v_mfma_f32_16x16x32_bf16 v[92:95], v[130:133], v[166:169], v[92:95]
	v_mfma_f32_16x16x32_bf16 v[88:91], v[134:137], v[166:169], v[88:91]
	v_mfma_f32_16x16x32_bf16 v[84:87], v[140:143], v[166:169], v[84:87]
	v_mfma_f32_16x16x32_bf16 v[80:83], v[144:147], v[166:169], v[80:83]
	ds_read_b128 v[120:123], v117 offset:4096
	ds_read_b128 v[158:161], v117 offset:5120
	ds_read_b128 v[162:165], v117 offset:6144
	ds_read_b128 v[166:169], v117 offset:7168
	s_waitcnt lgkmcnt(0)
	v_bfe_u32 v117, v138, 5, 1
	v_mfma_f32_16x16x32_bf16 v[60:63], v[130:133], v[120:123], v[60:63]
	s_barrier
	v_mfma_f32_16x16x32_bf16 v[56:59], v[134:137], v[120:123], v[56:59]
	v_mfma_f32_16x16x32_bf16 v[52:55], v[140:143], v[120:123], v[52:55]
	v_mfma_f32_16x16x32_bf16 v[48:51], v[144:147], v[120:123], v[48:51]
	v_lshrrev_b32_e32 v121, 1, v138
	v_lshlrev_b32_e32 v120, 7, v116
	v_and_b32_e32 v121, 8, v121
	v_or3_b32 v122, s15, v120, v121
	v_and_b32_e32 v121, 64, v172
	v_xor_b32_e32 v120, 16, v172
	v_add_u32_e32 v121, 64, v121
	v_cmp_lt_i32_e32 vcc, v120, v121
	v_xor_b32_e32 v123, 32, v172
	v_mfma_f32_16x16x32_bf16 v[76:79], v[130:133], v[174:177], v[76:79]
	v_cndmask_b32_e32 v120, v172, v120, vcc
	v_cmp_lt_i32_e32 vcc, v123, v121
	v_lshlrev_b32_e32 v120, 2, v120
	v_mfma_f32_16x16x32_bf16 v[44:47], v[130:133], v[158:161], v[44:47]
	v_cndmask_b32_e32 v121, v172, v123, vcc
	v_bitop3_b32 v123, v117, v138, 7 bitop3:0x78
	v_lshlrev_b32_e32 v123, 4, v123
	v_or_b32_e32 v126, v122, v123
	s_waitcnt vmcnt(0)
	ds_write_b64 v126, v[124:125]
	v_mul_f32_e32 v124, v179, v179
	v_fmac_f32_e32 v124, v178, v178
	v_fmac_f32_e32 v124, v180, v180
	v_bitop3_b32 v125, v117, v119, 2 bitop3:0x36
	v_fmac_f32_e32 v124, v181, v181
	v_lshlrev_b32_e32 v125, 4, v125
	v_add_f32_e32 v124, v128, v124
	v_cvt_pk_bf16_f32 v126, v178, v179
	v_or_b32_e32 v128, v122, v125
	ds_write_b64 v128, v[126:127]
	v_mul_f32_e32 v126, v183, v183
	v_fmac_f32_e32 v126, v182, v182
	v_fmac_f32_e32 v126, v184, v184
	v_fmac_f32_e32 v126, v185, v185
	v_add_f32_e32 v128, v124, v126
	v_bitop3_b32 v124, v117, v119, 4 bitop3:0x36
	v_lshlrev_b32_e32 v124, 4, v124
	v_mfma_f32_16x16x32_bf16 v[28:31], v[130:133], v[162:165], v[28:31]
	v_cvt_pk_bf16_f32 v126, v182, v183
	v_cvt_pk_bf16_f32 v127, v184, v185
	v_lshlrev_b32_e32 v121, 2, v121
	v_mfma_f32_16x16x32_bf16 v[12:15], v[130:133], v[166:169], v[12:15]
	v_or_b32_e32 v130, v122, v124
	ds_write_b64 v130, v[126:127]
	v_mul_f32_e32 v126, v113, v113
	v_fmac_f32_e32 v126, v112, v112
	v_fmac_f32_e32 v126, v114, v114
	v_fmac_f32_e32 v126, v115, v115
	v_add_f32_e32 v128, v128, v126
	v_cvt_pk_bf16_f32 v126, v112, v113
	v_bitop3_b32 v112, v117, v119, 6 bitop3:0x36
	v_lshlrev_b32_e32 v112, 4, v112
	v_cvt_pk_bf16_f32 v127, v114, v115
	v_or_b32_e32 v113, v122, v112
	ds_write_b64 v113, v[126:127]
	ds_bpermute_b32 v113, v120, v128
	v_mfma_f32_16x16x32_bf16 v[72:75], v[134:137], v[174:177], v[72:75]
	v_cmp_gt_u32_e32 vcc, 16, v118
	v_or_b32_e32 v116, s8, v116
	s_waitcnt lgkmcnt(0)
	v_add_f32_e32 v113, v128, v113
	ds_bpermute_b32 v114, v121, v113
	v_mfma_f32_16x16x32_bf16 v[68:71], v[140:143], v[174:177], v[68:71]
	v_mfma_f32_16x16x32_bf16 v[64:67], v[144:147], v[174:177], v[64:67]
	v_mfma_f32_16x16x32_bf16 v[40:43], v[134:137], v[158:161], v[40:43]
	v_mfma_f32_16x16x32_bf16 v[36:39], v[140:143], v[158:161], v[36:39]
	v_mfma_f32_16x16x32_bf16 v[32:35], v[144:147], v[158:161], v[32:35]
	v_mfma_f32_16x16x32_bf16 v[24:27], v[134:137], v[162:165], v[24:27]
	v_mfma_f32_16x16x32_bf16 v[20:23], v[140:143], v[162:165], v[20:23]
	v_mfma_f32_16x16x32_bf16 v[16:19], v[144:147], v[162:165], v[16:19]
	v_mfma_f32_16x16x32_bf16 v[8:11], v[134:137], v[166:169], v[8:11]
	v_mfma_f32_16x16x32_bf16 v[4:7], v[140:143], v[166:169], v[4:7]
	v_mfma_f32_16x16x32_bf16 v[0:3], v[144:147], v[166:169], v[0:3]
	s_and_saveexec_b64 s[6:7], vcc
	s_cbranch_execz .LBB0_1078
	v_ashrrev_i32_e32 v117, 31, v116
	s_waitcnt lgkmcnt(0)
	v_add_f32_e32 v113, v113, v114
	v_lshlrev_b64 v[114:115], 6, v[116:117]
	v_lshl_add_u64 v[114:115], s[64:65], 0, v[114:115]
	v_lshl_add_u64 v[114:115], s[10:11], 2, v[114:115]
	global_store_dword v[114:115], v113, off
